# all s_setprio instructions removed (they were priority-0 no-ops at every MFMA block boundary)
# speedup vs baseline: 1.0043x; 1.0014x over previous
.LBB0_214:
	s_add_u32 s24, s24, 0x40080
	s_addc_u32 s25, s25, 0
	s_add_u32 s48, s26, 0x100
	s_addc_u32 s49, s27, 0
	s_mov_b32 s50, -2
	s_waitcnt lgkmcnt(0)
	v_xor_b32_e32 v246, 64, v153
	v_xor_b32_e32 v247, 64, v149
	v_add_u32_e32 v248, s42, v247
	v_add_u32_e32 v249, s43, v247
	ds_read_b128 v[144:147], v151
	ds_read_b128 v[154:157], v248
	ds_read_b128 v[158:161], v151 offset:2048
	ds_read_b128 v[162:165], v248 offset:2048
	ds_read_b128 v[166:169], v152
	ds_read_b128 v[170:173], v249
	ds_read_b128 v[174:177], v152 offset:2048
	ds_read_b128 v[178:181], v249 offset:2048
	s_add_u32 s26, s24, 0xfffc0080
	s_addc_u32 s27, s25, -1
	s_cmp_eq_u32 s50, 12
	s_cselect_b32 s29, s17, s27
	s_cselect_b32 s28, s46, s26
	s_cselect_b32 s27, s15, s49
	s_cselect_b32 s26, s47, s48
	v_lshl_add_u64 v[214:215], s[24:25], 0, v[136:137]
	s_add_i32 m0, s23, 0xc000
	ds_read_b128 v[182:185], v153
	ds_read_b128 v[186:189], v246
	ds_read_b128 v[190:193], v153 offset:2048
	ds_read_b128 v[194:197], v246 offset:2048
	ds_read_b128 v[198:201], v153 offset:4096
	ds_read_b128 v[202:205], v246 offset:4096
	ds_read_b128 v[206:209], v153 offset:6144
	ds_read_b128 v[210:213], v246 offset:6144
	global_load_lds_dwordx4 v[214:215], off
	v_lshl_add_u64 v[214:215], s[24:25], 0, v[138:139]
	s_add_i32 m0, s23, 0xe000
	s_nop 0
	global_load_lds_dwordx4 v[214:215], off
	s_waitcnt vmcnt(8)
	s_waitcnt lgkmcnt(0)
	s_barrier
	s_waitcnt lgkmcnt(0)
	v_mfma_f32_16x16x32_bf16 v[124:127], v[144:147], v[182:185], 0
	s_add_i32 s37, s37, 1
	s_mul_i32 s6, s37, s38
	s_mul_hi_u32 s7, s37, s41
	v_mfma_f32_16x16x32_bf16 v[120:123], v[158:161], v[182:185], 0
	s_add_i32 s7, s7, s6
	s_mul_i32 s6, s37, s41
	s_add_u32 s18, s6, s96
	v_mfma_f32_16x16x32_bf16 v[108:111], v[144:147], v[190:193], 0
	s_addc_u32 s19, s7, s31
	v_cmp_lt_i64_e64 s[6:7], s[18:19], v[140:141]
	s_ashr_i32 s14, s18, 31
	v_mfma_f32_16x16x32_bf16 v[104:107], v[158:161], v[190:193], 0
	s_lshr_b32 s14, s14, 29
	s_add_i32 s14, s18, s14
	s_ashr_i32 s15, s14, 3
	v_mfma_f32_16x16x32_bf16 v[92:95], v[144:147], v[198:201], 0
	s_and_b32 s14, s14, -8
	s_sub_i32 s14, s18, s14
	s_cmp_lt_i32 s14, 0
	v_mfma_f32_16x16x32_bf16 v[88:91], v[158:161], v[198:201], 0
	s_cselect_b32 s16, s33, 0x160
	s_mul_i32 s14, s14, s16
	s_add_i32 s14, s14, s15
	v_mfma_f32_16x16x32_bf16 v[76:79], v[144:147], v[206:209], 0
	s_mul_hi_i32 s15, s14, 0x2e8ba2e9
	s_lshr_b32 s16, s15, 31
	s_ashr_i32 s15, s15, 5
	v_mfma_f32_16x16x32_bf16 v[72:75], v[158:161], v[206:209], 0
	s_add_i32 s15, s15, s16
	s_lshl_b32 s16, s15, 3
	s_sub_i32 s17, 0x80, s16
	v_mfma_f32_16x16x32_bf16 v[124:127], v[154:157], v[186:189], v[124:127]
	s_min_i32 s17, s17, 8
	s_abs_i32 s18, s17
	v_cvt_f32_u32_e32 v252, s18
	v_mfma_f32_16x16x32_bf16 v[120:123], v[162:165], v[186:189], v[120:123]
	s_sub_i32 s20, 0, s18
	s_mulk_i32 s15, 0xb0
	s_sub_i32 s15, s14, s15
	v_mfma_f32_16x16x32_bf16 v[108:111], v[154:157], v[194:197], v[108:111]
	v_rcp_iflag_f32_e32 v252, v252
	s_abs_i32 s14, s15
	s_xor_b32 s19, s15, s17
	v_mfma_f32_16x16x32_bf16 v[104:107], v[162:165], v[194:197], v[104:107]
	s_ashr_i32 s19, s19, 31
	v_mul_f32_e32 v252, 0x4f7ffffe, v252
	v_cvt_u32_f32_e32 v252, v252
	v_mfma_f32_16x16x32_bf16 v[92:95], v[154:157], v[202:205], v[92:95]
	s_nop 0
	v_readfirstlane_b32 s21, v252
	s_mul_i32 s20, s20, s21
	v_mfma_f32_16x16x32_bf16 v[88:91], v[162:165], v[202:205], v[88:91]
	s_mul_hi_u32 s20, s21, s20
	s_add_i32 s21, s21, s20
	s_mul_hi_u32 s20, s14, s21
	v_mfma_f32_16x16x32_bf16 v[76:79], v[154:157], v[210:213], v[76:79]
	s_mul_i32 s21, s20, s18
	s_sub_i32 s14, s14, s21
	s_add_i32 s98, s20, 1
	v_mfma_f32_16x16x32_bf16 v[72:75], v[162:165], v[210:213], v[72:75]
	s_sub_i32 s21, s14, s18
	s_cmp_ge_u32 s14, s18
	s_cselect_b32 s20, s98, s20
	v_mfma_f32_16x16x32_bf16 v[116:119], v[166:169], v[182:185], 0
	s_cselect_b32 s14, s21, s14
	s_add_i32 s21, s20, 1
	s_cmp_ge_u32 s14, s18
	v_mfma_f32_16x16x32_bf16 v[112:115], v[174:177], v[182:185], 0
	s_cselect_b32 s14, s21, s20
	s_xor_b32 s14, s14, s19
	s_sub_i32 s14, s14, s19
	v_mfma_f32_16x16x32_bf16 v[100:103], v[166:169], v[190:193], 0
	s_mul_i32 s17, s14, s17
	s_sub_i32 s15, s15, s17
	s_add_i32 s16, s16, s15
	v_mfma_f32_16x16x32_bf16 v[96:99], v[174:177], v[190:193], 0
	s_ashr_i32 s17, s16, 31
	s_lshl_b64 s[18:19], s[16:17], 19
	s_add_u32 s18, s90, s18
	v_mfma_f32_16x16x32_bf16 v[84:87], v[166:169], v[198:201], 0
	s_addc_u32 s19, s91, s19
	s_and_b64 s[20:21], s[6:7], exec
	s_cselect_b32 s17, s19, s25
	v_mfma_f32_16x16x32_bf16 v[80:83], v[174:177], v[198:201], 0
	s_cselect_b32 s46, s18, s24
	s_ashr_i32 s15, s14, 31
	s_lshl_b64 s[20:21], s[14:15], 19
	v_mfma_f32_16x16x32_bf16 v[68:71], v[166:169], v[206:209], 0
	s_add_u32 s20, s2, s20
	s_addc_u32 s21, s3, s21
	s_and_b64 s[98:99], s[6:7], exec
	v_mfma_f32_16x16x32_bf16 v[64:67], v[174:177], v[206:209], 0
	s_cselect_b32 s15, s21, s27
	s_cselect_b32 s47, s20, s26
	v_mfma_f32_16x16x32_bf16 v[116:119], v[170:173], v[186:189], v[116:119]
	v_mfma_f32_16x16x32_bf16 v[112:115], v[178:181], v[186:189], v[112:115]
	v_mfma_f32_16x16x32_bf16 v[100:103], v[170:173], v[194:197], v[100:103]
	v_mfma_f32_16x16x32_bf16 v[96:99], v[178:181], v[194:197], v[96:99]
	v_mfma_f32_16x16x32_bf16 v[84:87], v[170:173], v[202:205], v[84:87]
	v_mfma_f32_16x16x32_bf16 v[80:83], v[178:181], v[202:205], v[80:83]
	v_mfma_f32_16x16x32_bf16 v[68:71], v[170:173], v[210:213], v[68:71]
	v_mfma_f32_16x16x32_bf16 v[64:67], v[178:181], v[210:213], v[64:67]
	s_barrier
	s_add_i32 s51, s42, s30
	v_lshl_add_u64 v[214:215], s[26:27], 0, v[132:133]
	s_mov_b32 m0, s51
	ds_read_b128 v[182:185], v153 offset:16384
	ds_read_b128 v[186:189], v246 offset:16384
	ds_read_b128 v[190:193], v153 offset:18432
	ds_read_b128 v[194:197], v246 offset:18432
	ds_read_b128 v[198:201], v153 offset:20480
	ds_read_b128 v[202:205], v246 offset:20480
	ds_read_b128 v[206:209], v153 offset:22528
	ds_read_b128 v[210:213], v246 offset:22528
	global_load_lds_dwordx4 v[214:215], off
	s_add_i32 m0, s51, 0x2000
	s_add_u32 s52, s26, 0x40000
	v_lshl_add_u64 v[216:217], s[26:27], 0, v[128:129]
	s_addc_u32 s53, s27, 0
	s_add_i32 s51, s43, s30
	global_load_lds_dwordx4 v[216:217], off
	v_lshl_add_u64 v[218:219], s[52:53], 0, v[132:133]
	s_mov_b32 m0, s51
	v_lshl_add_u64 v[220:221], s[28:29], 0, v[130:131]
	global_load_lds_dwordx4 v[218:219], off
	v_lshl_add_u64 v[218:219], s[52:53], 0, v[128:129]
	s_add_i32 m0, s51, 0x2000
	s_nop 0
	global_load_lds_dwordx4 v[218:219], off
	v_lshl_add_u64 v[218:219], s[28:29], 0, v[134:135]
	s_mov_b32 m0, s23
	s_nop 0
	global_load_lds_dwordx4 v[218:219], off
	s_mov_b32 m0, s34
	s_nop 0
	global_load_lds_dwordx4 v[220:221], off
	s_waitcnt vmcnt(8)
	s_waitcnt lgkmcnt(0)
	s_barrier
	s_waitcnt lgkmcnt(0)
	v_mfma_f32_16x16x32_bf16 v[60:63], v[144:147], v[182:185], 0
	v_mfma_f32_16x16x32_bf16 v[56:59], v[158:161], v[182:185], 0
	v_mfma_f32_16x16x32_bf16 v[44:47], v[144:147], v[190:193], 0
	v_mfma_f32_16x16x32_bf16 v[40:43], v[158:161], v[190:193], 0
	v_mfma_f32_16x16x32_bf16 v[28:31], v[144:147], v[198:201], 0
	v_mfma_f32_16x16x32_bf16 v[24:27], v[158:161], v[198:201], 0
	v_mfma_f32_16x16x32_bf16 v[12:15], v[144:147], v[206:209], 0
	v_mfma_f32_16x16x32_bf16 v[8:11], v[158:161], v[206:209], 0
	v_mfma_f32_16x16x32_bf16 v[60:63], v[154:157], v[186:189], v[60:63]
	v_mfma_f32_16x16x32_bf16 v[56:59], v[162:165], v[186:189], v[56:59]
	v_mfma_f32_16x16x32_bf16 v[44:47], v[154:157], v[194:197], v[44:47]
	v_mfma_f32_16x16x32_bf16 v[40:43], v[162:165], v[194:197], v[40:43]
	v_mfma_f32_16x16x32_bf16 v[28:31], v[154:157], v[202:205], v[28:31]
	v_mfma_f32_16x16x32_bf16 v[24:27], v[162:165], v[202:205], v[24:27]
	v_mfma_f32_16x16x32_bf16 v[12:15], v[154:157], v[210:213], v[12:15]
	v_mfma_f32_16x16x32_bf16 v[8:11], v[162:165], v[210:213], v[8:11]
	v_mfma_f32_16x16x32_bf16 v[52:55], v[166:169], v[182:185], 0
	v_mfma_f32_16x16x32_bf16 v[48:51], v[174:177], v[182:185], 0
	v_mfma_f32_16x16x32_bf16 v[36:39], v[166:169], v[190:193], 0
	v_mfma_f32_16x16x32_bf16 v[32:35], v[174:177], v[190:193], 0
	v_mfma_f32_16x16x32_bf16 v[20:23], v[166:169], v[198:201], 0
	v_mfma_f32_16x16x32_bf16 v[16:19], v[174:177], v[198:201], 0
	v_mfma_f32_16x16x32_bf16 v[4:7], v[166:169], v[206:209], 0
	v_mfma_f32_16x16x32_bf16 v[0:3], v[174:177], v[206:209], 0
	v_mfma_f32_16x16x32_bf16 v[52:55], v[170:173], v[186:189], v[52:55]
	v_mfma_f32_16x16x32_bf16 v[48:51], v[178:181], v[186:189], v[48:51]
	v_mfma_f32_16x16x32_bf16 v[36:39], v[170:173], v[194:197], v[36:39]
	v_mfma_f32_16x16x32_bf16 v[32:35], v[178:181], v[194:197], v[32:35]
	v_mfma_f32_16x16x32_bf16 v[20:23], v[170:173], v[202:205], v[20:23]
	v_mfma_f32_16x16x32_bf16 v[16:19], v[178:181], v[202:205], v[16:19]
	v_mfma_f32_16x16x32_bf16 v[4:7], v[170:173], v[210:213], v[4:7]
	v_mfma_f32_16x16x32_bf16 v[0:3], v[178:181], v[210:213], v[0:3]
	s_barrier
	s_add_i32 s51, 0, 0x18000
	s_add_i32 s52, 0, 0x1c000
	v_add_u32_e32 v162, s51, v149
	v_add_u32_e32 v250, s51, v247
	v_add_u32_e32 v178, s52, v149
	v_add_u32_e32 v251, s52, v247
	ds_read_b128 v[144:147], v162
	ds_read_b128 v[154:157], v250
	ds_read_b128 v[158:161], v162 offset:2048
	ds_read_b128 v[162:165], v250 offset:2048
	ds_read_b128 v[166:169], v178
	ds_read_b128 v[170:173], v251
	ds_read_b128 v[174:177], v178 offset:2048
	ds_read_b128 v[178:181], v251 offset:2048
	s_add_u32 s28, s28, 0x40000
	s_addc_u32 s29, s29, 0
	s_mov_b32 m0, s35
	v_lshl_add_u64 v[222:223], s[28:29], 0, v[134:135]
	ds_read_b128 v[182:185], v153 offset:32768
	ds_read_b128 v[186:189], v246 offset:32768
	ds_read_b128 v[190:193], v153 offset:34816
	ds_read_b128 v[194:197], v246 offset:34816
	ds_read_b128 v[198:201], v153 offset:36864
	ds_read_b128 v[202:205], v246 offset:36864
	ds_read_b128 v[206:209], v153 offset:38912
	ds_read_b128 v[210:213], v246 offset:38912
	global_load_lds_dwordx4 v[222:223], off
	v_lshl_add_u64 v[222:223], s[28:29], 0, v[130:131]
	s_mov_b32 m0, s36
	s_nop 0
	global_load_lds_dwordx4 v[222:223], off
	s_waitcnt vmcnt(8)
	s_waitcnt lgkmcnt(0)
	s_barrier
	s_waitcnt lgkmcnt(0)
	v_mfma_f32_16x16x32_bf16 v[124:127], v[144:147], v[182:185], v[124:127]
	v_mfma_f32_16x16x32_bf16 v[120:123], v[158:161], v[182:185], v[120:123]
	v_mfma_f32_16x16x32_bf16 v[108:111], v[144:147], v[190:193], v[108:111]
	v_mfma_f32_16x16x32_bf16 v[104:107], v[158:161], v[190:193], v[104:107]
	v_mfma_f32_16x16x32_bf16 v[92:95], v[144:147], v[198:201], v[92:95]
	v_mfma_f32_16x16x32_bf16 v[88:91], v[158:161], v[198:201], v[88:91]
	v_mfma_f32_16x16x32_bf16 v[76:79], v[144:147], v[206:209], v[76:79]
	v_mfma_f32_16x16x32_bf16 v[72:75], v[158:161], v[206:209], v[72:75]
	v_mfma_f32_16x16x32_bf16 v[124:127], v[154:157], v[186:189], v[124:127]
	v_mfma_f32_16x16x32_bf16 v[120:123], v[162:165], v[186:189], v[120:123]
	v_mfma_f32_16x16x32_bf16 v[108:111], v[154:157], v[194:197], v[108:111]
	v_mfma_f32_16x16x32_bf16 v[104:107], v[162:165], v[194:197], v[104:107]
	v_mfma_f32_16x16x32_bf16 v[92:95], v[154:157], v[202:205], v[92:95]
	v_mfma_f32_16x16x32_bf16 v[88:91], v[162:165], v[202:205], v[88:91]
	v_mfma_f32_16x16x32_bf16 v[76:79], v[154:157], v[210:213], v[76:79]
	v_mfma_f32_16x16x32_bf16 v[72:75], v[162:165], v[210:213], v[72:75]
	v_mfma_f32_16x16x32_bf16 v[116:119], v[166:169], v[182:185], v[116:119]
	v_mfma_f32_16x16x32_bf16 v[112:115], v[174:177], v[182:185], v[112:115]
	v_mfma_f32_16x16x32_bf16 v[100:103], v[166:169], v[190:193], v[100:103]
	v_mfma_f32_16x16x32_bf16 v[96:99], v[174:177], v[190:193], v[96:99]
	v_mfma_f32_16x16x32_bf16 v[84:87], v[166:169], v[198:201], v[84:87]
	v_mfma_f32_16x16x32_bf16 v[80:83], v[174:177], v[198:201], v[80:83]
	v_mfma_f32_16x16x32_bf16 v[68:71], v[166:169], v[206:209], v[68:71]
	v_mfma_f32_16x16x32_bf16 v[64:67], v[174:177], v[206:209], v[64:67]
	v_mfma_f32_16x16x32_bf16 v[116:119], v[170:173], v[186:189], v[116:119]
	v_mfma_f32_16x16x32_bf16 v[112:115], v[178:181], v[186:189], v[112:115]
	v_mfma_f32_16x16x32_bf16 v[100:103], v[170:173], v[194:197], v[100:103]
	v_mfma_f32_16x16x32_bf16 v[96:99], v[178:181], v[194:197], v[96:99]
	v_mfma_f32_16x16x32_bf16 v[84:87], v[170:173], v[202:205], v[84:87]
	v_mfma_f32_16x16x32_bf16 v[80:83], v[178:181], v[202:205], v[80:83]
	v_mfma_f32_16x16x32_bf16 v[68:71], v[170:173], v[210:213], v[68:71]
	v_mfma_f32_16x16x32_bf16 v[64:67], v[178:181], v[210:213], v[64:67]
	s_barrier
	s_add_i32 s28, s51, s30
	v_lshl_add_u64 v[214:215], v[214:215], 0, s[10:11]
	s_mov_b32 m0, s28
	ds_read_b128 v[182:185], v153 offset:49152
	ds_read_b128 v[186:189], v246 offset:49152
	ds_read_b128 v[190:193], v153 offset:51200
	ds_read_b128 v[194:197], v246 offset:51200
	ds_read_b128 v[198:201], v153 offset:53248
	ds_read_b128 v[202:205], v246 offset:53248
	ds_read_b128 v[206:209], v153 offset:55296
	ds_read_b128 v[210:213], v246 offset:55296
	global_load_lds_dwordx4 v[214:215], off
	s_add_i32 m0, s28, 0x2000
	s_add_u32 s26, s26, 0x40080
	v_lshl_add_u64 v[214:215], v[216:217], 0, s[10:11]
	s_addc_u32 s27, s27, 0
	s_add_i32 s28, s52, s30
	global_load_lds_dwordx4 v[214:215], off
	v_lshl_add_u64 v[214:215], s[26:27], 0, v[132:133]
	s_mov_b32 m0, s28
	s_nop 0
	global_load_lds_dwordx4 v[214:215], off
	v_lshl_add_u64 v[214:215], s[26:27], 0, v[128:129]
	s_add_i32 m0, s28, 0x2000
	s_nop 0
	global_load_lds_dwordx4 v[214:215], off
	v_lshl_add_u64 v[214:215], v[218:219], 0, s[10:11]
	s_mov_b32 m0, s39
	s_nop 0
	global_load_lds_dwordx4 v[214:215], off
	v_lshl_add_u64 v[214:215], v[220:221], 0, s[10:11]
	s_mov_b32 m0, s40
	s_nop 0
	global_load_lds_dwordx4 v[214:215], off
	s_waitcnt vmcnt(8)
	s_waitcnt lgkmcnt(0)
	s_barrier
	s_waitcnt lgkmcnt(0)
	v_mfma_f32_16x16x32_bf16 v[60:63], v[144:147], v[182:185], v[60:63]
	v_mfma_f32_16x16x32_bf16 v[56:59], v[158:161], v[182:185], v[56:59]
	v_mfma_f32_16x16x32_bf16 v[44:47], v[144:147], v[190:193], v[44:47]
	v_mfma_f32_16x16x32_bf16 v[40:43], v[158:161], v[190:193], v[40:43]
	v_mfma_f32_16x16x32_bf16 v[28:31], v[144:147], v[198:201], v[28:31]
	v_mfma_f32_16x16x32_bf16 v[24:27], v[158:161], v[198:201], v[24:27]
	v_mfma_f32_16x16x32_bf16 v[12:15], v[144:147], v[206:209], v[12:15]
	v_mfma_f32_16x16x32_bf16 v[8:11], v[158:161], v[206:209], v[8:11]
	v_mfma_f32_16x16x32_bf16 v[60:63], v[154:157], v[186:189], v[60:63]
	v_mfma_f32_16x16x32_bf16 v[56:59], v[162:165], v[186:189], v[56:59]
	v_mfma_f32_16x16x32_bf16 v[44:47], v[154:157], v[194:197], v[44:47]
	v_mfma_f32_16x16x32_bf16 v[40:43], v[162:165], v[194:197], v[40:43]
	v_mfma_f32_16x16x32_bf16 v[28:31], v[154:157], v[202:205], v[28:31]
	v_mfma_f32_16x16x32_bf16 v[24:27], v[162:165], v[202:205], v[24:27]
	v_mfma_f32_16x16x32_bf16 v[12:15], v[154:157], v[210:213], v[12:15]
	v_mfma_f32_16x16x32_bf16 v[8:11], v[162:165], v[210:213], v[8:11]
	v_mfma_f32_16x16x32_bf16 v[52:55], v[166:169], v[182:185], v[52:55]
	v_mfma_f32_16x16x32_bf16 v[48:51], v[174:177], v[182:185], v[48:51]
	v_mfma_f32_16x16x32_bf16 v[36:39], v[166:169], v[190:193], v[36:39]
	v_mfma_f32_16x16x32_bf16 v[32:35], v[174:177], v[190:193], v[32:35]
	v_mfma_f32_16x16x32_bf16 v[20:23], v[166:169], v[198:201], v[20:23]
	v_mfma_f32_16x16x32_bf16 v[16:19], v[174:177], v[198:201], v[16:19]
	v_mfma_f32_16x16x32_bf16 v[4:7], v[166:169], v[206:209], v[4:7]
	v_mfma_f32_16x16x32_bf16 v[0:3], v[174:177], v[206:209], v[0:3]
	v_mfma_f32_16x16x32_bf16 v[52:55], v[170:173], v[186:189], v[52:55]
	v_mfma_f32_16x16x32_bf16 v[48:51], v[178:181], v[186:189], v[48:51]
	v_mfma_f32_16x16x32_bf16 v[36:39], v[170:173], v[194:197], v[36:39]
	v_mfma_f32_16x16x32_bf16 v[32:35], v[178:181], v[194:197], v[32:35]
	v_mfma_f32_16x16x32_bf16 v[20:23], v[170:173], v[202:205], v[20:23]
	v_mfma_f32_16x16x32_bf16 v[16:19], v[178:181], v[202:205], v[16:19]
	v_mfma_f32_16x16x32_bf16 v[4:7], v[170:173], v[210:213], v[4:7]
	v_mfma_f32_16x16x32_bf16 v[0:3], v[178:181], v[210:213], v[0:3]
	s_barrier
	s_add_i32 s50, s50, 2
	s_add_u32 s24, s24, 0x100
	s_addc_u32 s25, s25, 0
	s_add_u32 s48, s48, 0x100
	s_addc_u32 s49, s49, 0
	s_cmp_gt_u32 s50, 13
.LBB0_217:
	ds_read_b128 v[144:147], v151
	ds_read_b128 v[154:157], v248
	ds_read_b128 v[158:161], v151 offset:2048
	ds_read_b128 v[162:165], v248 offset:2048
	ds_read_b128 v[166:169], v152
	ds_read_b128 v[170:173], v249
	ds_read_b128 v[174:177], v152 offset:2048
	ds_read_b128 v[178:181], v249 offset:2048
	s_add_u32 s26, s24, 0xfffc0080
	s_addc_u32 s27, s25, -1
	s_cmp_eq_u32 s50, 12
	s_cselect_b32 s29, s17, s27
	s_cselect_b32 s28, s46, s26
	s_cselect_b32 s27, s15, s49
	s_cselect_b32 s26, s47, s48
	v_lshl_add_u64 v[214:215], s[24:25], 0, v[136:137]
	s_add_i32 m0, s23, 0xc000
	ds_read_b128 v[182:185], v153
	ds_read_b128 v[186:189], v246
	ds_read_b128 v[190:193], v153 offset:2048
	ds_read_b128 v[194:197], v246 offset:2048
	ds_read_b128 v[198:201], v153 offset:4096
	ds_read_b128 v[202:205], v246 offset:4096
	ds_read_b128 v[206:209], v153 offset:6144
	ds_read_b128 v[210:213], v246 offset:6144
	global_load_lds_dwordx4 v[214:215], off
	v_lshl_add_u64 v[214:215], s[24:25], 0, v[138:139]
	s_add_i32 m0, s23, 0xe000
	s_nop 0
	global_load_lds_dwordx4 v[214:215], off
	s_waitcnt vmcnt(8)
	s_waitcnt lgkmcnt(0)
	s_barrier
	s_waitcnt lgkmcnt(0)
	v_mfma_f32_16x16x32_bf16 v[124:127], v[144:147], v[182:185], v[124:127]
	v_mfma_f32_16x16x32_bf16 v[120:123], v[158:161], v[182:185], v[120:123]
	v_mfma_f32_16x16x32_bf16 v[108:111], v[144:147], v[190:193], v[108:111]
	v_mfma_f32_16x16x32_bf16 v[104:107], v[158:161], v[190:193], v[104:107]
	v_mfma_f32_16x16x32_bf16 v[92:95], v[144:147], v[198:201], v[92:95]
	v_mfma_f32_16x16x32_bf16 v[88:91], v[158:161], v[198:201], v[88:91]
	v_mfma_f32_16x16x32_bf16 v[76:79], v[144:147], v[206:209], v[76:79]
	v_mfma_f32_16x16x32_bf16 v[72:75], v[158:161], v[206:209], v[72:75]
	v_mfma_f32_16x16x32_bf16 v[124:127], v[154:157], v[186:189], v[124:127]
	v_mfma_f32_16x16x32_bf16 v[120:123], v[162:165], v[186:189], v[120:123]
	v_mfma_f32_16x16x32_bf16 v[108:111], v[154:157], v[194:197], v[108:111]
	v_mfma_f32_16x16x32_bf16 v[104:107], v[162:165], v[194:197], v[104:107]
	v_mfma_f32_16x16x32_bf16 v[92:95], v[154:157], v[202:205], v[92:95]
	v_mfma_f32_16x16x32_bf16 v[88:91], v[162:165], v[202:205], v[88:91]
	v_mfma_f32_16x16x32_bf16 v[76:79], v[154:157], v[210:213], v[76:79]
	v_mfma_f32_16x16x32_bf16 v[72:75], v[162:165], v[210:213], v[72:75]
	v_mfma_f32_16x16x32_bf16 v[116:119], v[166:169], v[182:185], v[116:119]
	v_mfma_f32_16x16x32_bf16 v[112:115], v[174:177], v[182:185], v[112:115]
	v_mfma_f32_16x16x32_bf16 v[100:103], v[166:169], v[190:193], v[100:103]
	v_mfma_f32_16x16x32_bf16 v[96:99], v[174:177], v[190:193], v[96:99]
	v_mfma_f32_16x16x32_bf16 v[84:87], v[166:169], v[198:201], v[84:87]
	v_mfma_f32_16x16x32_bf16 v[80:83], v[174:177], v[198:201], v[80:83]
	v_mfma_f32_16x16x32_bf16 v[68:71], v[166:169], v[206:209], v[68:71]
	v_mfma_f32_16x16x32_bf16 v[64:67], v[174:177], v[206:209], v[64:67]
	v_mfma_f32_16x16x32_bf16 v[116:119], v[170:173], v[186:189], v[116:119]
	v_mfma_f32_16x16x32_bf16 v[112:115], v[178:181], v[186:189], v[112:115]
	v_mfma_f32_16x16x32_bf16 v[100:103], v[170:173], v[194:197], v[100:103]
	v_mfma_f32_16x16x32_bf16 v[96:99], v[178:181], v[194:197], v[96:99]
	v_mfma_f32_16x16x32_bf16 v[84:87], v[170:173], v[202:205], v[84:87]
	v_mfma_f32_16x16x32_bf16 v[80:83], v[178:181], v[202:205], v[80:83]
	v_mfma_f32_16x16x32_bf16 v[68:71], v[170:173], v[210:213], v[68:71]
	v_mfma_f32_16x16x32_bf16 v[64:67], v[178:181], v[210:213], v[64:67]
	s_barrier
	s_add_i32 s51, s42, s30
	v_lshl_add_u64 v[214:215], s[26:27], 0, v[132:133]
	s_mov_b32 m0, s51
	ds_read_b128 v[182:185], v153 offset:16384
	ds_read_b128 v[186:189], v246 offset:16384
	ds_read_b128 v[190:193], v153 offset:18432
	ds_read_b128 v[194:197], v246 offset:18432
	ds_read_b128 v[198:201], v153 offset:20480
	ds_read_b128 v[202:205], v246 offset:20480
	ds_read_b128 v[206:209], v153 offset:22528
	ds_read_b128 v[210:213], v246 offset:22528
	global_load_lds_dwordx4 v[214:215], off
	s_add_i32 m0, s51, 0x2000
	s_add_u32 s52, s26, 0x40000
	v_lshl_add_u64 v[216:217], s[26:27], 0, v[128:129]
	s_addc_u32 s53, s27, 0
	s_add_i32 s51, s43, s30
	global_load_lds_dwordx4 v[216:217], off
	v_lshl_add_u64 v[218:219], s[52:53], 0, v[132:133]
	s_mov_b32 m0, s51
	v_lshl_add_u64 v[220:221], s[28:29], 0, v[130:131]
	global_load_lds_dwordx4 v[218:219], off
	v_lshl_add_u64 v[218:219], s[52:53], 0, v[128:129]
	s_add_i32 m0, s51, 0x2000
	s_nop 0
	global_load_lds_dwordx4 v[218:219], off
	v_lshl_add_u64 v[218:219], s[28:29], 0, v[134:135]
	s_mov_b32 m0, s23
	s_nop 0
	global_load_lds_dwordx4 v[218:219], off
	s_mov_b32 m0, s34
	s_nop 0
	global_load_lds_dwordx4 v[220:221], off
	s_waitcnt vmcnt(8)
	s_waitcnt lgkmcnt(0)
	s_barrier
	s_waitcnt lgkmcnt(0)
	v_mfma_f32_16x16x32_bf16 v[60:63], v[144:147], v[182:185], v[60:63]
	v_mfma_f32_16x16x32_bf16 v[56:59], v[158:161], v[182:185], v[56:59]
	v_mfma_f32_16x16x32_bf16 v[44:47], v[144:147], v[190:193], v[44:47]
	v_mfma_f32_16x16x32_bf16 v[40:43], v[158:161], v[190:193], v[40:43]
	v_mfma_f32_16x16x32_bf16 v[28:31], v[144:147], v[198:201], v[28:31]
	v_mfma_f32_16x16x32_bf16 v[24:27], v[158:161], v[198:201], v[24:27]
	v_mfma_f32_16x16x32_bf16 v[12:15], v[144:147], v[206:209], v[12:15]
	v_mfma_f32_16x16x32_bf16 v[8:11], v[158:161], v[206:209], v[8:11]
	v_mfma_f32_16x16x32_bf16 v[60:63], v[154:157], v[186:189], v[60:63]
	v_mfma_f32_16x16x32_bf16 v[56:59], v[162:165], v[186:189], v[56:59]
	v_mfma_f32_16x16x32_bf16 v[44:47], v[154:157], v[194:197], v[44:47]
	v_mfma_f32_16x16x32_bf16 v[40:43], v[162:165], v[194:197], v[40:43]
	v_mfma_f32_16x16x32_bf16 v[28:31], v[154:157], v[202:205], v[28:31]
	v_mfma_f32_16x16x32_bf16 v[24:27], v[162:165], v[202:205], v[24:27]
	v_mfma_f32_16x16x32_bf16 v[12:15], v[154:157], v[210:213], v[12:15]
	v_mfma_f32_16x16x32_bf16 v[8:11], v[162:165], v[210:213], v[8:11]
	v_mfma_f32_16x16x32_bf16 v[52:55], v[166:169], v[182:185], v[52:55]
	v_mfma_f32_16x16x32_bf16 v[48:51], v[174:177], v[182:185], v[48:51]
	v_mfma_f32_16x16x32_bf16 v[36:39], v[166:169], v[190:193], v[36:39]
	v_mfma_f32_16x16x32_bf16 v[32:35], v[174:177], v[190:193], v[32:35]
	v_mfma_f32_16x16x32_bf16 v[20:23], v[166:169], v[198:201], v[20:23]
	v_mfma_f32_16x16x32_bf16 v[16:19], v[174:177], v[198:201], v[16:19]
	v_mfma_f32_16x16x32_bf16 v[4:7], v[166:169], v[206:209], v[4:7]
	v_mfma_f32_16x16x32_bf16 v[0:3], v[174:177], v[206:209], v[0:3]
	v_mfma_f32_16x16x32_bf16 v[52:55], v[170:173], v[186:189], v[52:55]
	v_mfma_f32_16x16x32_bf16 v[48:51], v[178:181], v[186:189], v[48:51]
	v_mfma_f32_16x16x32_bf16 v[36:39], v[170:173], v[194:197], v[36:39]
	v_mfma_f32_16x16x32_bf16 v[32:35], v[178:181], v[194:197], v[32:35]
	v_mfma_f32_16x16x32_bf16 v[20:23], v[170:173], v[202:205], v[20:23]
	v_mfma_f32_16x16x32_bf16 v[16:19], v[178:181], v[202:205], v[16:19]
	v_mfma_f32_16x16x32_bf16 v[4:7], v[170:173], v[210:213], v[4:7]
	v_mfma_f32_16x16x32_bf16 v[0:3], v[178:181], v[210:213], v[0:3]
	s_barrier
	s_add_i32 s51, 0, 0x18000
	s_add_i32 s52, 0, 0x1c000
	v_add_u32_e32 v162, s51, v149
	v_add_u32_e32 v250, s51, v247
	v_add_u32_e32 v178, s52, v149
	v_add_u32_e32 v251, s52, v247
	ds_read_b128 v[144:147], v162
	ds_read_b128 v[154:157], v250
	ds_read_b128 v[158:161], v162 offset:2048
	ds_read_b128 v[162:165], v250 offset:2048
	ds_read_b128 v[166:169], v178
	ds_read_b128 v[170:173], v251
	ds_read_b128 v[174:177], v178 offset:2048
	ds_read_b128 v[178:181], v251 offset:2048
	s_add_u32 s28, s28, 0x40000
	s_addc_u32 s29, s29, 0
	s_mov_b32 m0, s35
	v_lshl_add_u64 v[222:223], s[28:29], 0, v[134:135]
	ds_read_b128 v[182:185], v153 offset:32768
	ds_read_b128 v[186:189], v246 offset:32768
	ds_read_b128 v[190:193], v153 offset:34816
	ds_read_b128 v[194:197], v246 offset:34816
	ds_read_b128 v[198:201], v153 offset:36864
	ds_read_b128 v[202:205], v246 offset:36864
	ds_read_b128 v[206:209], v153 offset:38912
	ds_read_b128 v[210:213], v246 offset:38912
	global_load_lds_dwordx4 v[222:223], off
	v_lshl_add_u64 v[222:223], s[28:29], 0, v[130:131]
	s_mov_b32 m0, s36
	s_nop 0
	global_load_lds_dwordx4 v[222:223], off
	s_waitcnt vmcnt(8)
	s_waitcnt lgkmcnt(0)
	s_barrier
	s_waitcnt lgkmcnt(0)
	v_mfma_f32_16x16x32_bf16 v[124:127], v[144:147], v[182:185], v[124:127]
	v_mfma_f32_16x16x32_bf16 v[120:123], v[158:161], v[182:185], v[120:123]
	v_mfma_f32_16x16x32_bf16 v[108:111], v[144:147], v[190:193], v[108:111]
	v_mfma_f32_16x16x32_bf16 v[104:107], v[158:161], v[190:193], v[104:107]
	v_mfma_f32_16x16x32_bf16 v[92:95], v[144:147], v[198:201], v[92:95]
	v_mfma_f32_16x16x32_bf16 v[88:91], v[158:161], v[198:201], v[88:91]
	v_mfma_f32_16x16x32_bf16 v[76:79], v[144:147], v[206:209], v[76:79]
	v_mfma_f32_16x16x32_bf16 v[72:75], v[158:161], v[206:209], v[72:75]
	v_mfma_f32_16x16x32_bf16 v[124:127], v[154:157], v[186:189], v[124:127]
	v_mfma_f32_16x16x32_bf16 v[120:123], v[162:165], v[186:189], v[120:123]
	v_mfma_f32_16x16x32_bf16 v[108:111], v[154:157], v[194:197], v[108:111]
	v_mfma_f32_16x16x32_bf16 v[104:107], v[162:165], v[194:197], v[104:107]
	v_mfma_f32_16x16x32_bf16 v[92:95], v[154:157], v[202:205], v[92:95]
	v_mfma_f32_16x16x32_bf16 v[88:91], v[162:165], v[202:205], v[88:91]
	v_mfma_f32_16x16x32_bf16 v[76:79], v[154:157], v[210:213], v[76:79]
	v_mfma_f32_16x16x32_bf16 v[72:75], v[162:165], v[210:213], v[72:75]
	v_mfma_f32_16x16x32_bf16 v[116:119], v[166:169], v[182:185], v[116:119]
	v_mfma_f32_16x16x32_bf16 v[112:115], v[174:177], v[182:185], v[112:115]
	v_mfma_f32_16x16x32_bf16 v[100:103], v[166:169], v[190:193], v[100:103]
	v_mfma_f32_16x16x32_bf16 v[96:99], v[174:177], v[190:193], v[96:99]
	v_mfma_f32_16x16x32_bf16 v[84:87], v[166:169], v[198:201], v[84:87]
	v_mfma_f32_16x16x32_bf16 v[80:83], v[174:177], v[198:201], v[80:83]
	v_mfma_f32_16x16x32_bf16 v[68:71], v[166:169], v[206:209], v[68:71]
	v_mfma_f32_16x16x32_bf16 v[64:67], v[174:177], v[206:209], v[64:67]
	v_mfma_f32_16x16x32_bf16 v[116:119], v[170:173], v[186:189], v[116:119]
	v_mfma_f32_16x16x32_bf16 v[112:115], v[178:181], v[186:189], v[112:115]
	v_mfma_f32_16x16x32_bf16 v[100:103], v[170:173], v[194:197], v[100:103]
	v_mfma_f32_16x16x32_bf16 v[96:99], v[178:181], v[194:197], v[96:99]
	v_mfma_f32_16x16x32_bf16 v[84:87], v[170:173], v[202:205], v[84:87]
	v_mfma_f32_16x16x32_bf16 v[80:83], v[178:181], v[202:205], v[80:83]
	v_mfma_f32_16x16x32_bf16 v[68:71], v[170:173], v[210:213], v[68:71]
	v_mfma_f32_16x16x32_bf16 v[64:67], v[178:181], v[210:213], v[64:67]
	s_barrier
	s_add_i32 s28, s51, s30
	v_lshl_add_u64 v[214:215], v[214:215], 0, s[10:11]
	s_mov_b32 m0, s28
	ds_read_b128 v[182:185], v153 offset:49152
	ds_read_b128 v[186:189], v246 offset:49152
	ds_read_b128 v[190:193], v153 offset:51200
	ds_read_b128 v[194:197], v246 offset:51200
	ds_read_b128 v[198:201], v153 offset:53248
	ds_read_b128 v[202:205], v246 offset:53248
	ds_read_b128 v[206:209], v153 offset:55296
	ds_read_b128 v[210:213], v246 offset:55296
	global_load_lds_dwordx4 v[214:215], off
	s_add_i32 m0, s28, 0x2000
	s_add_u32 s26, s26, 0x40080
	v_lshl_add_u64 v[214:215], v[216:217], 0, s[10:11]
	s_addc_u32 s27, s27, 0
	s_add_i32 s28, s52, s30
	global_load_lds_dwordx4 v[214:215], off
	v_lshl_add_u64 v[214:215], s[26:27], 0, v[132:133]
	s_mov_b32 m0, s28
	s_nop 0
	global_load_lds_dwordx4 v[214:215], off
	v_lshl_add_u64 v[214:215], s[26:27], 0, v[128:129]
	s_add_i32 m0, s28, 0x2000
	s_nop 0
	global_load_lds_dwordx4 v[214:215], off
	v_lshl_add_u64 v[214:215], v[218:219], 0, s[10:11]
	s_mov_b32 m0, s39
	s_nop 0
	global_load_lds_dwordx4 v[214:215], off
	v_lshl_add_u64 v[214:215], v[220:221], 0, s[10:11]
	s_mov_b32 m0, s40
	s_nop 0
	global_load_lds_dwordx4 v[214:215], off
	s_waitcnt vmcnt(8)
	s_waitcnt lgkmcnt(0)
	s_barrier
	s_waitcnt lgkmcnt(0)
	v_mfma_f32_16x16x32_bf16 v[60:63], v[144:147], v[182:185], v[60:63]
	v_mfma_f32_16x16x32_bf16 v[56:59], v[158:161], v[182:185], v[56:59]
	v_mfma_f32_16x16x32_bf16 v[44:47], v[144:147], v[190:193], v[44:47]
	v_mfma_f32_16x16x32_bf16 v[40:43], v[158:161], v[190:193], v[40:43]
	v_mfma_f32_16x16x32_bf16 v[28:31], v[144:147], v[198:201], v[28:31]
	v_mfma_f32_16x16x32_bf16 v[24:27], v[158:161], v[198:201], v[24:27]
	v_mfma_f32_16x16x32_bf16 v[12:15], v[144:147], v[206:209], v[12:15]
	v_mfma_f32_16x16x32_bf16 v[8:11], v[158:161], v[206:209], v[8:11]
	v_mfma_f32_16x16x32_bf16 v[60:63], v[154:157], v[186:189], v[60:63]
	v_mfma_f32_16x16x32_bf16 v[56:59], v[162:165], v[186:189], v[56:59]
	v_mfma_f32_16x16x32_bf16 v[44:47], v[154:157], v[194:197], v[44:47]
	v_mfma_f32_16x16x32_bf16 v[40:43], v[162:165], v[194:197], v[40:43]
	v_mfma_f32_16x16x32_bf16 v[28:31], v[154:157], v[202:205], v[28:31]
	v_mfma_f32_16x16x32_bf16 v[24:27], v[162:165], v[202:205], v[24:27]
	v_mfma_f32_16x16x32_bf16 v[12:15], v[154:157], v[210:213], v[12:15]
	v_mfma_f32_16x16x32_bf16 v[8:11], v[162:165], v[210:213], v[8:11]
	v_mfma_f32_16x16x32_bf16 v[52:55], v[166:169], v[182:185], v[52:55]
	v_mfma_f32_16x16x32_bf16 v[48:51], v[174:177], v[182:185], v[48:51]
	v_mfma_f32_16x16x32_bf16 v[36:39], v[166:169], v[190:193], v[36:39]
	v_mfma_f32_16x16x32_bf16 v[32:35], v[174:177], v[190:193], v[32:35]
	v_mfma_f32_16x16x32_bf16 v[20:23], v[166:169], v[198:201], v[20:23]
	v_mfma_f32_16x16x32_bf16 v[16:19], v[174:177], v[198:201], v[16:19]
	v_mfma_f32_16x16x32_bf16 v[4:7], v[166:169], v[206:209], v[4:7]
	v_mfma_f32_16x16x32_bf16 v[0:3], v[174:177], v[206:209], v[0:3]
	v_mfma_f32_16x16x32_bf16 v[52:55], v[170:173], v[186:189], v[52:55]
	v_mfma_f32_16x16x32_bf16 v[48:51], v[178:181], v[186:189], v[48:51]
	v_mfma_f32_16x16x32_bf16 v[36:39], v[170:173], v[194:197], v[36:39]
	v_mfma_f32_16x16x32_bf16 v[32:35], v[178:181], v[194:197], v[32:35]
	v_mfma_f32_16x16x32_bf16 v[20:23], v[170:173], v[202:205], v[20:23]
	v_mfma_f32_16x16x32_bf16 v[16:19], v[178:181], v[202:205], v[16:19]
	v_mfma_f32_16x16x32_bf16 v[4:7], v[170:173], v[210:213], v[4:7]
	v_mfma_f32_16x16x32_bf16 v[0:3], v[178:181], v[210:213], v[0:3]
	s_barrier
	s_add_i32 s50, s50, 2
	s_add_u32 s24, s24, 0x100
	s_addc_u32 s25, s25, 0
	s_add_u32 s48, s48, 0x100
	s_addc_u32 s49, s49, 0
	s_cmp_gt_u32 s50, 13
	s_cbranch_scc0 .LBB0_217
	s_and_b64 vcc, exec, s[12:13]
	s_cbranch_vccz .LBB0_220
	s_barrier

.LBB0_295:
	s_add_u32 s46, s20, 0x100
	s_addc_u32 s47, s21, 0
	s_mov_b32 s48, -2
	s_waitcnt lgkmcnt(0)
	v_xor_b32_e32 v246, 64, v171
	v_xor_b32_e32 v247, 64, v167
	v_add_u32_e32 v248, s40, v247
	v_add_u32_e32 v249, s41, v247
	ds_read_b128 v[144:147], v169
	ds_read_b128 v[148:151], v248
	ds_read_b128 v[152:155], v169 offset:2048
	ds_read_b128 v[156:159], v248 offset:2048
	ds_read_b128 v[160:163], v170
	ds_read_b128 v[172:175], v249
	ds_read_b128 v[176:179], v170 offset:2048
	ds_read_b128 v[180:183], v249 offset:2048
	s_add_u32 s20, s18, 0x100
	s_addc_u32 s21, s19, 0
	s_cmp_eq_u32 s48, 40
	s_cselect_b32 s25, s9, s21
	s_cselect_b32 s24, s8, s20
	s_cselect_b32 s23, s17, s47
	s_cselect_b32 s22, s16, s46
	v_lshl_add_u64 v[164:165], s[18:19], 0, v[136:137]
	s_add_i32 m0, s28, 0xc000
	ds_read_b128 v[184:187], v171
	ds_read_b128 v[188:191], v246
	ds_read_b128 v[192:195], v171 offset:2048
	ds_read_b128 v[196:199], v246 offset:2048
	ds_read_b128 v[200:203], v171 offset:4096
	ds_read_b128 v[204:207], v246 offset:4096
	ds_read_b128 v[208:211], v171 offset:6144
	ds_read_b128 v[212:215], v246 offset:6144
	global_load_lds_dwordx4 v[164:165], off
	v_lshl_add_u64 v[164:165], s[18:19], 0, v[138:139]
	s_add_i32 m0, s28, 0xe000
	s_nop 0
	global_load_lds_dwordx4 v[164:165], off
	s_waitcnt vmcnt(8)
	s_waitcnt lgkmcnt(0)
	s_barrier
	s_waitcnt lgkmcnt(0)
	v_mfma_f32_16x16x32_bf16 v[124:127], v[144:147], v[184:187], 0
	v_mfma_f32_16x16x32_bf16 v[120:123], v[152:155], v[184:187], 0
	v_mfma_f32_16x16x32_bf16 v[116:119], v[144:147], v[192:195], 0
	v_mfma_f32_16x16x32_bf16 v[112:115], v[152:155], v[192:195], 0
	v_mfma_f32_16x16x32_bf16 v[96:99], v[144:147], v[200:203], 0
	v_mfma_f32_16x16x32_bf16 v[88:91], v[152:155], v[200:203], 0
	v_mfma_f32_16x16x32_bf16 v[80:83], v[144:147], v[208:211], 0
	v_mfma_f32_16x16x32_bf16 v[72:75], v[152:155], v[208:211], 0
	v_mfma_f32_16x16x32_bf16 v[124:127], v[148:151], v[188:191], v[124:127]
	v_mfma_f32_16x16x32_bf16 v[120:123], v[156:159], v[188:191], v[120:123]
	v_mfma_f32_16x16x32_bf16 v[116:119], v[148:151], v[196:199], v[116:119]
	v_mfma_f32_16x16x32_bf16 v[112:115], v[156:159], v[196:199], v[112:115]
	v_mfma_f32_16x16x32_bf16 v[96:99], v[148:151], v[204:207], v[96:99]
	v_mfma_f32_16x16x32_bf16 v[88:91], v[156:159], v[204:207], v[88:91]
	v_mfma_f32_16x16x32_bf16 v[80:83], v[148:151], v[212:215], v[80:83]
	v_mfma_f32_16x16x32_bf16 v[72:75], v[156:159], v[212:215], v[72:75]
	v_mfma_f32_16x16x32_bf16 v[108:111], v[160:163], v[184:187], 0
	v_mfma_f32_16x16x32_bf16 v[104:107], v[176:179], v[184:187], 0
	v_mfma_f32_16x16x32_bf16 v[100:103], v[160:163], v[192:195], 0
	v_mfma_f32_16x16x32_bf16 v[92:95], v[176:179], v[192:195], 0
	v_mfma_f32_16x16x32_bf16 v[84:87], v[160:163], v[200:203], 0
	v_mfma_f32_16x16x32_bf16 v[76:79], v[176:179], v[200:203], 0
	v_mfma_f32_16x16x32_bf16 v[68:71], v[160:163], v[208:211], 0
	v_mfma_f32_16x16x32_bf16 v[64:67], v[176:179], v[208:211], 0
	v_mfma_f32_16x16x32_bf16 v[108:111], v[172:175], v[188:191], v[108:111]
	v_mfma_f32_16x16x32_bf16 v[104:107], v[180:183], v[188:191], v[104:107]
	v_mfma_f32_16x16x32_bf16 v[100:103], v[172:175], v[196:199], v[100:103]
	v_mfma_f32_16x16x32_bf16 v[92:95], v[180:183], v[196:199], v[92:95]
	v_mfma_f32_16x16x32_bf16 v[84:87], v[172:175], v[204:207], v[84:87]
	v_mfma_f32_16x16x32_bf16 v[76:79], v[180:183], v[204:207], v[76:79]
	v_mfma_f32_16x16x32_bf16 v[68:71], v[172:175], v[212:215], v[68:71]
	v_mfma_f32_16x16x32_bf16 v[64:67], v[180:183], v[212:215], v[64:67]
	s_barrier
	s_add_i32 s18, s40, s26
	v_lshl_add_u64 v[164:165], s[22:23], 0, v[132:133]
	s_mov_b32 m0, s18
	ds_read_b128 v[184:187], v171 offset:16384
	ds_read_b128 v[188:191], v246 offset:16384
	ds_read_b128 v[192:195], v171 offset:18432
	ds_read_b128 v[196:199], v246 offset:18432
	ds_read_b128 v[200:203], v171 offset:20480
	ds_read_b128 v[204:207], v246 offset:20480
	ds_read_b128 v[208:211], v171 offset:22528
	ds_read_b128 v[212:215], v246 offset:22528
	global_load_lds_dwordx4 v[164:165], off
	s_add_i32 m0, s18, 0x2000
	s_add_u32 s18, s22, 0xb0000
	v_lshl_add_u64 v[216:217], s[22:23], 0, v[128:129]
	s_addc_u32 s19, s23, 0
	s_add_i32 s49, s41, s26
	global_load_lds_dwordx4 v[216:217], off
	v_lshl_add_u64 v[218:219], s[18:19], 0, v[132:133]
	s_mov_b32 m0, s49
	v_lshl_add_u64 v[220:221], s[24:25], 0, v[130:131]
	global_load_lds_dwordx4 v[218:219], off
	v_lshl_add_u64 v[218:219], s[18:19], 0, v[128:129]
	s_add_i32 m0, s49, 0x2000
	s_nop 0
	global_load_lds_dwordx4 v[218:219], off
	v_lshl_add_u64 v[218:219], s[24:25], 0, v[134:135]
	s_mov_b32 m0, s28
	s_nop 0
	global_load_lds_dwordx4 v[218:219], off
	s_mov_b32 m0, s29
	s_nop 0
	global_load_lds_dwordx4 v[220:221], off
	s_waitcnt vmcnt(8)
	s_waitcnt lgkmcnt(0)
	s_barrier
	s_waitcnt lgkmcnt(0)
	v_mfma_f32_16x16x32_bf16 v[60:63], v[144:147], v[184:187], 0
	v_mfma_f32_16x16x32_bf16 v[56:59], v[152:155], v[184:187], 0
	v_mfma_f32_16x16x32_bf16 v[48:51], v[144:147], v[192:195], 0
	v_mfma_f32_16x16x32_bf16 v[40:43], v[152:155], v[192:195], 0
	v_mfma_f32_16x16x32_bf16 v[32:35], v[144:147], v[200:203], 0
	v_mfma_f32_16x16x32_bf16 v[24:27], v[152:155], v[200:203], 0
	v_mfma_f32_16x16x32_bf16 v[16:19], v[144:147], v[208:211], 0
	v_mfma_f32_16x16x32_bf16 v[8:11], v[152:155], v[208:211], 0
	v_mfma_f32_16x16x32_bf16 v[60:63], v[148:151], v[188:191], v[60:63]
	v_mfma_f32_16x16x32_bf16 v[56:59], v[156:159], v[188:191], v[56:59]
	v_mfma_f32_16x16x32_bf16 v[48:51], v[148:151], v[196:199], v[48:51]
	v_mfma_f32_16x16x32_bf16 v[40:43], v[156:159], v[196:199], v[40:43]
	v_mfma_f32_16x16x32_bf16 v[32:35], v[148:151], v[204:207], v[32:35]
	v_mfma_f32_16x16x32_bf16 v[24:27], v[156:159], v[204:207], v[24:27]
	v_mfma_f32_16x16x32_bf16 v[16:19], v[148:151], v[212:215], v[16:19]
	v_mfma_f32_16x16x32_bf16 v[8:11], v[156:159], v[212:215], v[8:11]
	v_mfma_f32_16x16x32_bf16 v[52:55], v[160:163], v[184:187], 0
	v_mfma_f32_16x16x32_bf16 v[44:47], v[176:179], v[184:187], 0
	v_mfma_f32_16x16x32_bf16 v[36:39], v[160:163], v[192:195], 0
	v_mfma_f32_16x16x32_bf16 v[28:31], v[176:179], v[192:195], 0
	v_mfma_f32_16x16x32_bf16 v[20:23], v[160:163], v[200:203], 0
	v_mfma_f32_16x16x32_bf16 v[12:15], v[176:179], v[200:203], 0
	v_mfma_f32_16x16x32_bf16 v[4:7], v[160:163], v[208:211], 0
	v_mfma_f32_16x16x32_bf16 v[0:3], v[176:179], v[208:211], 0
	v_mfma_f32_16x16x32_bf16 v[52:55], v[172:175], v[188:191], v[52:55]
	v_mfma_f32_16x16x32_bf16 v[44:47], v[180:183], v[188:191], v[44:47]
	v_mfma_f32_16x16x32_bf16 v[36:39], v[172:175], v[196:199], v[36:39]
	v_mfma_f32_16x16x32_bf16 v[28:31], v[180:183], v[196:199], v[28:31]
	v_mfma_f32_16x16x32_bf16 v[20:23], v[172:175], v[204:207], v[20:23]
	v_mfma_f32_16x16x32_bf16 v[12:15], v[180:183], v[204:207], v[12:15]
	v_mfma_f32_16x16x32_bf16 v[4:7], v[172:175], v[212:215], v[4:7]
	v_mfma_f32_16x16x32_bf16 v[0:3], v[180:183], v[212:215], v[0:3]
	s_barrier
	s_add_i32 s49, 0, 0x18000
	s_add_i32 s50, 0, 0x1c000
	v_add_u32_e32 v156, s49, v167
	v_add_u32_e32 v250, s49, v247
	v_add_u32_e32 v180, s50, v167
	v_add_u32_e32 v251, s50, v247
	ds_read_b128 v[144:147], v156
	ds_read_b128 v[148:151], v250
	ds_read_b128 v[152:155], v156 offset:2048
	ds_read_b128 v[156:159], v250 offset:2048
	ds_read_b128 v[160:163], v180
	ds_read_b128 v[172:175], v251
	ds_read_b128 v[176:179], v180 offset:2048
	ds_read_b128 v[180:183], v251 offset:2048
	s_add_u32 s18, s24, 0xb0000
	s_addc_u32 s19, s25, 0
	s_mov_b32 m0, s30
	v_lshl_add_u64 v[222:223], s[18:19], 0, v[134:135]
	ds_read_b128 v[184:187], v171 offset:32768
	ds_read_b128 v[188:191], v246 offset:32768
	ds_read_b128 v[192:195], v171 offset:34816
	ds_read_b128 v[196:199], v246 offset:34816
	ds_read_b128 v[200:203], v171 offset:36864
	ds_read_b128 v[204:207], v246 offset:36864
	ds_read_b128 v[208:211], v171 offset:38912
	ds_read_b128 v[212:215], v246 offset:38912
	global_load_lds_dwordx4 v[222:223], off
	v_lshl_add_u64 v[222:223], s[18:19], 0, v[130:131]
	s_mov_b32 m0, s31
	s_nop 0
	global_load_lds_dwordx4 v[222:223], off
	s_waitcnt vmcnt(8)
	s_waitcnt lgkmcnt(0)
	s_barrier
	s_waitcnt lgkmcnt(0)
	v_mfma_f32_16x16x32_bf16 v[124:127], v[144:147], v[184:187], v[124:127]
	v_mfma_f32_16x16x32_bf16 v[120:123], v[152:155], v[184:187], v[120:123]
	v_mfma_f32_16x16x32_bf16 v[116:119], v[144:147], v[192:195], v[116:119]
	v_mfma_f32_16x16x32_bf16 v[112:115], v[152:155], v[192:195], v[112:115]
	v_mfma_f32_16x16x32_bf16 v[96:99], v[144:147], v[200:203], v[96:99]
	v_mfma_f32_16x16x32_bf16 v[88:91], v[152:155], v[200:203], v[88:91]
	v_mfma_f32_16x16x32_bf16 v[80:83], v[144:147], v[208:211], v[80:83]
	v_mfma_f32_16x16x32_bf16 v[72:75], v[152:155], v[208:211], v[72:75]
	v_mfma_f32_16x16x32_bf16 v[124:127], v[148:151], v[188:191], v[124:127]
	v_mfma_f32_16x16x32_bf16 v[120:123], v[156:159], v[188:191], v[120:123]
	v_mfma_f32_16x16x32_bf16 v[116:119], v[148:151], v[196:199], v[116:119]
	v_mfma_f32_16x16x32_bf16 v[112:115], v[156:159], v[196:199], v[112:115]
	v_mfma_f32_16x16x32_bf16 v[96:99], v[148:151], v[204:207], v[96:99]
	v_mfma_f32_16x16x32_bf16 v[88:91], v[156:159], v[204:207], v[88:91]
	v_mfma_f32_16x16x32_bf16 v[80:83], v[148:151], v[212:215], v[80:83]
	v_mfma_f32_16x16x32_bf16 v[72:75], v[156:159], v[212:215], v[72:75]
	v_mfma_f32_16x16x32_bf16 v[108:111], v[160:163], v[184:187], v[108:111]
	v_mfma_f32_16x16x32_bf16 v[104:107], v[176:179], v[184:187], v[104:107]
	v_mfma_f32_16x16x32_bf16 v[100:103], v[160:163], v[192:195], v[100:103]
	v_mfma_f32_16x16x32_bf16 v[92:95], v[176:179], v[192:195], v[92:95]
	v_mfma_f32_16x16x32_bf16 v[84:87], v[160:163], v[200:203], v[84:87]
	v_mfma_f32_16x16x32_bf16 v[76:79], v[176:179], v[200:203], v[76:79]
	v_mfma_f32_16x16x32_bf16 v[68:71], v[160:163], v[208:211], v[68:71]
	v_mfma_f32_16x16x32_bf16 v[64:67], v[176:179], v[208:211], v[64:67]
	v_mfma_f32_16x16x32_bf16 v[108:111], v[172:175], v[188:191], v[108:111]
	v_mfma_f32_16x16x32_bf16 v[104:107], v[180:183], v[188:191], v[104:107]
	v_mfma_f32_16x16x32_bf16 v[100:103], v[172:175], v[196:199], v[100:103]
	v_mfma_f32_16x16x32_bf16 v[92:95], v[180:183], v[196:199], v[92:95]
	v_mfma_f32_16x16x32_bf16 v[84:87], v[172:175], v[204:207], v[84:87]
	v_mfma_f32_16x16x32_bf16 v[76:79], v[180:183], v[204:207], v[76:79]
	v_mfma_f32_16x16x32_bf16 v[68:71], v[172:175], v[212:215], v[68:71]
	v_mfma_f32_16x16x32_bf16 v[64:67], v[180:183], v[212:215], v[64:67]
	s_barrier
	s_add_i32 s18, s49, s26
	v_lshl_add_u64 v[164:165], v[164:165], 0, s[12:13]
	s_mov_b32 m0, s18
	ds_read_b128 v[184:187], v171 offset:49152
	ds_read_b128 v[188:191], v246 offset:49152
	ds_read_b128 v[192:195], v171 offset:51200
	ds_read_b128 v[196:199], v246 offset:51200
	ds_read_b128 v[200:203], v171 offset:53248
	ds_read_b128 v[204:207], v246 offset:53248
	ds_read_b128 v[208:211], v171 offset:55296
	ds_read_b128 v[212:215], v246 offset:55296
	global_load_lds_dwordx4 v[164:165], off
	s_add_i32 m0, s18, 0x2000
	s_add_u32 s18, s22, 0xb0080
	v_lshl_add_u64 v[164:165], v[216:217], 0, s[12:13]
	s_addc_u32 s19, s23, 0
	s_add_i32 s22, s50, s26
	global_load_lds_dwordx4 v[164:165], off
	v_lshl_add_u64 v[164:165], s[18:19], 0, v[132:133]
	s_mov_b32 m0, s22
	s_nop 0
	global_load_lds_dwordx4 v[164:165], off
	v_lshl_add_u64 v[164:165], s[18:19], 0, v[128:129]
	s_add_i32 m0, s22, 0x2000
	s_nop 0
	global_load_lds_dwordx4 v[164:165], off
	v_lshl_add_u64 v[164:165], v[218:219], 0, s[12:13]
	s_mov_b32 m0, s37
	s_nop 0
	global_load_lds_dwordx4 v[164:165], off
	v_lshl_add_u64 v[164:165], v[220:221], 0, s[12:13]
	s_mov_b32 m0, s38
	s_nop 0
	global_load_lds_dwordx4 v[164:165], off
	s_waitcnt vmcnt(8)
	s_waitcnt lgkmcnt(0)
	s_barrier
	s_waitcnt lgkmcnt(0)
	v_mfma_f32_16x16x32_bf16 v[60:63], v[144:147], v[184:187], v[60:63]
	v_mfma_f32_16x16x32_bf16 v[56:59], v[152:155], v[184:187], v[56:59]
	v_mfma_f32_16x16x32_bf16 v[48:51], v[144:147], v[192:195], v[48:51]
	v_mfma_f32_16x16x32_bf16 v[40:43], v[152:155], v[192:195], v[40:43]
	v_mfma_f32_16x16x32_bf16 v[32:35], v[144:147], v[200:203], v[32:35]
	v_mfma_f32_16x16x32_bf16 v[24:27], v[152:155], v[200:203], v[24:27]
	v_mfma_f32_16x16x32_bf16 v[16:19], v[144:147], v[208:211], v[16:19]
	v_mfma_f32_16x16x32_bf16 v[8:11], v[152:155], v[208:211], v[8:11]
	v_mfma_f32_16x16x32_bf16 v[60:63], v[148:151], v[188:191], v[60:63]
	v_mfma_f32_16x16x32_bf16 v[56:59], v[156:159], v[188:191], v[56:59]
	v_mfma_f32_16x16x32_bf16 v[48:51], v[148:151], v[196:199], v[48:51]
	v_mfma_f32_16x16x32_bf16 v[40:43], v[156:159], v[196:199], v[40:43]
	v_mfma_f32_16x16x32_bf16 v[32:35], v[148:151], v[204:207], v[32:35]
	v_mfma_f32_16x16x32_bf16 v[24:27], v[156:159], v[204:207], v[24:27]
	v_mfma_f32_16x16x32_bf16 v[16:19], v[148:151], v[212:215], v[16:19]
	v_mfma_f32_16x16x32_bf16 v[8:11], v[156:159], v[212:215], v[8:11]
	v_mfma_f32_16x16x32_bf16 v[52:55], v[160:163], v[184:187], v[52:55]
	v_mfma_f32_16x16x32_bf16 v[44:47], v[176:179], v[184:187], v[44:47]
	v_mfma_f32_16x16x32_bf16 v[36:39], v[160:163], v[192:195], v[36:39]
	v_mfma_f32_16x16x32_bf16 v[28:31], v[176:179], v[192:195], v[28:31]
	v_mfma_f32_16x16x32_bf16 v[20:23], v[160:163], v[200:203], v[20:23]
	v_mfma_f32_16x16x32_bf16 v[12:15], v[176:179], v[200:203], v[12:15]
	v_mfma_f32_16x16x32_bf16 v[4:7], v[160:163], v[208:211], v[4:7]
	v_mfma_f32_16x16x32_bf16 v[0:3], v[176:179], v[208:211], v[0:3]
	v_mfma_f32_16x16x32_bf16 v[52:55], v[172:175], v[188:191], v[52:55]
	v_mfma_f32_16x16x32_bf16 v[44:47], v[180:183], v[188:191], v[44:47]
	v_mfma_f32_16x16x32_bf16 v[36:39], v[172:175], v[196:199], v[36:39]
	v_mfma_f32_16x16x32_bf16 v[28:31], v[180:183], v[196:199], v[28:31]
	v_mfma_f32_16x16x32_bf16 v[20:23], v[172:175], v[204:207], v[20:23]
	v_mfma_f32_16x16x32_bf16 v[12:15], v[180:183], v[204:207], v[12:15]
	v_mfma_f32_16x16x32_bf16 v[4:7], v[172:175], v[212:215], v[4:7]
	v_mfma_f32_16x16x32_bf16 v[0:3], v[180:183], v[212:215], v[0:3]
	s_barrier
	s_add_i32 s48, s48, 2
	s_add_u32 s46, s46, 0x100
	s_addc_u32 s47, s47, 0
	s_cmp_gt_u32 s48, 41
	s_mov_b64 s[18:19], s[20:21]
.LBB0_296:
	ds_read_b128 v[144:147], v169
	ds_read_b128 v[148:151], v248
	ds_read_b128 v[152:155], v169 offset:2048
	ds_read_b128 v[156:159], v248 offset:2048
	ds_read_b128 v[160:163], v170
	ds_read_b128 v[172:175], v249
	ds_read_b128 v[176:179], v170 offset:2048
	ds_read_b128 v[180:183], v249 offset:2048
	s_add_u32 s20, s18, 0x100
	s_addc_u32 s21, s19, 0
	s_cmp_eq_u32 s48, 40
	s_cselect_b32 s25, s9, s21
	s_cselect_b32 s24, s8, s20
	s_cselect_b32 s23, s17, s47
	s_cselect_b32 s22, s16, s46
	v_lshl_add_u64 v[164:165], s[18:19], 0, v[136:137]
	s_add_i32 m0, s28, 0xc000
	ds_read_b128 v[184:187], v171
	ds_read_b128 v[188:191], v246
	ds_read_b128 v[192:195], v171 offset:2048
	ds_read_b128 v[196:199], v246 offset:2048
	ds_read_b128 v[200:203], v171 offset:4096
	ds_read_b128 v[204:207], v246 offset:4096
	ds_read_b128 v[208:211], v171 offset:6144
	ds_read_b128 v[212:215], v246 offset:6144
	global_load_lds_dwordx4 v[164:165], off
	v_lshl_add_u64 v[164:165], s[18:19], 0, v[138:139]
	s_add_i32 m0, s28, 0xe000
	s_nop 0
	global_load_lds_dwordx4 v[164:165], off
	s_waitcnt vmcnt(8)
	s_waitcnt lgkmcnt(0)
	s_barrier
	s_waitcnt lgkmcnt(0)
	v_mfma_f32_16x16x32_bf16 v[124:127], v[144:147], v[184:187], v[124:127]
	v_mfma_f32_16x16x32_bf16 v[120:123], v[152:155], v[184:187], v[120:123]
	v_mfma_f32_16x16x32_bf16 v[116:119], v[144:147], v[192:195], v[116:119]
	v_mfma_f32_16x16x32_bf16 v[112:115], v[152:155], v[192:195], v[112:115]
	v_mfma_f32_16x16x32_bf16 v[96:99], v[144:147], v[200:203], v[96:99]
	v_mfma_f32_16x16x32_bf16 v[88:91], v[152:155], v[200:203], v[88:91]
	v_mfma_f32_16x16x32_bf16 v[80:83], v[144:147], v[208:211], v[80:83]
	v_mfma_f32_16x16x32_bf16 v[72:75], v[152:155], v[208:211], v[72:75]
	v_mfma_f32_16x16x32_bf16 v[124:127], v[148:151], v[188:191], v[124:127]
	v_mfma_f32_16x16x32_bf16 v[120:123], v[156:159], v[188:191], v[120:123]
	v_mfma_f32_16x16x32_bf16 v[116:119], v[148:151], v[196:199], v[116:119]
	v_mfma_f32_16x16x32_bf16 v[112:115], v[156:159], v[196:199], v[112:115]
	v_mfma_f32_16x16x32_bf16 v[96:99], v[148:151], v[204:207], v[96:99]
	v_mfma_f32_16x16x32_bf16 v[88:91], v[156:159], v[204:207], v[88:91]
	v_mfma_f32_16x16x32_bf16 v[80:83], v[148:151], v[212:215], v[80:83]
	v_mfma_f32_16x16x32_bf16 v[72:75], v[156:159], v[212:215], v[72:75]
	v_mfma_f32_16x16x32_bf16 v[108:111], v[160:163], v[184:187], v[108:111]
	v_mfma_f32_16x16x32_bf16 v[104:107], v[176:179], v[184:187], v[104:107]
	v_mfma_f32_16x16x32_bf16 v[100:103], v[160:163], v[192:195], v[100:103]
	v_mfma_f32_16x16x32_bf16 v[92:95], v[176:179], v[192:195], v[92:95]
	v_mfma_f32_16x16x32_bf16 v[84:87], v[160:163], v[200:203], v[84:87]
	v_mfma_f32_16x16x32_bf16 v[76:79], v[176:179], v[200:203], v[76:79]
	v_mfma_f32_16x16x32_bf16 v[68:71], v[160:163], v[208:211], v[68:71]
	v_mfma_f32_16x16x32_bf16 v[64:67], v[176:179], v[208:211], v[64:67]
	v_mfma_f32_16x16x32_bf16 v[108:111], v[172:175], v[188:191], v[108:111]
	v_mfma_f32_16x16x32_bf16 v[104:107], v[180:183], v[188:191], v[104:107]
	v_mfma_f32_16x16x32_bf16 v[100:103], v[172:175], v[196:199], v[100:103]
	v_mfma_f32_16x16x32_bf16 v[92:95], v[180:183], v[196:199], v[92:95]
	v_mfma_f32_16x16x32_bf16 v[84:87], v[172:175], v[204:207], v[84:87]
	v_mfma_f32_16x16x32_bf16 v[76:79], v[180:183], v[204:207], v[76:79]
	v_mfma_f32_16x16x32_bf16 v[68:71], v[172:175], v[212:215], v[68:71]
	v_mfma_f32_16x16x32_bf16 v[64:67], v[180:183], v[212:215], v[64:67]
	s_barrier
	s_add_i32 s18, s40, s26
	v_lshl_add_u64 v[164:165], s[22:23], 0, v[132:133]
	s_mov_b32 m0, s18
	ds_read_b128 v[184:187], v171 offset:16384
	ds_read_b128 v[188:191], v246 offset:16384
	ds_read_b128 v[192:195], v171 offset:18432
	ds_read_b128 v[196:199], v246 offset:18432
	ds_read_b128 v[200:203], v171 offset:20480
	ds_read_b128 v[204:207], v246 offset:20480
	ds_read_b128 v[208:211], v171 offset:22528
	ds_read_b128 v[212:215], v246 offset:22528
	global_load_lds_dwordx4 v[164:165], off
	s_add_i32 m0, s18, 0x2000
	s_add_u32 s18, s22, 0xb0000
	v_lshl_add_u64 v[216:217], s[22:23], 0, v[128:129]
	s_addc_u32 s19, s23, 0
	s_add_i32 s49, s41, s26
	global_load_lds_dwordx4 v[216:217], off
	v_lshl_add_u64 v[218:219], s[18:19], 0, v[132:133]
	s_mov_b32 m0, s49
	v_lshl_add_u64 v[220:221], s[24:25], 0, v[130:131]
	global_load_lds_dwordx4 v[218:219], off
	v_lshl_add_u64 v[218:219], s[18:19], 0, v[128:129]
	s_add_i32 m0, s49, 0x2000
	s_nop 0
	global_load_lds_dwordx4 v[218:219], off
	v_lshl_add_u64 v[218:219], s[24:25], 0, v[134:135]
	s_mov_b32 m0, s28
	s_nop 0
	global_load_lds_dwordx4 v[218:219], off
	s_mov_b32 m0, s29
	s_nop 0
	global_load_lds_dwordx4 v[220:221], off
	s_waitcnt vmcnt(8)
	s_waitcnt lgkmcnt(0)
	s_barrier
	s_waitcnt lgkmcnt(0)
	v_mfma_f32_16x16x32_bf16 v[60:63], v[144:147], v[184:187], v[60:63]
	v_mfma_f32_16x16x32_bf16 v[56:59], v[152:155], v[184:187], v[56:59]
	v_mfma_f32_16x16x32_bf16 v[48:51], v[144:147], v[192:195], v[48:51]
	v_mfma_f32_16x16x32_bf16 v[40:43], v[152:155], v[192:195], v[40:43]
	v_mfma_f32_16x16x32_bf16 v[32:35], v[144:147], v[200:203], v[32:35]
	v_mfma_f32_16x16x32_bf16 v[24:27], v[152:155], v[200:203], v[24:27]
	v_mfma_f32_16x16x32_bf16 v[16:19], v[144:147], v[208:211], v[16:19]
	v_mfma_f32_16x16x32_bf16 v[8:11], v[152:155], v[208:211], v[8:11]
	v_mfma_f32_16x16x32_bf16 v[60:63], v[148:151], v[188:191], v[60:63]
	v_mfma_f32_16x16x32_bf16 v[56:59], v[156:159], v[188:191], v[56:59]
	v_mfma_f32_16x16x32_bf16 v[48:51], v[148:151], v[196:199], v[48:51]
	v_mfma_f32_16x16x32_bf16 v[40:43], v[156:159], v[196:199], v[40:43]
	v_mfma_f32_16x16x32_bf16 v[32:35], v[148:151], v[204:207], v[32:35]
	v_mfma_f32_16x16x32_bf16 v[24:27], v[156:159], v[204:207], v[24:27]
	v_mfma_f32_16x16x32_bf16 v[16:19], v[148:151], v[212:215], v[16:19]
	v_mfma_f32_16x16x32_bf16 v[8:11], v[156:159], v[212:215], v[8:11]
	v_mfma_f32_16x16x32_bf16 v[52:55], v[160:163], v[184:187], v[52:55]
	v_mfma_f32_16x16x32_bf16 v[44:47], v[176:179], v[184:187], v[44:47]
	v_mfma_f32_16x16x32_bf16 v[36:39], v[160:163], v[192:195], v[36:39]
	v_mfma_f32_16x16x32_bf16 v[28:31], v[176:179], v[192:195], v[28:31]
	v_mfma_f32_16x16x32_bf16 v[20:23], v[160:163], v[200:203], v[20:23]
	v_mfma_f32_16x16x32_bf16 v[12:15], v[176:179], v[200:203], v[12:15]
	v_mfma_f32_16x16x32_bf16 v[4:7], v[160:163], v[208:211], v[4:7]
	v_mfma_f32_16x16x32_bf16 v[0:3], v[176:179], v[208:211], v[0:3]
	v_mfma_f32_16x16x32_bf16 v[52:55], v[172:175], v[188:191], v[52:55]
	v_mfma_f32_16x16x32_bf16 v[44:47], v[180:183], v[188:191], v[44:47]
	v_mfma_f32_16x16x32_bf16 v[36:39], v[172:175], v[196:199], v[36:39]
	v_mfma_f32_16x16x32_bf16 v[28:31], v[180:183], v[196:199], v[28:31]
	v_mfma_f32_16x16x32_bf16 v[20:23], v[172:175], v[204:207], v[20:23]
	v_mfma_f32_16x16x32_bf16 v[12:15], v[180:183], v[204:207], v[12:15]
	v_mfma_f32_16x16x32_bf16 v[4:7], v[172:175], v[212:215], v[4:7]
	v_mfma_f32_16x16x32_bf16 v[0:3], v[180:183], v[212:215], v[0:3]
	s_barrier
	s_add_i32 s49, 0, 0x18000
	s_add_i32 s50, 0, 0x1c000
	v_add_u32_e32 v156, s49, v167
	v_add_u32_e32 v250, s49, v247
	v_add_u32_e32 v180, s50, v167
	v_add_u32_e32 v251, s50, v247
	ds_read_b128 v[144:147], v156
	ds_read_b128 v[148:151], v250
	ds_read_b128 v[152:155], v156 offset:2048
	ds_read_b128 v[156:159], v250 offset:2048
	ds_read_b128 v[160:163], v180
	ds_read_b128 v[172:175], v251
	ds_read_b128 v[176:179], v180 offset:2048
	ds_read_b128 v[180:183], v251 offset:2048
	s_add_u32 s18, s24, 0xb0000
	s_addc_u32 s19, s25, 0
	s_mov_b32 m0, s30
	v_lshl_add_u64 v[222:223], s[18:19], 0, v[134:135]
	ds_read_b128 v[184:187], v171 offset:32768
	ds_read_b128 v[188:191], v246 offset:32768
	ds_read_b128 v[192:195], v171 offset:34816
	ds_read_b128 v[196:199], v246 offset:34816
	ds_read_b128 v[200:203], v171 offset:36864
	ds_read_b128 v[204:207], v246 offset:36864
	ds_read_b128 v[208:211], v171 offset:38912
	ds_read_b128 v[212:215], v246 offset:38912
	global_load_lds_dwordx4 v[222:223], off
	v_lshl_add_u64 v[222:223], s[18:19], 0, v[130:131]
	s_mov_b32 m0, s31
	s_nop 0
	global_load_lds_dwordx4 v[222:223], off
	s_waitcnt vmcnt(8)
	s_waitcnt lgkmcnt(0)
	s_barrier
	s_waitcnt lgkmcnt(0)
	v_mfma_f32_16x16x32_bf16 v[124:127], v[144:147], v[184:187], v[124:127]
	v_mfma_f32_16x16x32_bf16 v[120:123], v[152:155], v[184:187], v[120:123]
	v_mfma_f32_16x16x32_bf16 v[116:119], v[144:147], v[192:195], v[116:119]
	v_mfma_f32_16x16x32_bf16 v[112:115], v[152:155], v[192:195], v[112:115]
	v_mfma_f32_16x16x32_bf16 v[96:99], v[144:147], v[200:203], v[96:99]
	v_mfma_f32_16x16x32_bf16 v[88:91], v[152:155], v[200:203], v[88:91]
	v_mfma_f32_16x16x32_bf16 v[80:83], v[144:147], v[208:211], v[80:83]
	v_mfma_f32_16x16x32_bf16 v[72:75], v[152:155], v[208:211], v[72:75]
	v_mfma_f32_16x16x32_bf16 v[124:127], v[148:151], v[188:191], v[124:127]
	v_mfma_f32_16x16x32_bf16 v[120:123], v[156:159], v[188:191], v[120:123]
	v_mfma_f32_16x16x32_bf16 v[116:119], v[148:151], v[196:199], v[116:119]
	v_mfma_f32_16x16x32_bf16 v[112:115], v[156:159], v[196:199], v[112:115]
	v_mfma_f32_16x16x32_bf16 v[96:99], v[148:151], v[204:207], v[96:99]
	v_mfma_f32_16x16x32_bf16 v[88:91], v[156:159], v[204:207], v[88:91]
	v_mfma_f32_16x16x32_bf16 v[80:83], v[148:151], v[212:215], v[80:83]
	v_mfma_f32_16x16x32_bf16 v[72:75], v[156:159], v[212:215], v[72:75]
	v_mfma_f32_16x16x32_bf16 v[108:111], v[160:163], v[184:187], v[108:111]
	v_mfma_f32_16x16x32_bf16 v[104:107], v[176:179], v[184:187], v[104:107]
	v_mfma_f32_16x16x32_bf16 v[100:103], v[160:163], v[192:195], v[100:103]
	v_mfma_f32_16x16x32_bf16 v[92:95], v[176:179], v[192:195], v[92:95]
	v_mfma_f32_16x16x32_bf16 v[84:87], v[160:163], v[200:203], v[84:87]
	v_mfma_f32_16x16x32_bf16 v[76:79], v[176:179], v[200:203], v[76:79]
	v_mfma_f32_16x16x32_bf16 v[68:71], v[160:163], v[208:211], v[68:71]
	v_mfma_f32_16x16x32_bf16 v[64:67], v[176:179], v[208:211], v[64:67]
	v_mfma_f32_16x16x32_bf16 v[108:111], v[172:175], v[188:191], v[108:111]
	v_mfma_f32_16x16x32_bf16 v[104:107], v[180:183], v[188:191], v[104:107]
	v_mfma_f32_16x16x32_bf16 v[100:103], v[172:175], v[196:199], v[100:103]
	v_mfma_f32_16x16x32_bf16 v[92:95], v[180:183], v[196:199], v[92:95]
	v_mfma_f32_16x16x32_bf16 v[84:87], v[172:175], v[204:207], v[84:87]
	v_mfma_f32_16x16x32_bf16 v[76:79], v[180:183], v[204:207], v[76:79]
	v_mfma_f32_16x16x32_bf16 v[68:71], v[172:175], v[212:215], v[68:71]
	v_mfma_f32_16x16x32_bf16 v[64:67], v[180:183], v[212:215], v[64:67]
	s_barrier
	s_add_i32 s18, s49, s26
	v_lshl_add_u64 v[164:165], v[164:165], 0, s[12:13]
	s_mov_b32 m0, s18
	ds_read_b128 v[184:187], v171 offset:49152
	ds_read_b128 v[188:191], v246 offset:49152
	ds_read_b128 v[192:195], v171 offset:51200
	ds_read_b128 v[196:199], v246 offset:51200
	ds_read_b128 v[200:203], v171 offset:53248
	ds_read_b128 v[204:207], v246 offset:53248
	ds_read_b128 v[208:211], v171 offset:55296
	ds_read_b128 v[212:215], v246 offset:55296
	global_load_lds_dwordx4 v[164:165], off
	s_add_i32 m0, s18, 0x2000
	s_add_u32 s18, s22, 0xb0080
	v_lshl_add_u64 v[164:165], v[216:217], 0, s[12:13]
	s_addc_u32 s19, s23, 0
	s_add_i32 s22, s50, s26
	global_load_lds_dwordx4 v[164:165], off
	v_lshl_add_u64 v[164:165], s[18:19], 0, v[132:133]
	s_mov_b32 m0, s22
	s_nop 0
	global_load_lds_dwordx4 v[164:165], off
	v_lshl_add_u64 v[164:165], s[18:19], 0, v[128:129]
	s_add_i32 m0, s22, 0x2000
	s_nop 0
	global_load_lds_dwordx4 v[164:165], off
	v_lshl_add_u64 v[164:165], v[218:219], 0, s[12:13]
	s_mov_b32 m0, s37
	s_nop 0
	global_load_lds_dwordx4 v[164:165], off
	v_lshl_add_u64 v[164:165], v[220:221], 0, s[12:13]
	s_mov_b32 m0, s38
	s_nop 0
	global_load_lds_dwordx4 v[164:165], off
	s_waitcnt vmcnt(8)
	s_waitcnt lgkmcnt(0)
	s_barrier
	s_waitcnt lgkmcnt(0)
	v_mfma_f32_16x16x32_bf16 v[60:63], v[144:147], v[184:187], v[60:63]
	v_mfma_f32_16x16x32_bf16 v[56:59], v[152:155], v[184:187], v[56:59]
	v_mfma_f32_16x16x32_bf16 v[48:51], v[144:147], v[192:195], v[48:51]
	v_mfma_f32_16x16x32_bf16 v[40:43], v[152:155], v[192:195], v[40:43]
	v_mfma_f32_16x16x32_bf16 v[32:35], v[144:147], v[200:203], v[32:35]
	v_mfma_f32_16x16x32_bf16 v[24:27], v[152:155], v[200:203], v[24:27]
	v_mfma_f32_16x16x32_bf16 v[16:19], v[144:147], v[208:211], v[16:19]
	v_mfma_f32_16x16x32_bf16 v[8:11], v[152:155], v[208:211], v[8:11]
	v_mfma_f32_16x16x32_bf16 v[60:63], v[148:151], v[188:191], v[60:63]
	v_mfma_f32_16x16x32_bf16 v[56:59], v[156:159], v[188:191], v[56:59]
	v_mfma_f32_16x16x32_bf16 v[48:51], v[148:151], v[196:199], v[48:51]
	v_mfma_f32_16x16x32_bf16 v[40:43], v[156:159], v[196:199], v[40:43]
	v_mfma_f32_16x16x32_bf16 v[32:35], v[148:151], v[204:207], v[32:35]
	v_mfma_f32_16x16x32_bf16 v[24:27], v[156:159], v[204:207], v[24:27]
	v_mfma_f32_16x16x32_bf16 v[16:19], v[148:151], v[212:215], v[16:19]
	v_mfma_f32_16x16x32_bf16 v[8:11], v[156:159], v[212:215], v[8:11]
	v_mfma_f32_16x16x32_bf16 v[52:55], v[160:163], v[184:187], v[52:55]
	v_mfma_f32_16x16x32_bf16 v[44:47], v[176:179], v[184:187], v[44:47]
	v_mfma_f32_16x16x32_bf16 v[36:39], v[160:163], v[192:195], v[36:39]
	v_mfma_f32_16x16x32_bf16 v[28:31], v[176:179], v[192:195], v[28:31]
	v_mfma_f32_16x16x32_bf16 v[20:23], v[160:163], v[200:203], v[20:23]
	v_mfma_f32_16x16x32_bf16 v[12:15], v[176:179], v[200:203], v[12:15]
	v_mfma_f32_16x16x32_bf16 v[4:7], v[160:163], v[208:211], v[4:7]
	v_mfma_f32_16x16x32_bf16 v[0:3], v[176:179], v[208:211], v[0:3]
	v_mfma_f32_16x16x32_bf16 v[52:55], v[172:175], v[188:191], v[52:55]
	v_mfma_f32_16x16x32_bf16 v[44:47], v[180:183], v[188:191], v[44:47]
	v_mfma_f32_16x16x32_bf16 v[36:39], v[172:175], v[196:199], v[36:39]
	v_mfma_f32_16x16x32_bf16 v[28:31], v[180:183], v[196:199], v[28:31]
	v_mfma_f32_16x16x32_bf16 v[20:23], v[172:175], v[204:207], v[20:23]
	v_mfma_f32_16x16x32_bf16 v[12:15], v[180:183], v[204:207], v[12:15]
	v_mfma_f32_16x16x32_bf16 v[4:7], v[172:175], v[212:215], v[4:7]
	v_mfma_f32_16x16x32_bf16 v[0:3], v[180:183], v[212:215], v[0:3]
	s_barrier
	s_add_i32 s48, s48, 2
	s_add_u32 s46, s46, 0x100
	s_addc_u32 s47, s47, 0
	s_cmp_gt_u32 s48, 41
	s_mov_b64 s[18:19], s[20:21]
	s_cbranch_scc0 .LBB0_296
	s_and_b64 vcc, exec, s[14:15]
	s_cbranch_vccz .LBB0_299
	s_barrier

.LBB0_430:
	s_add_u32 s28, s28, 0x40080
	s_addc_u32 s29, s29, 0
	s_add_u32 s56, s30, 0x100
	s_addc_u32 s57, s31, 0
	s_mov_b32 s58, -2
	v_xor_b32_e32 v246, 64, v241
	v_xor_b32_e32 v247, 64, v237
	v_add_u32_e32 v248, s50, v247
	v_add_u32_e32 v249, s51, v247
	ds_read_b128 v[130:133], v239
	ds_read_b128 v[134:137], v248
	ds_read_b128 v[138:141], v239 offset:2048
	ds_read_b128 v[142:145], v248 offset:2048
	ds_read_b128 v[146:149], v240
	ds_read_b128 v[150:153], v249
	ds_read_b128 v[154:157], v240 offset:2048
	ds_read_b128 v[158:161], v249 offset:2048
	s_add_u32 s30, s28, 0xfffc0080
	s_addc_u32 s31, s29, -1
	s_cmp_eq_u32 s58, 12
	s_cselect_b32 s35, s9, s31
	s_cselect_b32 s34, s23, s30
	s_cselect_b32 s31, s21, s57
	s_cselect_b32 s30, s55, s56
	v_lshl_add_u64 v[80:81], s[28:29], 0, v[222:223]
	s_add_i32 m0, s36, 0xc000
	ds_read_b128 v[162:165], v241
	ds_read_b128 v[166:169], v246
	ds_read_b128 v[170:173], v241 offset:2048
	ds_read_b128 v[174:177], v246 offset:2048
	ds_read_b128 v[178:181], v241 offset:4096
	ds_read_b128 v[182:185], v246 offset:4096
	ds_read_b128 v[186:189], v241 offset:6144
	ds_read_b128 v[190:193], v246 offset:6144
	global_load_lds_dwordx4 v[80:81], off
	v_lshl_add_u64 v[80:81], s[28:29], 0, v[224:225]
	s_add_i32 m0, s36, 0xe000
	s_nop 0
	global_load_lds_dwordx4 v[80:81], off
	s_waitcnt vmcnt(8)
	s_waitcnt lgkmcnt(0)
	s_barrier
	s_waitcnt lgkmcnt(0)
	v_mfma_f32_16x16x32_bf16 v[126:129], v[130:133], v[162:165], 0
	s_add_i32 s54, s54, 1
	s_mul_i32 s6, s54, s44
	s_mul_hi_u32 s7, s54, s49
	v_mfma_f32_16x16x32_bf16 v[122:125], v[138:141], v[162:165], 0
	s_add_i32 s7, s7, s6
	s_mul_i32 s6, s54, s49
	s_add_u32 s24, s6, s96
	v_mfma_f32_16x16x32_bf16 v[110:113], v[130:133], v[170:173], 0
	s_addc_u32 s25, s7, s45
	v_cmp_lt_i64_e64 s[6:7], s[24:25], v[226:227]
	s_ashr_i32 s9, s24, 31
	v_mfma_f32_16x16x32_bf16 v[106:109], v[138:141], v[170:173], 0
	s_lshr_b32 s9, s9, 29
	s_add_i32 s9, s24, s9
	s_ashr_i32 s20, s9, 3
	v_mfma_f32_16x16x32_bf16 v[94:97], v[130:133], v[178:181], 0
	s_and_b32 s9, s9, -8
	s_sub_i32 s9, s24, s9
	s_cmp_lt_i32 s9, 0
	v_mfma_f32_16x16x32_bf16 v[90:93], v[138:141], v[178:181], 0
	s_movk_i32 s21, 0xe1
	s_cselect_b32 s21, s21, 0xe0
	s_mul_i32 s9, s9, s21
	v_mfma_f32_16x16x32_bf16 v[76:79], v[130:133], v[186:189], 0
	s_add_i32 s9, s9, s20
	s_mul_hi_i32 s20, s9, 0x92492493
	s_add_i32 s20, s20, s9
	v_mfma_f32_16x16x32_bf16 v[72:75], v[138:141], v[186:189], 0
	s_lshr_b32 s21, s20, 31
	s_ashr_i32 s20, s20, 6
	s_add_i32 s20, s20, s21
	v_mfma_f32_16x16x32_bf16 v[126:129], v[134:137], v[166:169], v[126:129]
	s_lshl_b32 s21, s20, 3
	s_sub_i32 s22, 0x80, s21
	s_min_i32 s22, s22, 8
	v_mfma_f32_16x16x32_bf16 v[122:125], v[142:145], v[166:169], v[122:125]
	s_abs_i32 s23, s22
	v_cvt_f32_u32_e32 v252, s23
	s_sub_i32 s25, 0, s23
	v_mfma_f32_16x16x32_bf16 v[110:113], v[134:137], v[174:177], v[110:113]
	s_mulk_i32 s20, 0x70
	s_sub_i32 s9, s9, s20
	v_rcp_iflag_f32_e32 v252, v252
	v_mfma_f32_16x16x32_bf16 v[106:109], v[142:145], v[174:177], v[106:109]
	s_abs_i32 s20, s9
	s_xor_b32 s24, s9, s22
	s_ashr_i32 s24, s24, 31
	v_mfma_f32_16x16x32_bf16 v[94:97], v[134:137], v[182:185], v[94:97]
	v_mul_f32_e32 v252, 0x4f7ffffe, v252
	v_cvt_u32_f32_e32 v252, v252
	s_nop 0
	v_mfma_f32_16x16x32_bf16 v[90:93], v[142:145], v[182:185], v[90:93]
	v_readfirstlane_b32 s26, v252
	s_mul_i32 s25, s25, s26
	s_mul_hi_u32 s25, s26, s25
	v_mfma_f32_16x16x32_bf16 v[76:79], v[134:137], v[190:193], v[76:79]
	s_add_i32 s26, s26, s25
	s_mul_hi_u32 s25, s20, s26
	s_mul_i32 s26, s25, s23
	v_mfma_f32_16x16x32_bf16 v[72:75], v[142:145], v[190:193], v[72:75]
	s_sub_i32 s20, s20, s26
	s_add_i32 s27, s25, 1
	s_sub_i32 s26, s20, s23
	v_mfma_f32_16x16x32_bf16 v[118:121], v[146:149], v[162:165], 0
	s_cmp_ge_u32 s20, s23
	s_cselect_b32 s25, s27, s25
	s_cselect_b32 s20, s26, s20
	v_mfma_f32_16x16x32_bf16 v[114:117], v[154:157], v[162:165], 0
	s_add_i32 s26, s25, 1
	s_cmp_ge_u32 s20, s23
	s_cselect_b32 s20, s26, s25
	v_mfma_f32_16x16x32_bf16 v[102:105], v[146:149], v[170:173], 0
	s_xor_b32 s20, s20, s24
	s_sub_i32 s20, s20, s24
	s_mul_i32 s22, s20, s22
	v_mfma_f32_16x16x32_bf16 v[98:101], v[154:157], v[170:173], 0
	s_sub_i32 s9, s9, s22
	s_add_i32 s22, s21, s9
	s_ashr_i32 s23, s22, 31
	v_mfma_f32_16x16x32_bf16 v[86:89], v[146:149], v[178:181], 0
	s_lshl_b64 s[24:25], s[22:23], 19
	s_add_u32 s24, s90, s24
	s_addc_u32 s25, s91, s25
	v_mfma_f32_16x16x32_bf16 v[80:83], v[154:157], v[178:181], 0
	s_and_b64 s[26:27], s[6:7], exec
	s_cselect_b32 s9, s25, s29
	s_cselect_b32 s23, s24, s28
	v_mfma_f32_16x16x32_bf16 v[68:71], v[146:149], v[186:189], 0
	s_ashr_i32 s21, s20, 31
	s_lshl_b64 s[26:27], s[20:21], 19
	s_add_u32 s26, s2, s26
	v_mfma_f32_16x16x32_bf16 v[64:67], v[154:157], v[186:189], 0
	s_addc_u32 s27, s3, s27
	s_and_b64 s[98:99], s[6:7], exec
	s_cselect_b32 s21, s27, s31
	v_mfma_f32_16x16x32_bf16 v[118:121], v[150:153], v[166:169], v[118:121]
	s_cselect_b32 s55, s26, s30
	v_mfma_f32_16x16x32_bf16 v[114:117], v[158:161], v[166:169], v[114:117]
	v_mfma_f32_16x16x32_bf16 v[102:105], v[150:153], v[174:177], v[102:105]
	v_mfma_f32_16x16x32_bf16 v[98:101], v[158:161], v[174:177], v[98:101]
	v_mfma_f32_16x16x32_bf16 v[86:89], v[150:153], v[182:185], v[86:89]
	v_mfma_f32_16x16x32_bf16 v[80:83], v[158:161], v[182:185], v[80:83]
	v_mfma_f32_16x16x32_bf16 v[68:71], v[150:153], v[190:193], v[68:71]
	v_mfma_f32_16x16x32_bf16 v[64:67], v[158:161], v[190:193], v[64:67]
	s_barrier
	s_add_i32 s59, s50, s33
	v_lshl_add_u64 v[194:195], s[30:31], 0, v[212:213]
	s_mov_b32 m0, s59
	ds_read_b128 v[162:165], v241 offset:16384
	ds_read_b128 v[166:169], v246 offset:16384
	ds_read_b128 v[170:173], v241 offset:18432
	ds_read_b128 v[174:177], v246 offset:18432
	ds_read_b128 v[178:181], v241 offset:20480
	ds_read_b128 v[182:185], v246 offset:20480
	ds_read_b128 v[186:189], v241 offset:22528
	ds_read_b128 v[190:193], v246 offset:22528
	global_load_lds_dwordx4 v[194:195], off
	s_add_i32 m0, s59, 0x2000
	s_add_u32 s60, s30, 0x40000
	v_lshl_add_u64 v[196:197], s[30:31], 0, v[216:217]
	s_addc_u32 s61, s31, 0
	s_add_i32 s59, s51, s33
	global_load_lds_dwordx4 v[196:197], off
	v_lshl_add_u64 v[84:85], s[60:61], 0, v[212:213]
	s_mov_b32 m0, s59
	v_lshl_add_u64 v[198:199], s[34:35], 0, v[210:211]
	global_load_lds_dwordx4 v[84:85], off
	v_lshl_add_u64 v[84:85], s[60:61], 0, v[216:217]
	s_add_i32 m0, s59, 0x2000
	v_lshl_add_u64 v[200:201], s[34:35], 0, v[214:215]
	global_load_lds_dwordx4 v[84:85], off
	s_mov_b32 m0, s36
	s_nop 0
	global_load_lds_dwordx4 v[198:199], off
	s_mov_b32 m0, s37
	s_nop 0
	global_load_lds_dwordx4 v[200:201], off
	s_waitcnt vmcnt(8)
	s_waitcnt lgkmcnt(0)
	s_barrier
	s_waitcnt lgkmcnt(0)
	v_mfma_f32_16x16x32_bf16 v[60:63], v[130:133], v[162:165], 0
	v_mfma_f32_16x16x32_bf16 v[56:59], v[138:141], v[162:165], 0
	v_mfma_f32_16x16x32_bf16 v[44:47], v[130:133], v[170:173], 0
	v_mfma_f32_16x16x32_bf16 v[40:43], v[138:141], v[170:173], 0
	v_mfma_f32_16x16x32_bf16 v[28:31], v[130:133], v[178:181], 0
	v_mfma_f32_16x16x32_bf16 v[24:27], v[138:141], v[178:181], 0
	v_mfma_f32_16x16x32_bf16 v[12:15], v[130:133], v[186:189], 0
	v_mfma_f32_16x16x32_bf16 v[8:11], v[138:141], v[186:189], 0
	v_mfma_f32_16x16x32_bf16 v[60:63], v[134:137], v[166:169], v[60:63]
	v_mfma_f32_16x16x32_bf16 v[56:59], v[142:145], v[166:169], v[56:59]
	v_mfma_f32_16x16x32_bf16 v[44:47], v[134:137], v[174:177], v[44:47]
	v_mfma_f32_16x16x32_bf16 v[40:43], v[142:145], v[174:177], v[40:43]
	v_mfma_f32_16x16x32_bf16 v[28:31], v[134:137], v[182:185], v[28:31]
	v_mfma_f32_16x16x32_bf16 v[24:27], v[142:145], v[182:185], v[24:27]
	v_mfma_f32_16x16x32_bf16 v[12:15], v[134:137], v[190:193], v[12:15]
	v_mfma_f32_16x16x32_bf16 v[8:11], v[142:145], v[190:193], v[8:11]
	v_mfma_f32_16x16x32_bf16 v[52:55], v[146:149], v[162:165], 0
	v_mfma_f32_16x16x32_bf16 v[48:51], v[154:157], v[162:165], 0
	v_mfma_f32_16x16x32_bf16 v[36:39], v[146:149], v[170:173], 0
	v_mfma_f32_16x16x32_bf16 v[32:35], v[154:157], v[170:173], 0
	v_mfma_f32_16x16x32_bf16 v[20:23], v[146:149], v[178:181], 0
	v_mfma_f32_16x16x32_bf16 v[16:19], v[154:157], v[178:181], 0
	v_mfma_f32_16x16x32_bf16 v[4:7], v[146:149], v[186:189], 0
	v_mfma_f32_16x16x32_bf16 v[0:3], v[154:157], v[186:189], 0
	v_mfma_f32_16x16x32_bf16 v[52:55], v[150:153], v[166:169], v[52:55]
	v_mfma_f32_16x16x32_bf16 v[48:51], v[158:161], v[166:169], v[48:51]
	v_mfma_f32_16x16x32_bf16 v[36:39], v[150:153], v[174:177], v[36:39]
	v_mfma_f32_16x16x32_bf16 v[32:35], v[158:161], v[174:177], v[32:35]
	v_mfma_f32_16x16x32_bf16 v[20:23], v[150:153], v[182:185], v[20:23]
	v_mfma_f32_16x16x32_bf16 v[16:19], v[158:161], v[182:185], v[16:19]
	v_mfma_f32_16x16x32_bf16 v[4:7], v[150:153], v[190:193], v[4:7]
	v_mfma_f32_16x16x32_bf16 v[0:3], v[158:161], v[190:193], v[0:3]
	s_barrier
	s_add_i32 s59, 0, 0x18000
	v_add_u32_e32 v84, s59, v237
	v_add_u32_e32 v250, s59, v247
	s_add_i32 s60, 0, 0x1c000
	ds_read_b128 v[130:133], v84
	ds_read_b128 v[134:137], v250
	ds_read_b128 v[138:141], v84 offset:2048
	ds_read_b128 v[142:145], v250 offset:2048
	v_add_u32_e32 v84, s60, v237
	v_add_u32_e32 v251, s60, v247
	ds_read_b128 v[146:149], v84
	ds_read_b128 v[150:153], v251
	ds_read_b128 v[154:157], v84 offset:2048
	ds_read_b128 v[158:161], v251 offset:2048
	s_add_u32 s34, s34, 0x40000
	s_addc_u32 s35, s35, 0
	s_mov_b32 m0, s38
	v_lshl_add_u64 v[84:85], s[34:35], 0, v[210:211]
	ds_read_b128 v[162:165], v241 offset:32768
	ds_read_b128 v[166:169], v246 offset:32768
	ds_read_b128 v[170:173], v241 offset:34816
	ds_read_b128 v[174:177], v246 offset:34816
	ds_read_b128 v[178:181], v241 offset:36864
	ds_read_b128 v[182:185], v246 offset:36864
	ds_read_b128 v[186:189], v241 offset:38912
	ds_read_b128 v[190:193], v246 offset:38912
	global_load_lds_dwordx4 v[84:85], off
	v_lshl_add_u64 v[84:85], s[34:35], 0, v[214:215]
	s_mov_b32 m0, s39
	s_nop 0
	global_load_lds_dwordx4 v[84:85], off
	s_waitcnt vmcnt(8)
	s_waitcnt lgkmcnt(0)
	s_barrier
	s_waitcnt lgkmcnt(0)
	v_mfma_f32_16x16x32_bf16 v[126:129], v[130:133], v[162:165], v[126:129]
	v_mfma_f32_16x16x32_bf16 v[122:125], v[138:141], v[162:165], v[122:125]
	v_mfma_f32_16x16x32_bf16 v[110:113], v[130:133], v[170:173], v[110:113]
	v_mfma_f32_16x16x32_bf16 v[106:109], v[138:141], v[170:173], v[106:109]
	v_mfma_f32_16x16x32_bf16 v[94:97], v[130:133], v[178:181], v[94:97]
	v_mfma_f32_16x16x32_bf16 v[90:93], v[138:141], v[178:181], v[90:93]
	v_mfma_f32_16x16x32_bf16 v[76:79], v[130:133], v[186:189], v[76:79]
	v_mfma_f32_16x16x32_bf16 v[72:75], v[138:141], v[186:189], v[72:75]
	v_mfma_f32_16x16x32_bf16 v[126:129], v[134:137], v[166:169], v[126:129]
	v_mfma_f32_16x16x32_bf16 v[122:125], v[142:145], v[166:169], v[122:125]
	v_mfma_f32_16x16x32_bf16 v[110:113], v[134:137], v[174:177], v[110:113]
	v_mfma_f32_16x16x32_bf16 v[106:109], v[142:145], v[174:177], v[106:109]
	v_mfma_f32_16x16x32_bf16 v[94:97], v[134:137], v[182:185], v[94:97]
	v_mfma_f32_16x16x32_bf16 v[90:93], v[142:145], v[182:185], v[90:93]
	v_mfma_f32_16x16x32_bf16 v[76:79], v[134:137], v[190:193], v[76:79]
	v_mfma_f32_16x16x32_bf16 v[72:75], v[142:145], v[190:193], v[72:75]
	v_mfma_f32_16x16x32_bf16 v[118:121], v[146:149], v[162:165], v[118:121]
	v_mfma_f32_16x16x32_bf16 v[114:117], v[154:157], v[162:165], v[114:117]
	v_mfma_f32_16x16x32_bf16 v[102:105], v[146:149], v[170:173], v[102:105]
	v_mfma_f32_16x16x32_bf16 v[98:101], v[154:157], v[170:173], v[98:101]
	v_mfma_f32_16x16x32_bf16 v[84:87], v[146:149], v[178:181], v[86:89]
	v_mfma_f32_16x16x32_bf16 v[80:83], v[154:157], v[178:181], v[80:83]
	v_mfma_f32_16x16x32_bf16 v[68:71], v[146:149], v[186:189], v[68:71]
	v_mfma_f32_16x16x32_bf16 v[64:67], v[154:157], v[186:189], v[64:67]
	v_mfma_f32_16x16x32_bf16 v[118:121], v[150:153], v[166:169], v[118:121]
	v_mfma_f32_16x16x32_bf16 v[114:117], v[158:161], v[166:169], v[114:117]
	v_mfma_f32_16x16x32_bf16 v[102:105], v[150:153], v[174:177], v[102:105]
	v_mfma_f32_16x16x32_bf16 v[98:101], v[158:161], v[174:177], v[98:101]
	v_mfma_f32_16x16x32_bf16 v[86:89], v[150:153], v[182:185], v[84:87]
	v_mfma_f32_16x16x32_bf16 v[82:85], v[158:161], v[182:185], v[80:83]
	v_mfma_f32_16x16x32_bf16 v[68:71], v[150:153], v[190:193], v[68:71]
	v_mfma_f32_16x16x32_bf16 v[64:67], v[158:161], v[190:193], v[64:67]
	s_barrier
	s_add_i32 s34, s59, s33
	v_lshl_add_u64 v[80:81], v[194:195], 0, s[16:17]
	s_mov_b32 m0, s34
	ds_read_b128 v[162:165], v241 offset:49152
	ds_read_b128 v[166:169], v246 offset:49152
	ds_read_b128 v[170:173], v241 offset:51200
	ds_read_b128 v[174:177], v246 offset:51200
	ds_read_b128 v[178:181], v241 offset:53248
	ds_read_b128 v[182:185], v246 offset:53248
	ds_read_b128 v[186:189], v241 offset:55296
	ds_read_b128 v[190:193], v246 offset:55296
	global_load_lds_dwordx4 v[80:81], off
	s_add_i32 m0, s34, 0x2000
	s_add_u32 s30, s30, 0x40080
	v_lshl_add_u64 v[80:81], v[196:197], 0, s[16:17]
	s_addc_u32 s31, s31, 0
	s_add_i32 s34, s60, s33
	global_load_lds_dwordx4 v[80:81], off
	v_lshl_add_u64 v[80:81], s[30:31], 0, v[212:213]
	s_mov_b32 m0, s34
	s_nop 0
	global_load_lds_dwordx4 v[80:81], off
	v_lshl_add_u64 v[80:81], s[30:31], 0, v[216:217]
	s_add_i32 m0, s34, 0x2000
	s_nop 0
	global_load_lds_dwordx4 v[80:81], off
	v_lshl_add_u64 v[80:81], v[198:199], 0, s[16:17]
	s_mov_b32 m0, s47
	s_nop 0
	global_load_lds_dwordx4 v[80:81], off
	v_lshl_add_u64 v[80:81], v[200:201], 0, s[16:17]
	s_mov_b32 m0, s48
	s_nop 0
	global_load_lds_dwordx4 v[80:81], off
	s_waitcnt vmcnt(8)
	s_waitcnt lgkmcnt(0)
	s_barrier
	s_waitcnt lgkmcnt(0)
	v_mfma_f32_16x16x32_bf16 v[60:63], v[130:133], v[162:165], v[60:63]
	v_mfma_f32_16x16x32_bf16 v[56:59], v[138:141], v[162:165], v[56:59]
	v_mfma_f32_16x16x32_bf16 v[44:47], v[130:133], v[170:173], v[44:47]
	v_mfma_f32_16x16x32_bf16 v[40:43], v[138:141], v[170:173], v[40:43]
	v_mfma_f32_16x16x32_bf16 v[28:31], v[130:133], v[178:181], v[28:31]
	v_mfma_f32_16x16x32_bf16 v[24:27], v[138:141], v[178:181], v[24:27]
	v_mfma_f32_16x16x32_bf16 v[12:15], v[130:133], v[186:189], v[12:15]
	v_mfma_f32_16x16x32_bf16 v[8:11], v[138:141], v[186:189], v[8:11]
	v_mfma_f32_16x16x32_bf16 v[60:63], v[134:137], v[166:169], v[60:63]
	v_mfma_f32_16x16x32_bf16 v[56:59], v[142:145], v[166:169], v[56:59]
	v_mfma_f32_16x16x32_bf16 v[44:47], v[134:137], v[174:177], v[44:47]
	v_mfma_f32_16x16x32_bf16 v[40:43], v[142:145], v[174:177], v[40:43]
	v_mfma_f32_16x16x32_bf16 v[28:31], v[134:137], v[182:185], v[28:31]
	v_mfma_f32_16x16x32_bf16 v[24:27], v[142:145], v[182:185], v[24:27]
	v_mfma_f32_16x16x32_bf16 v[12:15], v[134:137], v[190:193], v[12:15]
	v_mfma_f32_16x16x32_bf16 v[8:11], v[142:145], v[190:193], v[8:11]
	v_mfma_f32_16x16x32_bf16 v[52:55], v[146:149], v[162:165], v[52:55]
	v_mfma_f32_16x16x32_bf16 v[48:51], v[154:157], v[162:165], v[48:51]
	v_mfma_f32_16x16x32_bf16 v[36:39], v[146:149], v[170:173], v[36:39]
	v_mfma_f32_16x16x32_bf16 v[32:35], v[154:157], v[170:173], v[32:35]
	v_mfma_f32_16x16x32_bf16 v[20:23], v[146:149], v[178:181], v[20:23]
	v_mfma_f32_16x16x32_bf16 v[16:19], v[154:157], v[178:181], v[16:19]
	v_mfma_f32_16x16x32_bf16 v[4:7], v[146:149], v[186:189], v[4:7]
	v_mfma_f32_16x16x32_bf16 v[0:3], v[154:157], v[186:189], v[0:3]
	v_mfma_f32_16x16x32_bf16 v[52:55], v[150:153], v[166:169], v[52:55]
	v_mfma_f32_16x16x32_bf16 v[48:51], v[158:161], v[166:169], v[48:51]
	v_mfma_f32_16x16x32_bf16 v[36:39], v[150:153], v[174:177], v[36:39]
	v_mfma_f32_16x16x32_bf16 v[32:35], v[158:161], v[174:177], v[32:35]
	v_mfma_f32_16x16x32_bf16 v[20:23], v[150:153], v[182:185], v[20:23]
	v_mfma_f32_16x16x32_bf16 v[16:19], v[158:161], v[182:185], v[16:19]
	v_mfma_f32_16x16x32_bf16 v[4:7], v[150:153], v[190:193], v[4:7]
	v_mfma_f32_16x16x32_bf16 v[0:3], v[158:161], v[190:193], v[0:3]
	s_barrier
	s_add_i32 s58, s58, 2
	s_add_u32 s28, s28, 0x100
	s_addc_u32 s29, s29, 0
	s_add_u32 s56, s56, 0x100
	s_addc_u32 s57, s57, 0
	s_cmp_gt_u32 s58, 13
.LBB0_433:
	ds_read_b128 v[130:133], v239
	ds_read_b128 v[134:137], v248
	ds_read_b128 v[138:141], v239 offset:2048
	ds_read_b128 v[142:145], v248 offset:2048
	ds_read_b128 v[146:149], v240
	ds_read_b128 v[150:153], v249
	ds_read_b128 v[154:157], v240 offset:2048
	ds_read_b128 v[158:161], v249 offset:2048
	s_add_u32 s30, s28, 0xfffc0080
	s_addc_u32 s31, s29, -1
	s_cmp_eq_u32 s58, 12
	s_cselect_b32 s35, s9, s31
	s_cselect_b32 s34, s23, s30
	s_cselect_b32 s31, s21, s57
	s_cselect_b32 s30, s55, s56
	v_lshl_add_u64 v[80:81], s[28:29], 0, v[222:223]
	s_add_i32 m0, s36, 0xc000
	ds_read_b128 v[162:165], v241
	ds_read_b128 v[166:169], v246
	ds_read_b128 v[170:173], v241 offset:2048
	ds_read_b128 v[174:177], v246 offset:2048
	ds_read_b128 v[178:181], v241 offset:4096
	ds_read_b128 v[182:185], v246 offset:4096
	ds_read_b128 v[186:189], v241 offset:6144
	ds_read_b128 v[190:193], v246 offset:6144
	global_load_lds_dwordx4 v[80:81], off
	v_lshl_add_u64 v[80:81], s[28:29], 0, v[224:225]
	s_add_i32 m0, s36, 0xe000
	s_nop 0
	global_load_lds_dwordx4 v[80:81], off
	s_waitcnt vmcnt(8)
	s_waitcnt lgkmcnt(0)
	s_barrier
	s_waitcnt lgkmcnt(0)
	v_mfma_f32_16x16x32_bf16 v[126:129], v[130:133], v[162:165], v[126:129]
	v_mfma_f32_16x16x32_bf16 v[122:125], v[138:141], v[162:165], v[122:125]
	v_mfma_f32_16x16x32_bf16 v[110:113], v[130:133], v[170:173], v[110:113]
	v_mfma_f32_16x16x32_bf16 v[106:109], v[138:141], v[170:173], v[106:109]
	v_mfma_f32_16x16x32_bf16 v[94:97], v[130:133], v[178:181], v[94:97]
	v_mfma_f32_16x16x32_bf16 v[90:93], v[138:141], v[178:181], v[90:93]
	v_mfma_f32_16x16x32_bf16 v[76:79], v[130:133], v[186:189], v[76:79]
	v_mfma_f32_16x16x32_bf16 v[72:75], v[138:141], v[186:189], v[72:75]
	v_mfma_f32_16x16x32_bf16 v[126:129], v[134:137], v[166:169], v[126:129]
	v_mfma_f32_16x16x32_bf16 v[122:125], v[142:145], v[166:169], v[122:125]
	v_mfma_f32_16x16x32_bf16 v[110:113], v[134:137], v[174:177], v[110:113]
	v_mfma_f32_16x16x32_bf16 v[106:109], v[142:145], v[174:177], v[106:109]
	v_mfma_f32_16x16x32_bf16 v[94:97], v[134:137], v[182:185], v[94:97]
	v_mfma_f32_16x16x32_bf16 v[90:93], v[142:145], v[182:185], v[90:93]
	v_mfma_f32_16x16x32_bf16 v[76:79], v[134:137], v[190:193], v[76:79]
	v_mfma_f32_16x16x32_bf16 v[72:75], v[142:145], v[190:193], v[72:75]
	v_mfma_f32_16x16x32_bf16 v[118:121], v[146:149], v[162:165], v[118:121]
	v_mfma_f32_16x16x32_bf16 v[114:117], v[154:157], v[162:165], v[114:117]
	v_mfma_f32_16x16x32_bf16 v[102:105], v[146:149], v[170:173], v[102:105]
	v_mfma_f32_16x16x32_bf16 v[98:101], v[154:157], v[170:173], v[98:101]
	v_mfma_f32_16x16x32_bf16 v[86:89], v[146:149], v[178:181], v[86:89]
	v_mfma_f32_16x16x32_bf16 v[80:83], v[154:157], v[178:181], v[82:85]
	v_mfma_f32_16x16x32_bf16 v[68:71], v[146:149], v[186:189], v[68:71]
	v_mfma_f32_16x16x32_bf16 v[64:67], v[154:157], v[186:189], v[64:67]
	v_mfma_f32_16x16x32_bf16 v[118:121], v[150:153], v[166:169], v[118:121]
	v_mfma_f32_16x16x32_bf16 v[114:117], v[158:161], v[166:169], v[114:117]
	v_mfma_f32_16x16x32_bf16 v[102:105], v[150:153], v[174:177], v[102:105]
	v_mfma_f32_16x16x32_bf16 v[98:101], v[158:161], v[174:177], v[98:101]
	v_mfma_f32_16x16x32_bf16 v[86:89], v[150:153], v[182:185], v[86:89]
	v_mfma_f32_16x16x32_bf16 v[80:83], v[158:161], v[182:185], v[80:83]
	v_mfma_f32_16x16x32_bf16 v[68:71], v[150:153], v[190:193], v[68:71]
	v_mfma_f32_16x16x32_bf16 v[64:67], v[158:161], v[190:193], v[64:67]
	s_barrier
	s_add_i32 s59, s50, s33
	v_lshl_add_u64 v[194:195], s[30:31], 0, v[212:213]
	s_mov_b32 m0, s59
	ds_read_b128 v[162:165], v241 offset:16384
	ds_read_b128 v[166:169], v246 offset:16384
	ds_read_b128 v[170:173], v241 offset:18432
	ds_read_b128 v[174:177], v246 offset:18432
	ds_read_b128 v[178:181], v241 offset:20480
	ds_read_b128 v[182:185], v246 offset:20480
	ds_read_b128 v[186:189], v241 offset:22528
	ds_read_b128 v[190:193], v246 offset:22528
	global_load_lds_dwordx4 v[194:195], off
	s_add_i32 m0, s59, 0x2000
	s_add_u32 s60, s30, 0x40000
	v_lshl_add_u64 v[196:197], s[30:31], 0, v[216:217]
	s_addc_u32 s61, s31, 0
	s_add_i32 s59, s51, s33
	global_load_lds_dwordx4 v[196:197], off
	v_lshl_add_u64 v[84:85], s[60:61], 0, v[212:213]
	s_mov_b32 m0, s59
	v_lshl_add_u64 v[198:199], s[34:35], 0, v[210:211]
	global_load_lds_dwordx4 v[84:85], off
	v_lshl_add_u64 v[84:85], s[60:61], 0, v[216:217]
	s_add_i32 m0, s59, 0x2000
	v_lshl_add_u64 v[200:201], s[34:35], 0, v[214:215]
	global_load_lds_dwordx4 v[84:85], off
	s_mov_b32 m0, s36
	s_nop 0
	global_load_lds_dwordx4 v[198:199], off
	s_mov_b32 m0, s37
	s_nop 0
	global_load_lds_dwordx4 v[200:201], off
	s_waitcnt vmcnt(8)
	s_waitcnt lgkmcnt(0)
	s_barrier
	s_waitcnt lgkmcnt(0)
	v_mfma_f32_16x16x32_bf16 v[60:63], v[130:133], v[162:165], v[60:63]
	v_mfma_f32_16x16x32_bf16 v[56:59], v[138:141], v[162:165], v[56:59]
	v_mfma_f32_16x16x32_bf16 v[44:47], v[130:133], v[170:173], v[44:47]
	v_mfma_f32_16x16x32_bf16 v[40:43], v[138:141], v[170:173], v[40:43]
	v_mfma_f32_16x16x32_bf16 v[28:31], v[130:133], v[178:181], v[28:31]
	v_mfma_f32_16x16x32_bf16 v[24:27], v[138:141], v[178:181], v[24:27]
	v_mfma_f32_16x16x32_bf16 v[12:15], v[130:133], v[186:189], v[12:15]
	v_mfma_f32_16x16x32_bf16 v[8:11], v[138:141], v[186:189], v[8:11]
	v_mfma_f32_16x16x32_bf16 v[60:63], v[134:137], v[166:169], v[60:63]
	v_mfma_f32_16x16x32_bf16 v[56:59], v[142:145], v[166:169], v[56:59]
	v_mfma_f32_16x16x32_bf16 v[44:47], v[134:137], v[174:177], v[44:47]
	v_mfma_f32_16x16x32_bf16 v[40:43], v[142:145], v[174:177], v[40:43]
	v_mfma_f32_16x16x32_bf16 v[28:31], v[134:137], v[182:185], v[28:31]
	v_mfma_f32_16x16x32_bf16 v[24:27], v[142:145], v[182:185], v[24:27]
	v_mfma_f32_16x16x32_bf16 v[12:15], v[134:137], v[190:193], v[12:15]
	v_mfma_f32_16x16x32_bf16 v[8:11], v[142:145], v[190:193], v[8:11]
	v_mfma_f32_16x16x32_bf16 v[52:55], v[146:149], v[162:165], v[52:55]
	v_mfma_f32_16x16x32_bf16 v[48:51], v[154:157], v[162:165], v[48:51]
	v_mfma_f32_16x16x32_bf16 v[36:39], v[146:149], v[170:173], v[36:39]
	v_mfma_f32_16x16x32_bf16 v[32:35], v[154:157], v[170:173], v[32:35]
	v_mfma_f32_16x16x32_bf16 v[20:23], v[146:149], v[178:181], v[20:23]
	v_mfma_f32_16x16x32_bf16 v[16:19], v[154:157], v[178:181], v[16:19]
	v_mfma_f32_16x16x32_bf16 v[4:7], v[146:149], v[186:189], v[4:7]
	v_mfma_f32_16x16x32_bf16 v[0:3], v[154:157], v[186:189], v[0:3]
	v_mfma_f32_16x16x32_bf16 v[52:55], v[150:153], v[166:169], v[52:55]
	v_mfma_f32_16x16x32_bf16 v[48:51], v[158:161], v[166:169], v[48:51]
	v_mfma_f32_16x16x32_bf16 v[36:39], v[150:153], v[174:177], v[36:39]
	v_mfma_f32_16x16x32_bf16 v[32:35], v[158:161], v[174:177], v[32:35]
	v_mfma_f32_16x16x32_bf16 v[20:23], v[150:153], v[182:185], v[20:23]
	v_mfma_f32_16x16x32_bf16 v[16:19], v[158:161], v[182:185], v[16:19]
	v_mfma_f32_16x16x32_bf16 v[4:7], v[150:153], v[190:193], v[4:7]
	v_mfma_f32_16x16x32_bf16 v[0:3], v[158:161], v[190:193], v[0:3]
	s_barrier
	s_add_i32 s59, 0, 0x18000
	v_add_u32_e32 v84, s59, v237
	v_add_u32_e32 v250, s59, v247
	s_add_i32 s60, 0, 0x1c000
	ds_read_b128 v[130:133], v84
	ds_read_b128 v[134:137], v250
	ds_read_b128 v[138:141], v84 offset:2048
	ds_read_b128 v[142:145], v250 offset:2048
	v_add_u32_e32 v84, s60, v237
	v_add_u32_e32 v251, s60, v247
	ds_read_b128 v[146:149], v84
	ds_read_b128 v[150:153], v251
	ds_read_b128 v[154:157], v84 offset:2048
	ds_read_b128 v[158:161], v251 offset:2048
	s_add_u32 s34, s34, 0x40000
	s_addc_u32 s35, s35, 0
	s_mov_b32 m0, s38
	v_lshl_add_u64 v[84:85], s[34:35], 0, v[210:211]
	ds_read_b128 v[162:165], v241 offset:32768
	ds_read_b128 v[166:169], v246 offset:32768
	ds_read_b128 v[170:173], v241 offset:34816
	ds_read_b128 v[174:177], v246 offset:34816
	ds_read_b128 v[178:181], v241 offset:36864
	ds_read_b128 v[182:185], v246 offset:36864
	ds_read_b128 v[186:189], v241 offset:38912
	ds_read_b128 v[190:193], v246 offset:38912
	global_load_lds_dwordx4 v[84:85], off
	v_lshl_add_u64 v[84:85], s[34:35], 0, v[214:215]
	s_mov_b32 m0, s39
	s_nop 0
	global_load_lds_dwordx4 v[84:85], off
	s_waitcnt vmcnt(8)
	s_waitcnt lgkmcnt(0)
	s_barrier
	s_waitcnt lgkmcnt(0)
	v_mfma_f32_16x16x32_bf16 v[126:129], v[130:133], v[162:165], v[126:129]
	v_mfma_f32_16x16x32_bf16 v[122:125], v[138:141], v[162:165], v[122:125]
	v_mfma_f32_16x16x32_bf16 v[110:113], v[130:133], v[170:173], v[110:113]
	v_mfma_f32_16x16x32_bf16 v[106:109], v[138:141], v[170:173], v[106:109]
	v_mfma_f32_16x16x32_bf16 v[94:97], v[130:133], v[178:181], v[94:97]
	v_mfma_f32_16x16x32_bf16 v[90:93], v[138:141], v[178:181], v[90:93]
	v_mfma_f32_16x16x32_bf16 v[76:79], v[130:133], v[186:189], v[76:79]
	v_mfma_f32_16x16x32_bf16 v[72:75], v[138:141], v[186:189], v[72:75]
	v_mfma_f32_16x16x32_bf16 v[126:129], v[134:137], v[166:169], v[126:129]
	v_mfma_f32_16x16x32_bf16 v[122:125], v[142:145], v[166:169], v[122:125]
	v_mfma_f32_16x16x32_bf16 v[110:113], v[134:137], v[174:177], v[110:113]
	v_mfma_f32_16x16x32_bf16 v[106:109], v[142:145], v[174:177], v[106:109]
	v_mfma_f32_16x16x32_bf16 v[94:97], v[134:137], v[182:185], v[94:97]
	v_mfma_f32_16x16x32_bf16 v[90:93], v[142:145], v[182:185], v[90:93]
	v_mfma_f32_16x16x32_bf16 v[76:79], v[134:137], v[190:193], v[76:79]
	v_mfma_f32_16x16x32_bf16 v[72:75], v[142:145], v[190:193], v[72:75]
	v_mfma_f32_16x16x32_bf16 v[118:121], v[146:149], v[162:165], v[118:121]
	v_mfma_f32_16x16x32_bf16 v[114:117], v[154:157], v[162:165], v[114:117]
	v_mfma_f32_16x16x32_bf16 v[102:105], v[146:149], v[170:173], v[102:105]
	v_mfma_f32_16x16x32_bf16 v[98:101], v[154:157], v[170:173], v[98:101]
	v_mfma_f32_16x16x32_bf16 v[84:87], v[146:149], v[178:181], v[86:89]
	v_mfma_f32_16x16x32_bf16 v[80:83], v[154:157], v[178:181], v[80:83]
	v_mfma_f32_16x16x32_bf16 v[68:71], v[146:149], v[186:189], v[68:71]
	v_mfma_f32_16x16x32_bf16 v[64:67], v[154:157], v[186:189], v[64:67]
	v_mfma_f32_16x16x32_bf16 v[118:121], v[150:153], v[166:169], v[118:121]
	v_mfma_f32_16x16x32_bf16 v[114:117], v[158:161], v[166:169], v[114:117]
	v_mfma_f32_16x16x32_bf16 v[102:105], v[150:153], v[174:177], v[102:105]
	v_mfma_f32_16x16x32_bf16 v[98:101], v[158:161], v[174:177], v[98:101]
	v_mfma_f32_16x16x32_bf16 v[86:89], v[150:153], v[182:185], v[84:87]
	v_mfma_f32_16x16x32_bf16 v[82:85], v[158:161], v[182:185], v[80:83]
	v_mfma_f32_16x16x32_bf16 v[68:71], v[150:153], v[190:193], v[68:71]
	v_mfma_f32_16x16x32_bf16 v[64:67], v[158:161], v[190:193], v[64:67]
	s_barrier
	s_add_i32 s34, s59, s33
	v_lshl_add_u64 v[80:81], v[194:195], 0, s[16:17]
	s_mov_b32 m0, s34
	ds_read_b128 v[162:165], v241 offset:49152
	ds_read_b128 v[166:169], v246 offset:49152
	ds_read_b128 v[170:173], v241 offset:51200
	ds_read_b128 v[174:177], v246 offset:51200
	ds_read_b128 v[178:181], v241 offset:53248
	ds_read_b128 v[182:185], v246 offset:53248
	ds_read_b128 v[186:189], v241 offset:55296
	ds_read_b128 v[190:193], v246 offset:55296
	global_load_lds_dwordx4 v[80:81], off
	s_add_i32 m0, s34, 0x2000
	s_add_u32 s30, s30, 0x40080
	v_lshl_add_u64 v[80:81], v[196:197], 0, s[16:17]
	s_addc_u32 s31, s31, 0
	s_add_i32 s34, s60, s33
	global_load_lds_dwordx4 v[80:81], off
	v_lshl_add_u64 v[80:81], s[30:31], 0, v[212:213]
	s_mov_b32 m0, s34
	s_nop 0
	global_load_lds_dwordx4 v[80:81], off
	v_lshl_add_u64 v[80:81], s[30:31], 0, v[216:217]
	s_add_i32 m0, s34, 0x2000
	s_nop 0
	global_load_lds_dwordx4 v[80:81], off
	v_lshl_add_u64 v[80:81], v[198:199], 0, s[16:17]
	s_mov_b32 m0, s47
	s_nop 0
	global_load_lds_dwordx4 v[80:81], off
	v_lshl_add_u64 v[80:81], v[200:201], 0, s[16:17]
	s_mov_b32 m0, s48
	s_nop 0
	global_load_lds_dwordx4 v[80:81], off
	s_waitcnt vmcnt(8)
	s_waitcnt lgkmcnt(0)
	s_barrier
	s_waitcnt lgkmcnt(0)
	v_mfma_f32_16x16x32_bf16 v[60:63], v[130:133], v[162:165], v[60:63]
	v_mfma_f32_16x16x32_bf16 v[56:59], v[138:141], v[162:165], v[56:59]
	v_mfma_f32_16x16x32_bf16 v[44:47], v[130:133], v[170:173], v[44:47]
	v_mfma_f32_16x16x32_bf16 v[40:43], v[138:141], v[170:173], v[40:43]
	v_mfma_f32_16x16x32_bf16 v[28:31], v[130:133], v[178:181], v[28:31]
	v_mfma_f32_16x16x32_bf16 v[24:27], v[138:141], v[178:181], v[24:27]
	v_mfma_f32_16x16x32_bf16 v[12:15], v[130:133], v[186:189], v[12:15]
	v_mfma_f32_16x16x32_bf16 v[8:11], v[138:141], v[186:189], v[8:11]
	v_mfma_f32_16x16x32_bf16 v[60:63], v[134:137], v[166:169], v[60:63]
	v_mfma_f32_16x16x32_bf16 v[56:59], v[142:145], v[166:169], v[56:59]
	v_mfma_f32_16x16x32_bf16 v[44:47], v[134:137], v[174:177], v[44:47]
	v_mfma_f32_16x16x32_bf16 v[40:43], v[142:145], v[174:177], v[40:43]
	v_mfma_f32_16x16x32_bf16 v[28:31], v[134:137], v[182:185], v[28:31]
	v_mfma_f32_16x16x32_bf16 v[24:27], v[142:145], v[182:185], v[24:27]
	v_mfma_f32_16x16x32_bf16 v[12:15], v[134:137], v[190:193], v[12:15]
	v_mfma_f32_16x16x32_bf16 v[8:11], v[142:145], v[190:193], v[8:11]
	v_mfma_f32_16x16x32_bf16 v[52:55], v[146:149], v[162:165], v[52:55]
	v_mfma_f32_16x16x32_bf16 v[48:51], v[154:157], v[162:165], v[48:51]
	v_mfma_f32_16x16x32_bf16 v[36:39], v[146:149], v[170:173], v[36:39]
	v_mfma_f32_16x16x32_bf16 v[32:35], v[154:157], v[170:173], v[32:35]
	v_mfma_f32_16x16x32_bf16 v[20:23], v[146:149], v[178:181], v[20:23]
	v_mfma_f32_16x16x32_bf16 v[16:19], v[154:157], v[178:181], v[16:19]
	v_mfma_f32_16x16x32_bf16 v[4:7], v[146:149], v[186:189], v[4:7]
	v_mfma_f32_16x16x32_bf16 v[0:3], v[154:157], v[186:189], v[0:3]
	v_mfma_f32_16x16x32_bf16 v[52:55], v[150:153], v[166:169], v[52:55]
	v_mfma_f32_16x16x32_bf16 v[48:51], v[158:161], v[166:169], v[48:51]
	v_mfma_f32_16x16x32_bf16 v[36:39], v[150:153], v[174:177], v[36:39]
	v_mfma_f32_16x16x32_bf16 v[32:35], v[158:161], v[174:177], v[32:35]
	v_mfma_f32_16x16x32_bf16 v[20:23], v[150:153], v[182:185], v[20:23]
	v_mfma_f32_16x16x32_bf16 v[16:19], v[158:161], v[182:185], v[16:19]
	v_mfma_f32_16x16x32_bf16 v[4:7], v[150:153], v[190:193], v[4:7]
	v_mfma_f32_16x16x32_bf16 v[0:3], v[158:161], v[190:193], v[0:3]
	s_barrier
	s_add_i32 s58, s58, 2
	s_add_u32 s28, s28, 0x100
	s_addc_u32 s29, s29, 0
	s_add_u32 s56, s56, 0x100
	s_addc_u32 s57, s57, 0
	s_cmp_gt_u32 s58, 13
	s_cbranch_scc0 .LBB0_433
	s_and_b64 vcc, exec, s[18:19]
	s_cbranch_vccnz .LBB0_438
	v_lshl_add_u32 v234, s10, 8, v221
	s_cmp_gt_i32 s8, 3
	s_mov_b64 s[28:29], -1
	s_cbranch_scc1 .LBB0_439

.LBB0_1025:
	s_ashr_i32 s23, s22, 31
	s_lshl_b64 s[24:25], s[22:23], 19
	s_add_u32 s24, s90, s24
	s_addc_u32 s25, s91, s25
	s_and_b64 s[26:27], s[6:7], exec
	s_cselect_b32 s23, s25, s35
	s_cselect_b32 s29, s24, s34
	s_ashr_i32 s21, s20, 31
	s_lshl_b64 s[26:27], s[20:21], 19
	s_add_u32 s26, s2, s26
	s_addc_u32 s27, s3, s27
	s_and_b64 s[38:39], s[6:7], exec
	s_cselect_b32 s21, s27, s37
	s_cselect_b32 s55, s26, s36
	s_add_u32 s34, s34, 0x40080
	s_addc_u32 s35, s35, 0
	s_add_u32 s56, s36, 0x100
	s_addc_u32 s57, s37, 0
	s_mov_b32 s58, -2
	s_waitcnt lgkmcnt(0)
	s_waitcnt vmcnt(0)
	v_xor_b32_e32 v246, 64, v189
	v_xor_b32_e32 v247, 64, v185
	v_add_u32_e32 v248, s53, v247
	v_add_u32_e32 v249, s54, v247
	ds_read_b128 v[128:131], v187
	ds_read_b128 v[132:135], v248
	ds_read_b128 v[152:155], v187 offset:2048
	ds_read_b128 v[156:159], v248 offset:2048
	ds_read_b128 v[160:163], v188
	ds_read_b128 v[164:167], v249
	ds_read_b128 v[168:171], v188 offset:2048
	ds_read_b128 v[172:175], v249 offset:2048
	s_add_u32 s36, s34, 0xfffc0080
	s_addc_u32 s37, s35, -1
	s_cmp_eq_u32 s58, 12
	s_cselect_b32 s39, s23, s37
	s_cselect_b32 s38, s29, s36
	s_cselect_b32 s37, s21, s57
	s_cselect_b32 s36, s55, s56
	v_lshl_add_u64 v[216:217], s[34:35], 0, v[144:145]
	s_add_i32 m0, s31, 0xc000
	ds_read_b128 v[176:179], v189
	ds_read_b128 v[180:183], v246
	ds_read_b128 v[192:195], v189 offset:2048
	ds_read_b128 v[196:199], v246 offset:2048
	ds_read_b128 v[200:203], v189 offset:4096
	ds_read_b128 v[204:207], v246 offset:4096
	ds_read_b128 v[208:211], v189 offset:6144
	ds_read_b128 v[212:215], v246 offset:6144
	global_load_lds_dwordx4 v[216:217], off
	v_lshl_add_u64 v[216:217], s[34:35], 0, v[146:147]
	s_add_i32 m0, s31, 0xe000
	s_nop 0
	global_load_lds_dwordx4 v[216:217], off
	s_waitcnt vmcnt(8)
	s_waitcnt lgkmcnt(0)
	s_barrier
	s_waitcnt lgkmcnt(0)
	v_mfma_f32_16x16x32_bf16 v[124:127], v[128:131], v[176:179], 0
	v_mfma_f32_16x16x32_bf16 v[120:123], v[152:155], v[176:179], 0
	v_mfma_f32_16x16x32_bf16 v[108:111], v[128:131], v[192:195], 0
	v_mfma_f32_16x16x32_bf16 v[104:107], v[152:155], v[192:195], 0
	v_mfma_f32_16x16x32_bf16 v[92:95], v[128:131], v[200:203], 0
	v_mfma_f32_16x16x32_bf16 v[88:91], v[152:155], v[200:203], 0
	v_mfma_f32_16x16x32_bf16 v[76:79], v[128:131], v[208:211], 0
	v_mfma_f32_16x16x32_bf16 v[72:75], v[152:155], v[208:211], 0
	v_mfma_f32_16x16x32_bf16 v[124:127], v[132:135], v[180:183], v[124:127]
	v_mfma_f32_16x16x32_bf16 v[120:123], v[156:159], v[180:183], v[120:123]
	v_mfma_f32_16x16x32_bf16 v[108:111], v[132:135], v[196:199], v[108:111]
	v_mfma_f32_16x16x32_bf16 v[104:107], v[156:159], v[196:199], v[104:107]
	v_mfma_f32_16x16x32_bf16 v[92:95], v[132:135], v[204:207], v[92:95]
	v_mfma_f32_16x16x32_bf16 v[88:91], v[156:159], v[204:207], v[88:91]
	v_mfma_f32_16x16x32_bf16 v[76:79], v[132:135], v[212:215], v[76:79]
	v_mfma_f32_16x16x32_bf16 v[72:75], v[156:159], v[212:215], v[72:75]
	v_mfma_f32_16x16x32_bf16 v[116:119], v[160:163], v[176:179], 0
	v_mfma_f32_16x16x32_bf16 v[112:115], v[168:171], v[176:179], 0
	v_mfma_f32_16x16x32_bf16 v[100:103], v[160:163], v[192:195], 0
	v_mfma_f32_16x16x32_bf16 v[96:99], v[168:171], v[192:195], 0
	v_mfma_f32_16x16x32_bf16 v[84:87], v[160:163], v[200:203], 0
	v_mfma_f32_16x16x32_bf16 v[80:83], v[168:171], v[200:203], 0
	v_mfma_f32_16x16x32_bf16 v[68:71], v[160:163], v[208:211], 0
	v_mfma_f32_16x16x32_bf16 v[64:67], v[168:171], v[208:211], 0
	v_mfma_f32_16x16x32_bf16 v[116:119], v[164:167], v[180:183], v[116:119]
	v_mfma_f32_16x16x32_bf16 v[112:115], v[172:175], v[180:183], v[112:115]
	v_mfma_f32_16x16x32_bf16 v[100:103], v[164:167], v[196:199], v[100:103]
	v_mfma_f32_16x16x32_bf16 v[96:99], v[172:175], v[196:199], v[96:99]
	v_mfma_f32_16x16x32_bf16 v[84:87], v[164:167], v[204:207], v[84:87]
	v_mfma_f32_16x16x32_bf16 v[80:83], v[172:175], v[204:207], v[80:83]
	v_mfma_f32_16x16x32_bf16 v[68:71], v[164:167], v[212:215], v[68:71]
	v_mfma_f32_16x16x32_bf16 v[64:67], v[172:175], v[212:215], v[64:67]
	s_barrier
	s_add_i32 s59, s53, s33
	v_lshl_add_u64 v[216:217], s[36:37], 0, v[138:139]
	s_mov_b32 m0, s59
	ds_read_b128 v[176:179], v189 offset:16384
	ds_read_b128 v[180:183], v246 offset:16384
	ds_read_b128 v[192:195], v189 offset:18432
	ds_read_b128 v[196:199], v246 offset:18432
	ds_read_b128 v[200:203], v189 offset:20480
	ds_read_b128 v[204:207], v246 offset:20480
	ds_read_b128 v[208:211], v189 offset:22528
	ds_read_b128 v[212:215], v246 offset:22528
	global_load_lds_dwordx4 v[216:217], off
	s_add_i32 m0, s59, 0x2000
	s_add_u32 s60, s36, 0x40000
	v_lshl_add_u64 v[218:219], s[36:37], 0, v[142:143]
	s_addc_u32 s61, s37, 0
	s_add_i32 s59, s54, s33
	global_load_lds_dwordx4 v[218:219], off
	v_lshl_add_u64 v[220:221], s[60:61], 0, v[138:139]
	s_mov_b32 m0, s59
	v_lshl_add_u64 v[222:223], s[38:39], 0, v[140:141]
	global_load_lds_dwordx4 v[220:221], off
	v_lshl_add_u64 v[220:221], s[60:61], 0, v[142:143]
	s_add_i32 m0, s59, 0x2000
	s_nop 0
	global_load_lds_dwordx4 v[220:221], off
	v_lshl_add_u64 v[220:221], s[38:39], 0, v[136:137]
	s_mov_b32 m0, s31
	s_nop 0
	global_load_lds_dwordx4 v[220:221], off
	s_mov_b32 m0, s40
	s_nop 0
	global_load_lds_dwordx4 v[222:223], off
	s_waitcnt vmcnt(8)
	s_waitcnt lgkmcnt(0)
	s_barrier
	s_waitcnt lgkmcnt(0)
	v_mfma_f32_16x16x32_bf16 v[60:63], v[128:131], v[176:179], 0
	v_mfma_f32_16x16x32_bf16 v[56:59], v[152:155], v[176:179], 0
	v_mfma_f32_16x16x32_bf16 v[44:47], v[128:131], v[192:195], 0
	v_mfma_f32_16x16x32_bf16 v[40:43], v[152:155], v[192:195], 0
	v_mfma_f32_16x16x32_bf16 v[28:31], v[128:131], v[200:203], 0
	v_mfma_f32_16x16x32_bf16 v[24:27], v[152:155], v[200:203], 0
	v_mfma_f32_16x16x32_bf16 v[12:15], v[128:131], v[208:211], 0
	v_mfma_f32_16x16x32_bf16 v[8:11], v[152:155], v[208:211], 0
	v_mfma_f32_16x16x32_bf16 v[60:63], v[132:135], v[180:183], v[60:63]
	v_mfma_f32_16x16x32_bf16 v[56:59], v[156:159], v[180:183], v[56:59]
	v_mfma_f32_16x16x32_bf16 v[44:47], v[132:135], v[196:199], v[44:47]
	v_mfma_f32_16x16x32_bf16 v[40:43], v[156:159], v[196:199], v[40:43]
	v_mfma_f32_16x16x32_bf16 v[28:31], v[132:135], v[204:207], v[28:31]
	v_mfma_f32_16x16x32_bf16 v[24:27], v[156:159], v[204:207], v[24:27]
	v_mfma_f32_16x16x32_bf16 v[12:15], v[132:135], v[212:215], v[12:15]
	v_mfma_f32_16x16x32_bf16 v[8:11], v[156:159], v[212:215], v[8:11]
	v_mfma_f32_16x16x32_bf16 v[52:55], v[160:163], v[176:179], 0
	v_mfma_f32_16x16x32_bf16 v[48:51], v[168:171], v[176:179], 0
	v_mfma_f32_16x16x32_bf16 v[36:39], v[160:163], v[192:195], 0
	v_mfma_f32_16x16x32_bf16 v[32:35], v[168:171], v[192:195], 0
	v_mfma_f32_16x16x32_bf16 v[20:23], v[160:163], v[200:203], 0
	v_mfma_f32_16x16x32_bf16 v[16:19], v[168:171], v[200:203], 0
	v_mfma_f32_16x16x32_bf16 v[4:7], v[160:163], v[208:211], 0
	v_mfma_f32_16x16x32_bf16 v[0:3], v[168:171], v[208:211], 0
	v_mfma_f32_16x16x32_bf16 v[52:55], v[164:167], v[180:183], v[52:55]
	v_mfma_f32_16x16x32_bf16 v[48:51], v[172:175], v[180:183], v[48:51]
	v_mfma_f32_16x16x32_bf16 v[36:39], v[164:167], v[196:199], v[36:39]
	v_mfma_f32_16x16x32_bf16 v[32:35], v[172:175], v[196:199], v[32:35]
	v_mfma_f32_16x16x32_bf16 v[20:23], v[164:167], v[204:207], v[20:23]
	v_mfma_f32_16x16x32_bf16 v[16:19], v[172:175], v[204:207], v[16:19]
	v_mfma_f32_16x16x32_bf16 v[4:7], v[164:167], v[212:215], v[4:7]
	v_mfma_f32_16x16x32_bf16 v[0:3], v[172:175], v[212:215], v[0:3]
	s_barrier
	s_add_i32 s59, 0, 0x18000
	s_add_i32 s60, 0, 0x1c000
	v_add_u32_e32 v156, s59, v185
	v_add_u32_e32 v250, s59, v247
	v_add_u32_e32 v172, s60, v185
	v_add_u32_e32 v251, s60, v247
	ds_read_b128 v[128:131], v156
	ds_read_b128 v[132:135], v250
	ds_read_b128 v[152:155], v156 offset:2048
	ds_read_b128 v[156:159], v250 offset:2048
	ds_read_b128 v[160:163], v172
	ds_read_b128 v[164:167], v251
	ds_read_b128 v[168:171], v172 offset:2048
	ds_read_b128 v[172:175], v251 offset:2048
	s_add_u32 s38, s38, 0x40000
	s_addc_u32 s39, s39, 0
	s_mov_b32 m0, s41
	v_lshl_add_u64 v[224:225], s[38:39], 0, v[136:137]
	ds_read_b128 v[176:179], v189 offset:32768
	ds_read_b128 v[180:183], v246 offset:32768
	ds_read_b128 v[192:195], v189 offset:34816
	ds_read_b128 v[196:199], v246 offset:34816
	ds_read_b128 v[200:203], v189 offset:36864
	ds_read_b128 v[204:207], v246 offset:36864
	ds_read_b128 v[208:211], v189 offset:38912
	ds_read_b128 v[212:215], v246 offset:38912
	global_load_lds_dwordx4 v[224:225], off
	v_lshl_add_u64 v[224:225], s[38:39], 0, v[140:141]
	s_mov_b32 m0, s42
	s_nop 0
	global_load_lds_dwordx4 v[224:225], off
	s_waitcnt vmcnt(8)
	s_waitcnt lgkmcnt(0)
	s_barrier
	s_waitcnt lgkmcnt(0)
	v_mfma_f32_16x16x32_bf16 v[124:127], v[128:131], v[176:179], v[124:127]
	v_mfma_f32_16x16x32_bf16 v[120:123], v[152:155], v[176:179], v[120:123]
	v_mfma_f32_16x16x32_bf16 v[108:111], v[128:131], v[192:195], v[108:111]
	v_mfma_f32_16x16x32_bf16 v[104:107], v[152:155], v[192:195], v[104:107]
	v_mfma_f32_16x16x32_bf16 v[92:95], v[128:131], v[200:203], v[92:95]
	v_mfma_f32_16x16x32_bf16 v[88:91], v[152:155], v[200:203], v[88:91]
	v_mfma_f32_16x16x32_bf16 v[76:79], v[128:131], v[208:211], v[76:79]
	v_mfma_f32_16x16x32_bf16 v[72:75], v[152:155], v[208:211], v[72:75]
	v_mfma_f32_16x16x32_bf16 v[124:127], v[132:135], v[180:183], v[124:127]
	v_mfma_f32_16x16x32_bf16 v[120:123], v[156:159], v[180:183], v[120:123]
	v_mfma_f32_16x16x32_bf16 v[108:111], v[132:135], v[196:199], v[108:111]
	v_mfma_f32_16x16x32_bf16 v[104:107], v[156:159], v[196:199], v[104:107]
	v_mfma_f32_16x16x32_bf16 v[92:95], v[132:135], v[204:207], v[92:95]
	v_mfma_f32_16x16x32_bf16 v[88:91], v[156:159], v[204:207], v[88:91]
	v_mfma_f32_16x16x32_bf16 v[76:79], v[132:135], v[212:215], v[76:79]
	v_mfma_f32_16x16x32_bf16 v[72:75], v[156:159], v[212:215], v[72:75]
	v_mfma_f32_16x16x32_bf16 v[116:119], v[160:163], v[176:179], v[116:119]
	v_mfma_f32_16x16x32_bf16 v[112:115], v[168:171], v[176:179], v[112:115]
	v_mfma_f32_16x16x32_bf16 v[100:103], v[160:163], v[192:195], v[100:103]
	v_mfma_f32_16x16x32_bf16 v[96:99], v[168:171], v[192:195], v[96:99]
	v_mfma_f32_16x16x32_bf16 v[84:87], v[160:163], v[200:203], v[84:87]
	v_mfma_f32_16x16x32_bf16 v[80:83], v[168:171], v[200:203], v[80:83]
	v_mfma_f32_16x16x32_bf16 v[68:71], v[160:163], v[208:211], v[68:71]
	v_mfma_f32_16x16x32_bf16 v[64:67], v[168:171], v[208:211], v[64:67]
	v_mfma_f32_16x16x32_bf16 v[116:119], v[164:167], v[180:183], v[116:119]
	v_mfma_f32_16x16x32_bf16 v[112:115], v[172:175], v[180:183], v[112:115]
	v_mfma_f32_16x16x32_bf16 v[100:103], v[164:167], v[196:199], v[100:103]
	v_mfma_f32_16x16x32_bf16 v[96:99], v[172:175], v[196:199], v[96:99]
	v_mfma_f32_16x16x32_bf16 v[84:87], v[164:167], v[204:207], v[84:87]
	v_mfma_f32_16x16x32_bf16 v[80:83], v[172:175], v[204:207], v[80:83]
	v_mfma_f32_16x16x32_bf16 v[68:71], v[164:167], v[212:215], v[68:71]
	v_mfma_f32_16x16x32_bf16 v[64:67], v[172:175], v[212:215], v[64:67]
	s_barrier
	s_add_i32 s38, s59, s33
	v_lshl_add_u64 v[216:217], v[216:217], 0, s[16:17]
	s_mov_b32 m0, s38
	ds_read_b128 v[176:179], v189 offset:49152
	ds_read_b128 v[180:183], v246 offset:49152
	ds_read_b128 v[192:195], v189 offset:51200
	ds_read_b128 v[196:199], v246 offset:51200
	ds_read_b128 v[200:203], v189 offset:53248
	ds_read_b128 v[204:207], v246 offset:53248
	ds_read_b128 v[208:211], v189 offset:55296
	ds_read_b128 v[212:215], v246 offset:55296
	global_load_lds_dwordx4 v[216:217], off
	s_add_i32 m0, s38, 0x2000
	s_add_u32 s36, s36, 0x40080
	v_lshl_add_u64 v[216:217], v[218:219], 0, s[16:17]
	s_addc_u32 s37, s37, 0
	s_add_i32 s38, s60, s33
	global_load_lds_dwordx4 v[216:217], off
	v_lshl_add_u64 v[216:217], s[36:37], 0, v[138:139]
	s_mov_b32 m0, s38
	s_nop 0
	global_load_lds_dwordx4 v[216:217], off
	v_lshl_add_u64 v[216:217], s[36:37], 0, v[142:143]
	s_add_i32 m0, s38, 0x2000
	s_nop 0
	global_load_lds_dwordx4 v[216:217], off
	v_lshl_add_u64 v[216:217], v[220:221], 0, s[16:17]
	s_mov_b32 m0, s48
	s_nop 0
	global_load_lds_dwordx4 v[216:217], off
	v_lshl_add_u64 v[216:217], v[222:223], 0, s[16:17]
	s_mov_b32 m0, s49
	s_nop 0
	global_load_lds_dwordx4 v[216:217], off
	s_waitcnt vmcnt(8)
	s_waitcnt lgkmcnt(0)
	s_barrier
	s_waitcnt lgkmcnt(0)
	v_mfma_f32_16x16x32_bf16 v[60:63], v[128:131], v[176:179], v[60:63]
	v_mfma_f32_16x16x32_bf16 v[56:59], v[152:155], v[176:179], v[56:59]
	v_mfma_f32_16x16x32_bf16 v[44:47], v[128:131], v[192:195], v[44:47]
	v_mfma_f32_16x16x32_bf16 v[40:43], v[152:155], v[192:195], v[40:43]
	v_mfma_f32_16x16x32_bf16 v[28:31], v[128:131], v[200:203], v[28:31]
	v_mfma_f32_16x16x32_bf16 v[24:27], v[152:155], v[200:203], v[24:27]
	v_mfma_f32_16x16x32_bf16 v[12:15], v[128:131], v[208:211], v[12:15]
	v_mfma_f32_16x16x32_bf16 v[8:11], v[152:155], v[208:211], v[8:11]
	v_mfma_f32_16x16x32_bf16 v[60:63], v[132:135], v[180:183], v[60:63]
	v_mfma_f32_16x16x32_bf16 v[56:59], v[156:159], v[180:183], v[56:59]
	v_mfma_f32_16x16x32_bf16 v[44:47], v[132:135], v[196:199], v[44:47]
	v_mfma_f32_16x16x32_bf16 v[40:43], v[156:159], v[196:199], v[40:43]
	v_mfma_f32_16x16x32_bf16 v[28:31], v[132:135], v[204:207], v[28:31]
	v_mfma_f32_16x16x32_bf16 v[24:27], v[156:159], v[204:207], v[24:27]
	v_mfma_f32_16x16x32_bf16 v[12:15], v[132:135], v[212:215], v[12:15]
	v_mfma_f32_16x16x32_bf16 v[8:11], v[156:159], v[212:215], v[8:11]
	v_mfma_f32_16x16x32_bf16 v[52:55], v[160:163], v[176:179], v[52:55]
	v_mfma_f32_16x16x32_bf16 v[48:51], v[168:171], v[176:179], v[48:51]
	v_mfma_f32_16x16x32_bf16 v[36:39], v[160:163], v[192:195], v[36:39]
	v_mfma_f32_16x16x32_bf16 v[32:35], v[168:171], v[192:195], v[32:35]
	v_mfma_f32_16x16x32_bf16 v[20:23], v[160:163], v[200:203], v[20:23]
	v_mfma_f32_16x16x32_bf16 v[16:19], v[168:171], v[200:203], v[16:19]
	v_mfma_f32_16x16x32_bf16 v[4:7], v[160:163], v[208:211], v[4:7]
	v_mfma_f32_16x16x32_bf16 v[0:3], v[168:171], v[208:211], v[0:3]
	v_mfma_f32_16x16x32_bf16 v[52:55], v[164:167], v[180:183], v[52:55]
	v_mfma_f32_16x16x32_bf16 v[48:51], v[172:175], v[180:183], v[48:51]
	v_mfma_f32_16x16x32_bf16 v[36:39], v[164:167], v[196:199], v[36:39]
	v_mfma_f32_16x16x32_bf16 v[32:35], v[172:175], v[196:199], v[32:35]
	v_mfma_f32_16x16x32_bf16 v[20:23], v[164:167], v[204:207], v[20:23]
	v_mfma_f32_16x16x32_bf16 v[16:19], v[172:175], v[204:207], v[16:19]
	v_mfma_f32_16x16x32_bf16 v[4:7], v[164:167], v[212:215], v[4:7]
	v_mfma_f32_16x16x32_bf16 v[0:3], v[172:175], v[212:215], v[0:3]
	s_barrier
	s_add_i32 s58, s58, 2
	s_add_u32 s34, s34, 0x100
	s_addc_u32 s35, s35, 0
	s_add_u32 s56, s56, 0x100
	s_addc_u32 s57, s57, 0
	s_cmp_gt_u32 s58, 13
.LBB0_1026:
	ds_read_b128 v[128:131], v187
	ds_read_b128 v[132:135], v248
	ds_read_b128 v[152:155], v187 offset:2048
	ds_read_b128 v[156:159], v248 offset:2048
	ds_read_b128 v[160:163], v188
	ds_read_b128 v[164:167], v249
	ds_read_b128 v[168:171], v188 offset:2048
	ds_read_b128 v[172:175], v249 offset:2048
	s_add_u32 s36, s34, 0xfffc0080
	s_addc_u32 s37, s35, -1
	s_cmp_eq_u32 s58, 12
	s_cselect_b32 s39, s23, s37
	s_cselect_b32 s38, s29, s36
	s_cselect_b32 s37, s21, s57
	s_cselect_b32 s36, s55, s56
	v_lshl_add_u64 v[216:217], s[34:35], 0, v[144:145]
	s_add_i32 m0, s31, 0xc000
	ds_read_b128 v[176:179], v189
	ds_read_b128 v[180:183], v246
	ds_read_b128 v[192:195], v189 offset:2048
	ds_read_b128 v[196:199], v246 offset:2048
	ds_read_b128 v[200:203], v189 offset:4096
	ds_read_b128 v[204:207], v246 offset:4096
	ds_read_b128 v[208:211], v189 offset:6144
	ds_read_b128 v[212:215], v246 offset:6144
	global_load_lds_dwordx4 v[216:217], off
	v_lshl_add_u64 v[216:217], s[34:35], 0, v[146:147]
	s_add_i32 m0, s31, 0xe000
	s_nop 0
	global_load_lds_dwordx4 v[216:217], off
	s_waitcnt vmcnt(8)
	s_waitcnt lgkmcnt(0)
	s_barrier
	s_waitcnt lgkmcnt(0)
	v_mfma_f32_16x16x32_bf16 v[124:127], v[128:131], v[176:179], v[124:127]
	v_mfma_f32_16x16x32_bf16 v[120:123], v[152:155], v[176:179], v[120:123]
	v_mfma_f32_16x16x32_bf16 v[108:111], v[128:131], v[192:195], v[108:111]
	v_mfma_f32_16x16x32_bf16 v[104:107], v[152:155], v[192:195], v[104:107]
	v_mfma_f32_16x16x32_bf16 v[92:95], v[128:131], v[200:203], v[92:95]
	v_mfma_f32_16x16x32_bf16 v[88:91], v[152:155], v[200:203], v[88:91]
	v_mfma_f32_16x16x32_bf16 v[76:79], v[128:131], v[208:211], v[76:79]
	v_mfma_f32_16x16x32_bf16 v[72:75], v[152:155], v[208:211], v[72:75]
	v_mfma_f32_16x16x32_bf16 v[124:127], v[132:135], v[180:183], v[124:127]
	v_mfma_f32_16x16x32_bf16 v[120:123], v[156:159], v[180:183], v[120:123]
	v_mfma_f32_16x16x32_bf16 v[108:111], v[132:135], v[196:199], v[108:111]
	v_mfma_f32_16x16x32_bf16 v[104:107], v[156:159], v[196:199], v[104:107]
	v_mfma_f32_16x16x32_bf16 v[92:95], v[132:135], v[204:207], v[92:95]
	v_mfma_f32_16x16x32_bf16 v[88:91], v[156:159], v[204:207], v[88:91]
	v_mfma_f32_16x16x32_bf16 v[76:79], v[132:135], v[212:215], v[76:79]
	v_mfma_f32_16x16x32_bf16 v[72:75], v[156:159], v[212:215], v[72:75]
	v_mfma_f32_16x16x32_bf16 v[116:119], v[160:163], v[176:179], v[116:119]
	v_mfma_f32_16x16x32_bf16 v[112:115], v[168:171], v[176:179], v[112:115]
	v_mfma_f32_16x16x32_bf16 v[100:103], v[160:163], v[192:195], v[100:103]
	v_mfma_f32_16x16x32_bf16 v[96:99], v[168:171], v[192:195], v[96:99]
	v_mfma_f32_16x16x32_bf16 v[84:87], v[160:163], v[200:203], v[84:87]
	v_mfma_f32_16x16x32_bf16 v[80:83], v[168:171], v[200:203], v[80:83]
	v_mfma_f32_16x16x32_bf16 v[68:71], v[160:163], v[208:211], v[68:71]
	v_mfma_f32_16x16x32_bf16 v[64:67], v[168:171], v[208:211], v[64:67]
	v_mfma_f32_16x16x32_bf16 v[116:119], v[164:167], v[180:183], v[116:119]
	v_mfma_f32_16x16x32_bf16 v[112:115], v[172:175], v[180:183], v[112:115]
	v_mfma_f32_16x16x32_bf16 v[100:103], v[164:167], v[196:199], v[100:103]
	v_mfma_f32_16x16x32_bf16 v[96:99], v[172:175], v[196:199], v[96:99]
	v_mfma_f32_16x16x32_bf16 v[84:87], v[164:167], v[204:207], v[84:87]
	v_mfma_f32_16x16x32_bf16 v[80:83], v[172:175], v[204:207], v[80:83]
	v_mfma_f32_16x16x32_bf16 v[68:71], v[164:167], v[212:215], v[68:71]
	v_mfma_f32_16x16x32_bf16 v[64:67], v[172:175], v[212:215], v[64:67]
	s_barrier
	s_add_i32 s59, s53, s33
	v_lshl_add_u64 v[216:217], s[36:37], 0, v[138:139]
	s_mov_b32 m0, s59
	ds_read_b128 v[176:179], v189 offset:16384
	ds_read_b128 v[180:183], v246 offset:16384
	ds_read_b128 v[192:195], v189 offset:18432
	ds_read_b128 v[196:199], v246 offset:18432
	ds_read_b128 v[200:203], v189 offset:20480
	ds_read_b128 v[204:207], v246 offset:20480
	ds_read_b128 v[208:211], v189 offset:22528
	ds_read_b128 v[212:215], v246 offset:22528
	global_load_lds_dwordx4 v[216:217], off
	s_add_i32 m0, s59, 0x2000
	s_add_u32 s60, s36, 0x40000
	v_lshl_add_u64 v[218:219], s[36:37], 0, v[142:143]
	s_addc_u32 s61, s37, 0
	s_add_i32 s59, s54, s33
	global_load_lds_dwordx4 v[218:219], off
	v_lshl_add_u64 v[220:221], s[60:61], 0, v[138:139]
	s_mov_b32 m0, s59
	v_lshl_add_u64 v[222:223], s[38:39], 0, v[140:141]
	global_load_lds_dwordx4 v[220:221], off
	v_lshl_add_u64 v[220:221], s[60:61], 0, v[142:143]
	s_add_i32 m0, s59, 0x2000
	s_nop 0
	global_load_lds_dwordx4 v[220:221], off
	v_lshl_add_u64 v[220:221], s[38:39], 0, v[136:137]
	s_mov_b32 m0, s31
	s_nop 0
	global_load_lds_dwordx4 v[220:221], off
	s_mov_b32 m0, s40
	s_nop 0
	global_load_lds_dwordx4 v[222:223], off
	s_waitcnt vmcnt(8)
	s_waitcnt lgkmcnt(0)
	s_barrier
	s_waitcnt lgkmcnt(0)
	v_mfma_f32_16x16x32_bf16 v[60:63], v[128:131], v[176:179], v[60:63]
	v_mfma_f32_16x16x32_bf16 v[56:59], v[152:155], v[176:179], v[56:59]
	v_mfma_f32_16x16x32_bf16 v[44:47], v[128:131], v[192:195], v[44:47]
	v_mfma_f32_16x16x32_bf16 v[40:43], v[152:155], v[192:195], v[40:43]
	v_mfma_f32_16x16x32_bf16 v[28:31], v[128:131], v[200:203], v[28:31]
	v_mfma_f32_16x16x32_bf16 v[24:27], v[152:155], v[200:203], v[24:27]
	v_mfma_f32_16x16x32_bf16 v[12:15], v[128:131], v[208:211], v[12:15]
	v_mfma_f32_16x16x32_bf16 v[8:11], v[152:155], v[208:211], v[8:11]
	v_mfma_f32_16x16x32_bf16 v[60:63], v[132:135], v[180:183], v[60:63]
	v_mfma_f32_16x16x32_bf16 v[56:59], v[156:159], v[180:183], v[56:59]
	v_mfma_f32_16x16x32_bf16 v[44:47], v[132:135], v[196:199], v[44:47]
	v_mfma_f32_16x16x32_bf16 v[40:43], v[156:159], v[196:199], v[40:43]
	v_mfma_f32_16x16x32_bf16 v[28:31], v[132:135], v[204:207], v[28:31]
	v_mfma_f32_16x16x32_bf16 v[24:27], v[156:159], v[204:207], v[24:27]
	v_mfma_f32_16x16x32_bf16 v[12:15], v[132:135], v[212:215], v[12:15]
	v_mfma_f32_16x16x32_bf16 v[8:11], v[156:159], v[212:215], v[8:11]
	v_mfma_f32_16x16x32_bf16 v[52:55], v[160:163], v[176:179], v[52:55]
	v_mfma_f32_16x16x32_bf16 v[48:51], v[168:171], v[176:179], v[48:51]
	v_mfma_f32_16x16x32_bf16 v[36:39], v[160:163], v[192:195], v[36:39]
	v_mfma_f32_16x16x32_bf16 v[32:35], v[168:171], v[192:195], v[32:35]
	v_mfma_f32_16x16x32_bf16 v[20:23], v[160:163], v[200:203], v[20:23]
	v_mfma_f32_16x16x32_bf16 v[16:19], v[168:171], v[200:203], v[16:19]
	v_mfma_f32_16x16x32_bf16 v[4:7], v[160:163], v[208:211], v[4:7]
	v_mfma_f32_16x16x32_bf16 v[0:3], v[168:171], v[208:211], v[0:3]
	v_mfma_f32_16x16x32_bf16 v[52:55], v[164:167], v[180:183], v[52:55]
	v_mfma_f32_16x16x32_bf16 v[48:51], v[172:175], v[180:183], v[48:51]
	v_mfma_f32_16x16x32_bf16 v[36:39], v[164:167], v[196:199], v[36:39]
	v_mfma_f32_16x16x32_bf16 v[32:35], v[172:175], v[196:199], v[32:35]
	v_mfma_f32_16x16x32_bf16 v[20:23], v[164:167], v[204:207], v[20:23]
	v_mfma_f32_16x16x32_bf16 v[16:19], v[172:175], v[204:207], v[16:19]
	v_mfma_f32_16x16x32_bf16 v[4:7], v[164:167], v[212:215], v[4:7]
	v_mfma_f32_16x16x32_bf16 v[0:3], v[172:175], v[212:215], v[0:3]
	s_barrier
	s_add_i32 s59, 0, 0x18000
	s_add_i32 s60, 0, 0x1c000
	v_add_u32_e32 v156, s59, v185
	v_add_u32_e32 v250, s59, v247
	v_add_u32_e32 v172, s60, v185
	v_add_u32_e32 v251, s60, v247
	ds_read_b128 v[128:131], v156
	ds_read_b128 v[132:135], v250
	ds_read_b128 v[152:155], v156 offset:2048
	ds_read_b128 v[156:159], v250 offset:2048
	ds_read_b128 v[160:163], v172
	ds_read_b128 v[164:167], v251
	ds_read_b128 v[168:171], v172 offset:2048
	ds_read_b128 v[172:175], v251 offset:2048
	s_add_u32 s38, s38, 0x40000
	s_addc_u32 s39, s39, 0
	s_mov_b32 m0, s41
	v_lshl_add_u64 v[224:225], s[38:39], 0, v[136:137]
	ds_read_b128 v[176:179], v189 offset:32768
	ds_read_b128 v[180:183], v246 offset:32768
	ds_read_b128 v[192:195], v189 offset:34816
	ds_read_b128 v[196:199], v246 offset:34816
	ds_read_b128 v[200:203], v189 offset:36864
	ds_read_b128 v[204:207], v246 offset:36864
	ds_read_b128 v[208:211], v189 offset:38912
	ds_read_b128 v[212:215], v246 offset:38912
	global_load_lds_dwordx4 v[224:225], off
	v_lshl_add_u64 v[224:225], s[38:39], 0, v[140:141]
	s_mov_b32 m0, s42
	s_nop 0
	global_load_lds_dwordx4 v[224:225], off
	s_waitcnt vmcnt(8)
	s_waitcnt lgkmcnt(0)
	s_barrier
	s_waitcnt lgkmcnt(0)
	v_mfma_f32_16x16x32_bf16 v[124:127], v[128:131], v[176:179], v[124:127]
	v_mfma_f32_16x16x32_bf16 v[120:123], v[152:155], v[176:179], v[120:123]
	v_mfma_f32_16x16x32_bf16 v[108:111], v[128:131], v[192:195], v[108:111]
	v_mfma_f32_16x16x32_bf16 v[104:107], v[152:155], v[192:195], v[104:107]
	v_mfma_f32_16x16x32_bf16 v[92:95], v[128:131], v[200:203], v[92:95]
	v_mfma_f32_16x16x32_bf16 v[88:91], v[152:155], v[200:203], v[88:91]
	v_mfma_f32_16x16x32_bf16 v[76:79], v[128:131], v[208:211], v[76:79]
	v_mfma_f32_16x16x32_bf16 v[72:75], v[152:155], v[208:211], v[72:75]
	v_mfma_f32_16x16x32_bf16 v[124:127], v[132:135], v[180:183], v[124:127]
	v_mfma_f32_16x16x32_bf16 v[120:123], v[156:159], v[180:183], v[120:123]
	v_mfma_f32_16x16x32_bf16 v[108:111], v[132:135], v[196:199], v[108:111]
	v_mfma_f32_16x16x32_bf16 v[104:107], v[156:159], v[196:199], v[104:107]
	v_mfma_f32_16x16x32_bf16 v[92:95], v[132:135], v[204:207], v[92:95]
	v_mfma_f32_16x16x32_bf16 v[88:91], v[156:159], v[204:207], v[88:91]
	v_mfma_f32_16x16x32_bf16 v[76:79], v[132:135], v[212:215], v[76:79]
	v_mfma_f32_16x16x32_bf16 v[72:75], v[156:159], v[212:215], v[72:75]
	v_mfma_f32_16x16x32_bf16 v[116:119], v[160:163], v[176:179], v[116:119]
	v_mfma_f32_16x16x32_bf16 v[112:115], v[168:171], v[176:179], v[112:115]
	v_mfma_f32_16x16x32_bf16 v[100:103], v[160:163], v[192:195], v[100:103]
	v_mfma_f32_16x16x32_bf16 v[96:99], v[168:171], v[192:195], v[96:99]
	v_mfma_f32_16x16x32_bf16 v[84:87], v[160:163], v[200:203], v[84:87]
	v_mfma_f32_16x16x32_bf16 v[80:83], v[168:171], v[200:203], v[80:83]
	v_mfma_f32_16x16x32_bf16 v[68:71], v[160:163], v[208:211], v[68:71]
	v_mfma_f32_16x16x32_bf16 v[64:67], v[168:171], v[208:211], v[64:67]
	v_mfma_f32_16x16x32_bf16 v[116:119], v[164:167], v[180:183], v[116:119]
	v_mfma_f32_16x16x32_bf16 v[112:115], v[172:175], v[180:183], v[112:115]
	v_mfma_f32_16x16x32_bf16 v[100:103], v[164:167], v[196:199], v[100:103]
	v_mfma_f32_16x16x32_bf16 v[96:99], v[172:175], v[196:199], v[96:99]
	v_mfma_f32_16x16x32_bf16 v[84:87], v[164:167], v[204:207], v[84:87]
	v_mfma_f32_16x16x32_bf16 v[80:83], v[172:175], v[204:207], v[80:83]
	v_mfma_f32_16x16x32_bf16 v[68:71], v[164:167], v[212:215], v[68:71]
	v_mfma_f32_16x16x32_bf16 v[64:67], v[172:175], v[212:215], v[64:67]
	s_barrier
	s_add_i32 s38, s59, s33
	v_lshl_add_u64 v[216:217], v[216:217], 0, s[16:17]
	s_mov_b32 m0, s38
	ds_read_b128 v[176:179], v189 offset:49152
	ds_read_b128 v[180:183], v246 offset:49152
	ds_read_b128 v[192:195], v189 offset:51200
	ds_read_b128 v[196:199], v246 offset:51200
	ds_read_b128 v[200:203], v189 offset:53248
	ds_read_b128 v[204:207], v246 offset:53248
	ds_read_b128 v[208:211], v189 offset:55296
	ds_read_b128 v[212:215], v246 offset:55296
	global_load_lds_dwordx4 v[216:217], off
	s_add_i32 m0, s38, 0x2000
	s_add_u32 s36, s36, 0x40080
	v_lshl_add_u64 v[216:217], v[218:219], 0, s[16:17]
	s_addc_u32 s37, s37, 0
	s_add_i32 s38, s60, s33
	global_load_lds_dwordx4 v[216:217], off
	v_lshl_add_u64 v[216:217], s[36:37], 0, v[138:139]
	s_mov_b32 m0, s38
	s_nop 0
	global_load_lds_dwordx4 v[216:217], off
	v_lshl_add_u64 v[216:217], s[36:37], 0, v[142:143]
	s_add_i32 m0, s38, 0x2000
	s_nop 0
	global_load_lds_dwordx4 v[216:217], off
	v_lshl_add_u64 v[216:217], v[220:221], 0, s[16:17]
	s_mov_b32 m0, s48
	s_nop 0
	global_load_lds_dwordx4 v[216:217], off
	v_lshl_add_u64 v[216:217], v[222:223], 0, s[16:17]
	s_mov_b32 m0, s49
	s_nop 0
	global_load_lds_dwordx4 v[216:217], off
	s_waitcnt vmcnt(8)
	s_waitcnt lgkmcnt(0)
	s_barrier
	s_waitcnt lgkmcnt(0)
	v_mfma_f32_16x16x32_bf16 v[60:63], v[128:131], v[176:179], v[60:63]
	v_mfma_f32_16x16x32_bf16 v[56:59], v[152:155], v[176:179], v[56:59]
	v_mfma_f32_16x16x32_bf16 v[44:47], v[128:131], v[192:195], v[44:47]
	v_mfma_f32_16x16x32_bf16 v[40:43], v[152:155], v[192:195], v[40:43]
	v_mfma_f32_16x16x32_bf16 v[28:31], v[128:131], v[200:203], v[28:31]
	v_mfma_f32_16x16x32_bf16 v[24:27], v[152:155], v[200:203], v[24:27]
	v_mfma_f32_16x16x32_bf16 v[12:15], v[128:131], v[208:211], v[12:15]
	v_mfma_f32_16x16x32_bf16 v[8:11], v[152:155], v[208:211], v[8:11]
	v_mfma_f32_16x16x32_bf16 v[60:63], v[132:135], v[180:183], v[60:63]
	v_mfma_f32_16x16x32_bf16 v[56:59], v[156:159], v[180:183], v[56:59]
	v_mfma_f32_16x16x32_bf16 v[44:47], v[132:135], v[196:199], v[44:47]
	v_mfma_f32_16x16x32_bf16 v[40:43], v[156:159], v[196:199], v[40:43]
	v_mfma_f32_16x16x32_bf16 v[28:31], v[132:135], v[204:207], v[28:31]
	v_mfma_f32_16x16x32_bf16 v[24:27], v[156:159], v[204:207], v[24:27]
	v_mfma_f32_16x16x32_bf16 v[12:15], v[132:135], v[212:215], v[12:15]
	v_mfma_f32_16x16x32_bf16 v[8:11], v[156:159], v[212:215], v[8:11]
	v_mfma_f32_16x16x32_bf16 v[52:55], v[160:163], v[176:179], v[52:55]
	v_mfma_f32_16x16x32_bf16 v[48:51], v[168:171], v[176:179], v[48:51]
	v_mfma_f32_16x16x32_bf16 v[36:39], v[160:163], v[192:195], v[36:39]
	v_mfma_f32_16x16x32_bf16 v[32:35], v[168:171], v[192:195], v[32:35]
	v_mfma_f32_16x16x32_bf16 v[20:23], v[160:163], v[200:203], v[20:23]
	v_mfma_f32_16x16x32_bf16 v[16:19], v[168:171], v[200:203], v[16:19]
	v_mfma_f32_16x16x32_bf16 v[4:7], v[160:163], v[208:211], v[4:7]
	v_mfma_f32_16x16x32_bf16 v[0:3], v[168:171], v[208:211], v[0:3]
	v_mfma_f32_16x16x32_bf16 v[52:55], v[164:167], v[180:183], v[52:55]
	v_mfma_f32_16x16x32_bf16 v[48:51], v[172:175], v[180:183], v[48:51]
	v_mfma_f32_16x16x32_bf16 v[36:39], v[164:167], v[196:199], v[36:39]
	v_mfma_f32_16x16x32_bf16 v[32:35], v[172:175], v[196:199], v[32:35]
	v_mfma_f32_16x16x32_bf16 v[20:23], v[164:167], v[204:207], v[20:23]
	v_mfma_f32_16x16x32_bf16 v[16:19], v[172:175], v[204:207], v[16:19]
	v_mfma_f32_16x16x32_bf16 v[4:7], v[164:167], v[212:215], v[4:7]
	v_mfma_f32_16x16x32_bf16 v[0:3], v[172:175], v[212:215], v[0:3]
	s_barrier
	s_add_i32 s58, s58, 2
	s_add_u32 s34, s34, 0x100
	s_addc_u32 s35, s35, 0
	s_add_u32 s56, s56, 0x100
	s_addc_u32 s57, s57, 0
	s_cmp_gt_u32 s58, 13
	s_cbranch_scc0 .LBB0_1026
	s_and_b64 vcc, exec, s[18:19]
	s_cbranch_vccz .LBB0_1029
	s_barrier

.LBB0_1110:
	s_add_u32 s24, s24, 0x40080
	s_addc_u32 s25, s25, 0
	s_add_u32 s53, s26, 0x100
	s_addc_u32 s54, s27, 0
	s_mov_b32 s55, -2
	s_waitcnt vmcnt(0)
	v_xor_b32_e32 v246, 64, v179
	v_xor_b32_e32 v247, 64, v167
	v_add_u32_e32 v248, s46, v247
	v_add_u32_e32 v249, s47, v247
	ds_read_b128 v[124:127], v171
	ds_read_b128 v[132:135], v248
	ds_read_b128 v[136:139], v171 offset:2048
	ds_read_b128 v[140:143], v248 offset:2048
	ds_read_b128 v[162:165], v175
	ds_read_b128 v[182:185], v249
	ds_read_b128 v[186:189], v175 offset:2048
	ds_read_b128 v[190:193], v249 offset:2048
	s_add_u32 s26, s24, 0xfffc0080
	s_addc_u32 s27, s25, -1
	s_cmp_eq_u32 s55, 12
	s_cselect_b32 s29, s17, s27
	s_cselect_b32 s28, s51, s26
	s_cselect_b32 s27, s15, s54
	s_cselect_b32 s26, s52, s53
	v_lshl_add_u64 v[172:173], s[24:25], 0, v[152:153]
	s_add_i32 m0, s23, 0xc000
	ds_read_b128 v[194:197], v179
	ds_read_b128 v[198:201], v246
	ds_read_b128 v[202:205], v179 offset:2048
	ds_read_b128 v[206:209], v246 offset:2048
	ds_read_b128 v[210:213], v179 offset:4096
	ds_read_b128 v[214:217], v246 offset:4096
	ds_read_b128 v[218:221], v179 offset:6144
	ds_read_b128 v[222:225], v246 offset:6144
	global_load_lds_dwordx4 v[172:173], off
	v_lshl_add_u64 v[172:173], s[24:25], 0, v[154:155]
	s_add_i32 m0, s23, 0xe000
	s_nop 0
	global_load_lds_dwordx4 v[172:173], off
	s_waitcnt vmcnt(8)
	s_waitcnt lgkmcnt(0)
	s_barrier
	s_waitcnt lgkmcnt(0)
	v_mfma_f32_16x16x32_bf16 v[128:131], v[124:127], v[194:197], 0
	s_add_i32 s39, s39, 1
	s_mul_i32 s0, s39, s42
	s_mul_hi_u32 s1, s39, s45
	v_mfma_f32_16x16x32_bf16 v[120:123], v[136:139], v[194:197], 0
	s_add_i32 s1, s1, s0
	s_mul_i32 s0, s39, s45
	s_add_u32 s18, s0, s96
	v_mfma_f32_16x16x32_bf16 v[108:111], v[124:127], v[202:205], 0
	s_addc_u32 s19, s1, s34
	v_cmp_lt_i64_e64 s[0:1], s[18:19], v[156:157]
	s_ashr_i32 s14, s18, 31
	v_mfma_f32_16x16x32_bf16 v[104:107], v[136:139], v[202:205], 0
	s_lshr_b32 s14, s14, 29
	s_add_i32 s14, s18, s14
	s_ashr_i32 s15, s14, 3
	v_mfma_f32_16x16x32_bf16 v[92:95], v[124:127], v[210:213], 0
	s_and_b32 s14, s14, -8
	s_sub_i32 s14, s18, s14
	s_cmp_lt_i32 s14, 0
	v_mfma_f32_16x16x32_bf16 v[88:91], v[136:139], v[210:213], 0
	s_cselect_b32 s16, s35, 0x160
	s_mul_i32 s14, s14, s16
	s_add_i32 s14, s14, s15
	v_mfma_f32_16x16x32_bf16 v[76:79], v[124:127], v[218:221], 0
	s_mul_hi_i32 s15, s14, 0x2e8ba2e9
	s_lshr_b32 s16, s15, 31
	s_ashr_i32 s15, s15, 5
	v_mfma_f32_16x16x32_bf16 v[72:75], v[136:139], v[218:221], 0
	s_add_i32 s15, s15, s16
	s_lshl_b32 s16, s15, 3
	s_sub_i32 s17, 0x80, s16
	v_mfma_f32_16x16x32_bf16 v[128:131], v[132:135], v[198:201], v[128:131]
	s_min_i32 s17, s17, 8
	s_abs_i32 s18, s17
	v_cvt_f32_u32_e32 v252, s18
	v_mfma_f32_16x16x32_bf16 v[120:123], v[140:143], v[198:201], v[120:123]
	s_sub_i32 s20, 0, s18
	s_mulk_i32 s15, 0xb0
	s_sub_i32 s15, s14, s15
	v_mfma_f32_16x16x32_bf16 v[108:111], v[132:135], v[206:209], v[108:111]
	v_rcp_iflag_f32_e32 v252, v252
	s_abs_i32 s14, s15
	s_xor_b32 s19, s15, s17
	v_mfma_f32_16x16x32_bf16 v[104:107], v[140:143], v[206:209], v[104:107]
	s_ashr_i32 s19, s19, 31
	v_mul_f32_e32 v252, 0x4f7ffffe, v252
	v_cvt_u32_f32_e32 v252, v252
	v_mfma_f32_16x16x32_bf16 v[92:95], v[132:135], v[214:217], v[92:95]
	s_nop 0
	v_readfirstlane_b32 s21, v252
	s_mul_i32 s20, s20, s21
	v_mfma_f32_16x16x32_bf16 v[88:91], v[140:143], v[214:217], v[88:91]
	s_mul_hi_u32 s20, s21, s20
	s_add_i32 s21, s21, s20
	s_mul_hi_u32 s20, s14, s21
	v_mfma_f32_16x16x32_bf16 v[76:79], v[132:135], v[222:225], v[76:79]
	s_mul_i32 s21, s20, s18
	s_sub_i32 s14, s14, s21
	s_add_i32 s98, s20, 1
	v_mfma_f32_16x16x32_bf16 v[72:75], v[140:143], v[222:225], v[72:75]
	s_sub_i32 s21, s14, s18
	s_cmp_ge_u32 s14, s18
	s_cselect_b32 s20, s98, s20
	v_mfma_f32_16x16x32_bf16 v[116:119], v[162:165], v[194:197], 0
	s_cselect_b32 s14, s21, s14
	s_add_i32 s21, s20, 1
	s_cmp_ge_u32 s14, s18
	v_mfma_f32_16x16x32_bf16 v[112:115], v[186:189], v[194:197], 0
	s_cselect_b32 s14, s21, s20
	s_xor_b32 s14, s14, s19
	s_sub_i32 s14, s14, s19
	v_mfma_f32_16x16x32_bf16 v[100:103], v[162:165], v[202:205], 0
	s_mul_i32 s17, s14, s17
	s_sub_i32 s15, s15, s17
	s_add_i32 s16, s16, s15
	v_mfma_f32_16x16x32_bf16 v[96:99], v[186:189], v[202:205], 0
	s_ashr_i32 s17, s16, 31
	s_lshl_b64 s[18:19], s[16:17], 19
	s_add_u32 s18, s2, s18
	v_mfma_f32_16x16x32_bf16 v[84:87], v[162:165], v[210:213], 0
	s_addc_u32 s19, s3, s19
	s_and_b64 s[20:21], s[0:1], exec
	s_cselect_b32 s17, s19, s25
	v_mfma_f32_16x16x32_bf16 v[80:83], v[186:189], v[210:213], 0
	s_cselect_b32 s51, s18, s24
	s_ashr_i32 s15, s14, 31
	s_lshl_b64 s[20:21], s[14:15], 19
	v_mfma_f32_16x16x32_bf16 v[68:71], v[162:165], v[218:221], 0
	s_add_u32 s20, s30, s20
	s_addc_u32 s21, s31, s21
	s_and_b64 s[98:99], s[0:1], exec
	v_mfma_f32_16x16x32_bf16 v[64:67], v[186:189], v[218:221], 0
	s_cselect_b32 s15, s21, s27
	s_cselect_b32 s52, s20, s26
	v_mfma_f32_16x16x32_bf16 v[116:119], v[182:185], v[198:201], v[116:119]
	v_mfma_f32_16x16x32_bf16 v[112:115], v[190:193], v[198:201], v[112:115]
	v_mfma_f32_16x16x32_bf16 v[100:103], v[182:185], v[206:209], v[100:103]
	v_mfma_f32_16x16x32_bf16 v[96:99], v[190:193], v[206:209], v[96:99]
	v_mfma_f32_16x16x32_bf16 v[84:87], v[182:185], v[214:217], v[84:87]
	v_mfma_f32_16x16x32_bf16 v[80:83], v[190:193], v[214:217], v[80:83]
	v_mfma_f32_16x16x32_bf16 v[68:71], v[182:185], v[222:225], v[68:71]
	v_mfma_f32_16x16x32_bf16 v[64:67], v[190:193], v[222:225], v[64:67]
	s_barrier
	s_add_i32 s56, s46, s33
	v_lshl_add_u64 v[172:173], s[26:27], 0, v[148:149]
	s_mov_b32 m0, s56
	ds_read_b128 v[194:197], v179 offset:16384
	ds_read_b128 v[198:201], v246 offset:16384
	ds_read_b128 v[202:205], v179 offset:18432
	ds_read_b128 v[206:209], v246 offset:18432
	ds_read_b128 v[210:213], v179 offset:20480
	ds_read_b128 v[214:217], v246 offset:20480
	ds_read_b128 v[218:221], v179 offset:22528
	ds_read_b128 v[222:225], v246 offset:22528
	global_load_lds_dwordx4 v[172:173], off
	s_add_i32 m0, s56, 0x2000
	s_add_u32 s56, s26, 0x40000
	v_lshl_add_u64 v[176:177], s[26:27], 0, v[144:145]
	s_addc_u32 s57, s27, 0
	s_add_i32 s58, s47, s33
	global_load_lds_dwordx4 v[176:177], off
	v_lshl_add_u64 v[226:227], s[56:57], 0, v[148:149]
	s_mov_b32 m0, s58
	v_lshl_add_u64 v[228:229], s[28:29], 0, v[146:147]
	global_load_lds_dwordx4 v[226:227], off
	v_lshl_add_u64 v[226:227], s[56:57], 0, v[144:145]
	s_add_i32 m0, s58, 0x2000
	s_nop 0
	global_load_lds_dwordx4 v[226:227], off
	v_lshl_add_u64 v[226:227], s[28:29], 0, v[150:151]
	s_mov_b32 m0, s23
	s_nop 0
	global_load_lds_dwordx4 v[226:227], off
	s_mov_b32 m0, s36
	s_nop 0
	global_load_lds_dwordx4 v[228:229], off
	s_waitcnt vmcnt(8)
	s_waitcnt lgkmcnt(0)
	s_barrier
	s_waitcnt lgkmcnt(0)
	v_mfma_f32_16x16x32_bf16 v[60:63], v[124:127], v[194:197], 0
	v_mfma_f32_16x16x32_bf16 v[56:59], v[136:139], v[194:197], 0
	v_mfma_f32_16x16x32_bf16 v[44:47], v[124:127], v[202:205], 0
	v_mfma_f32_16x16x32_bf16 v[40:43], v[136:139], v[202:205], 0
	v_mfma_f32_16x16x32_bf16 v[28:31], v[124:127], v[210:213], 0
	v_mfma_f32_16x16x32_bf16 v[24:27], v[136:139], v[210:213], 0
	v_mfma_f32_16x16x32_bf16 v[12:15], v[124:127], v[218:221], 0
	v_mfma_f32_16x16x32_bf16 v[8:11], v[136:139], v[218:221], 0
	v_mfma_f32_16x16x32_bf16 v[60:63], v[132:135], v[198:201], v[60:63]
	v_mfma_f32_16x16x32_bf16 v[56:59], v[140:143], v[198:201], v[56:59]
	v_mfma_f32_16x16x32_bf16 v[44:47], v[132:135], v[206:209], v[44:47]
	v_mfma_f32_16x16x32_bf16 v[40:43], v[140:143], v[206:209], v[40:43]
	v_mfma_f32_16x16x32_bf16 v[28:31], v[132:135], v[214:217], v[28:31]
	v_mfma_f32_16x16x32_bf16 v[24:27], v[140:143], v[214:217], v[24:27]
	v_mfma_f32_16x16x32_bf16 v[12:15], v[132:135], v[222:225], v[12:15]
	v_mfma_f32_16x16x32_bf16 v[8:11], v[140:143], v[222:225], v[8:11]
	v_mfma_f32_16x16x32_bf16 v[52:55], v[162:165], v[194:197], 0
	v_mfma_f32_16x16x32_bf16 v[48:51], v[186:189], v[194:197], 0
	v_mfma_f32_16x16x32_bf16 v[36:39], v[162:165], v[202:205], 0
	v_mfma_f32_16x16x32_bf16 v[32:35], v[186:189], v[202:205], 0
	v_mfma_f32_16x16x32_bf16 v[20:23], v[162:165], v[210:213], 0
	v_mfma_f32_16x16x32_bf16 v[16:19], v[186:189], v[210:213], 0
	v_mfma_f32_16x16x32_bf16 v[4:7], v[162:165], v[218:221], 0
	v_mfma_f32_16x16x32_bf16 v[0:3], v[186:189], v[218:221], 0
	v_mfma_f32_16x16x32_bf16 v[52:55], v[182:185], v[198:201], v[52:55]
	v_mfma_f32_16x16x32_bf16 v[48:51], v[190:193], v[198:201], v[48:51]
	v_mfma_f32_16x16x32_bf16 v[36:39], v[182:185], v[206:209], v[36:39]
	v_mfma_f32_16x16x32_bf16 v[32:35], v[190:193], v[206:209], v[32:35]
	v_mfma_f32_16x16x32_bf16 v[20:23], v[182:185], v[214:217], v[20:23]
	v_mfma_f32_16x16x32_bf16 v[16:19], v[190:193], v[214:217], v[16:19]
	v_mfma_f32_16x16x32_bf16 v[4:7], v[182:185], v[222:225], v[4:7]
	v_mfma_f32_16x16x32_bf16 v[0:3], v[190:193], v[222:225], v[0:3]
	s_barrier
	s_add_i32 s56, 0, 0x18000
	s_add_i32 s57, 0, 0x1c000
	v_add_u32_e32 v140, s56, v167
	v_add_u32_e32 v250, s56, v247
	v_add_u32_e32 v160, s57, v167
	v_add_u32_e32 v251, s57, v247
	ds_read_b128 v[124:127], v140
	ds_read_b128 v[132:135], v250
	ds_read_b128 v[136:139], v140 offset:2048
	ds_read_b128 v[140:143], v250 offset:2048
	ds_read_b128 v[162:165], v160
	ds_read_b128 v[182:185], v251
	ds_read_b128 v[186:189], v160 offset:2048
	ds_read_b128 v[190:193], v251 offset:2048
	s_add_u32 s28, s28, 0x40000
	s_addc_u32 s29, s29, 0
	s_mov_b32 m0, s37
	v_lshl_add_u64 v[230:231], s[28:29], 0, v[150:151]
	ds_read_b128 v[194:197], v179 offset:32768
	ds_read_b128 v[198:201], v246 offset:32768
	ds_read_b128 v[202:205], v179 offset:34816
	ds_read_b128 v[206:209], v246 offset:34816
	ds_read_b128 v[210:213], v179 offset:36864
	ds_read_b128 v[214:217], v246 offset:36864
	ds_read_b128 v[218:221], v179 offset:38912
	ds_read_b128 v[222:225], v246 offset:38912
	global_load_lds_dwordx4 v[230:231], off
	v_lshl_add_u64 v[230:231], s[28:29], 0, v[146:147]
	s_mov_b32 m0, s38
	s_nop 0
	global_load_lds_dwordx4 v[230:231], off
	s_waitcnt vmcnt(8)
	s_waitcnt lgkmcnt(0)
	s_barrier
	s_waitcnt lgkmcnt(0)
	v_mfma_f32_16x16x32_bf16 v[128:131], v[124:127], v[194:197], v[128:131]
	v_mfma_f32_16x16x32_bf16 v[120:123], v[136:139], v[194:197], v[120:123]
	v_mfma_f32_16x16x32_bf16 v[108:111], v[124:127], v[202:205], v[108:111]
	v_mfma_f32_16x16x32_bf16 v[104:107], v[136:139], v[202:205], v[104:107]
	v_mfma_f32_16x16x32_bf16 v[92:95], v[124:127], v[210:213], v[92:95]
	v_mfma_f32_16x16x32_bf16 v[88:91], v[136:139], v[210:213], v[88:91]
	v_mfma_f32_16x16x32_bf16 v[76:79], v[124:127], v[218:221], v[76:79]
	v_mfma_f32_16x16x32_bf16 v[72:75], v[136:139], v[218:221], v[72:75]
	v_mfma_f32_16x16x32_bf16 v[128:131], v[132:135], v[198:201], v[128:131]
	v_mfma_f32_16x16x32_bf16 v[120:123], v[140:143], v[198:201], v[120:123]
	v_mfma_f32_16x16x32_bf16 v[108:111], v[132:135], v[206:209], v[108:111]
	v_mfma_f32_16x16x32_bf16 v[104:107], v[140:143], v[206:209], v[104:107]
	v_mfma_f32_16x16x32_bf16 v[92:95], v[132:135], v[214:217], v[92:95]
	v_mfma_f32_16x16x32_bf16 v[88:91], v[140:143], v[214:217], v[88:91]
	v_mfma_f32_16x16x32_bf16 v[76:79], v[132:135], v[222:225], v[76:79]
	v_mfma_f32_16x16x32_bf16 v[72:75], v[140:143], v[222:225], v[72:75]
	v_mfma_f32_16x16x32_bf16 v[116:119], v[162:165], v[194:197], v[116:119]
	v_mfma_f32_16x16x32_bf16 v[112:115], v[186:189], v[194:197], v[112:115]
	v_mfma_f32_16x16x32_bf16 v[100:103], v[162:165], v[202:205], v[100:103]
	v_mfma_f32_16x16x32_bf16 v[96:99], v[186:189], v[202:205], v[96:99]
	v_mfma_f32_16x16x32_bf16 v[84:87], v[162:165], v[210:213], v[84:87]
	v_mfma_f32_16x16x32_bf16 v[80:83], v[186:189], v[210:213], v[80:83]
	v_mfma_f32_16x16x32_bf16 v[68:71], v[162:165], v[218:221], v[68:71]
	v_mfma_f32_16x16x32_bf16 v[64:67], v[186:189], v[218:221], v[64:67]
	v_mfma_f32_16x16x32_bf16 v[116:119], v[182:185], v[198:201], v[116:119]
	v_mfma_f32_16x16x32_bf16 v[112:115], v[190:193], v[198:201], v[112:115]
	v_mfma_f32_16x16x32_bf16 v[100:103], v[182:185], v[206:209], v[100:103]
	v_mfma_f32_16x16x32_bf16 v[96:99], v[190:193], v[206:209], v[96:99]
	v_mfma_f32_16x16x32_bf16 v[84:87], v[182:185], v[214:217], v[84:87]
	v_mfma_f32_16x16x32_bf16 v[80:83], v[190:193], v[214:217], v[80:83]
	v_mfma_f32_16x16x32_bf16 v[68:71], v[182:185], v[222:225], v[68:71]
	v_mfma_f32_16x16x32_bf16 v[64:67], v[190:193], v[222:225], v[64:67]
	s_barrier
	s_add_i32 s28, s56, s33
	v_lshl_add_u64 v[172:173], v[172:173], 0, s[10:11]
	s_mov_b32 m0, s28
	ds_read_b128 v[194:197], v179 offset:49152
	ds_read_b128 v[198:201], v246 offset:49152
	ds_read_b128 v[202:205], v179 offset:51200
	ds_read_b128 v[206:209], v246 offset:51200
	ds_read_b128 v[210:213], v179 offset:53248
	ds_read_b128 v[214:217], v246 offset:53248
	ds_read_b128 v[218:221], v179 offset:55296
	ds_read_b128 v[222:225], v246 offset:55296
	global_load_lds_dwordx4 v[172:173], off
	s_add_i32 m0, s28, 0x2000
	s_add_u32 s26, s26, 0x40080
	v_lshl_add_u64 v[172:173], v[176:177], 0, s[10:11]
	s_addc_u32 s27, s27, 0
	s_add_i32 s28, s57, s33
	global_load_lds_dwordx4 v[172:173], off
	v_lshl_add_u64 v[172:173], s[26:27], 0, v[148:149]
	s_mov_b32 m0, s28
	s_nop 0
	global_load_lds_dwordx4 v[172:173], off
	v_lshl_add_u64 v[172:173], s[26:27], 0, v[144:145]
	s_add_i32 m0, s28, 0x2000
	s_nop 0
	global_load_lds_dwordx4 v[172:173], off
	v_lshl_add_u64 v[172:173], v[226:227], 0, s[10:11]
	s_mov_b32 m0, s43
	s_nop 0
	global_load_lds_dwordx4 v[172:173], off
	v_lshl_add_u64 v[172:173], v[228:229], 0, s[10:11]
	s_mov_b32 m0, s44
	s_nop 0
	global_load_lds_dwordx4 v[172:173], off
	s_waitcnt vmcnt(8)
	s_waitcnt lgkmcnt(0)
	s_barrier
	s_waitcnt lgkmcnt(0)
	v_mfma_f32_16x16x32_bf16 v[60:63], v[124:127], v[194:197], v[60:63]
	v_mfma_f32_16x16x32_bf16 v[56:59], v[136:139], v[194:197], v[56:59]
	v_mfma_f32_16x16x32_bf16 v[44:47], v[124:127], v[202:205], v[44:47]
	v_mfma_f32_16x16x32_bf16 v[40:43], v[136:139], v[202:205], v[40:43]
	v_mfma_f32_16x16x32_bf16 v[28:31], v[124:127], v[210:213], v[28:31]
	v_mfma_f32_16x16x32_bf16 v[24:27], v[136:139], v[210:213], v[24:27]
	v_mfma_f32_16x16x32_bf16 v[12:15], v[124:127], v[218:221], v[12:15]
	v_mfma_f32_16x16x32_bf16 v[8:11], v[136:139], v[218:221], v[8:11]
	v_mfma_f32_16x16x32_bf16 v[60:63], v[132:135], v[198:201], v[60:63]
	v_mfma_f32_16x16x32_bf16 v[56:59], v[140:143], v[198:201], v[56:59]
	v_mfma_f32_16x16x32_bf16 v[44:47], v[132:135], v[206:209], v[44:47]
	v_mfma_f32_16x16x32_bf16 v[40:43], v[140:143], v[206:209], v[40:43]
	v_mfma_f32_16x16x32_bf16 v[28:31], v[132:135], v[214:217], v[28:31]
	v_mfma_f32_16x16x32_bf16 v[24:27], v[140:143], v[214:217], v[24:27]
	v_mfma_f32_16x16x32_bf16 v[12:15], v[132:135], v[222:225], v[12:15]
	v_mfma_f32_16x16x32_bf16 v[8:11], v[140:143], v[222:225], v[8:11]
	v_mfma_f32_16x16x32_bf16 v[52:55], v[162:165], v[194:197], v[52:55]
	v_mfma_f32_16x16x32_bf16 v[48:51], v[186:189], v[194:197], v[48:51]
	v_mfma_f32_16x16x32_bf16 v[36:39], v[162:165], v[202:205], v[36:39]
	v_mfma_f32_16x16x32_bf16 v[32:35], v[186:189], v[202:205], v[32:35]
	v_mfma_f32_16x16x32_bf16 v[20:23], v[162:165], v[210:213], v[20:23]
	v_mfma_f32_16x16x32_bf16 v[16:19], v[186:189], v[210:213], v[16:19]
	v_mfma_f32_16x16x32_bf16 v[4:7], v[162:165], v[218:221], v[4:7]
	v_mfma_f32_16x16x32_bf16 v[0:3], v[186:189], v[218:221], v[0:3]
	v_mfma_f32_16x16x32_bf16 v[52:55], v[182:185], v[198:201], v[52:55]
	v_mfma_f32_16x16x32_bf16 v[48:51], v[190:193], v[198:201], v[48:51]
	v_mfma_f32_16x16x32_bf16 v[36:39], v[182:185], v[206:209], v[36:39]
	v_mfma_f32_16x16x32_bf16 v[32:35], v[190:193], v[206:209], v[32:35]
	v_mfma_f32_16x16x32_bf16 v[20:23], v[182:185], v[214:217], v[20:23]
	v_mfma_f32_16x16x32_bf16 v[16:19], v[190:193], v[214:217], v[16:19]
	v_mfma_f32_16x16x32_bf16 v[4:7], v[182:185], v[222:225], v[4:7]
	v_mfma_f32_16x16x32_bf16 v[0:3], v[190:193], v[222:225], v[0:3]
	s_barrier
	s_add_i32 s55, s55, 2
	s_add_u32 s24, s24, 0x100
	s_addc_u32 s25, s25, 0
	s_add_u32 s53, s53, 0x100
	s_addc_u32 s54, s54, 0
	s_cmp_gt_u32 s55, 13
.LBB0_1113:
	ds_read_b128 v[124:127], v171
	ds_read_b128 v[132:135], v248
	ds_read_b128 v[136:139], v171 offset:2048
	ds_read_b128 v[140:143], v248 offset:2048
	ds_read_b128 v[162:165], v175
	ds_read_b128 v[182:185], v249
	ds_read_b128 v[186:189], v175 offset:2048
	ds_read_b128 v[190:193], v249 offset:2048
	s_add_u32 s26, s24, 0xfffc0080
	s_addc_u32 s27, s25, -1
	s_cmp_eq_u32 s55, 12
	s_cselect_b32 s29, s17, s27
	s_cselect_b32 s28, s51, s26
	s_cselect_b32 s27, s15, s54
	s_cselect_b32 s26, s52, s53
	v_lshl_add_u64 v[172:173], s[24:25], 0, v[152:153]
	s_add_i32 m0, s23, 0xc000
	ds_read_b128 v[194:197], v179
	ds_read_b128 v[198:201], v246
	ds_read_b128 v[202:205], v179 offset:2048
	ds_read_b128 v[206:209], v246 offset:2048
	ds_read_b128 v[210:213], v179 offset:4096
	ds_read_b128 v[214:217], v246 offset:4096
	ds_read_b128 v[218:221], v179 offset:6144
	ds_read_b128 v[222:225], v246 offset:6144
	global_load_lds_dwordx4 v[172:173], off
	v_lshl_add_u64 v[172:173], s[24:25], 0, v[154:155]
	s_add_i32 m0, s23, 0xe000
	s_nop 0
	global_load_lds_dwordx4 v[172:173], off
	s_waitcnt vmcnt(8)
	s_waitcnt lgkmcnt(0)
	s_barrier
	s_waitcnt lgkmcnt(0)
	v_mfma_f32_16x16x32_bf16 v[128:131], v[124:127], v[194:197], v[128:131]
	v_mfma_f32_16x16x32_bf16 v[120:123], v[136:139], v[194:197], v[120:123]
	v_mfma_f32_16x16x32_bf16 v[108:111], v[124:127], v[202:205], v[108:111]
	v_mfma_f32_16x16x32_bf16 v[104:107], v[136:139], v[202:205], v[104:107]
	v_mfma_f32_16x16x32_bf16 v[92:95], v[124:127], v[210:213], v[92:95]
	v_mfma_f32_16x16x32_bf16 v[88:91], v[136:139], v[210:213], v[88:91]
	v_mfma_f32_16x16x32_bf16 v[76:79], v[124:127], v[218:221], v[76:79]
	v_mfma_f32_16x16x32_bf16 v[72:75], v[136:139], v[218:221], v[72:75]
	v_mfma_f32_16x16x32_bf16 v[128:131], v[132:135], v[198:201], v[128:131]
	v_mfma_f32_16x16x32_bf16 v[120:123], v[140:143], v[198:201], v[120:123]
	v_mfma_f32_16x16x32_bf16 v[108:111], v[132:135], v[206:209], v[108:111]
	v_mfma_f32_16x16x32_bf16 v[104:107], v[140:143], v[206:209], v[104:107]
	v_mfma_f32_16x16x32_bf16 v[92:95], v[132:135], v[214:217], v[92:95]
	v_mfma_f32_16x16x32_bf16 v[88:91], v[140:143], v[214:217], v[88:91]
	v_mfma_f32_16x16x32_bf16 v[76:79], v[132:135], v[222:225], v[76:79]
	v_mfma_f32_16x16x32_bf16 v[72:75], v[140:143], v[222:225], v[72:75]
	v_mfma_f32_16x16x32_bf16 v[116:119], v[162:165], v[194:197], v[116:119]
	v_mfma_f32_16x16x32_bf16 v[112:115], v[186:189], v[194:197], v[112:115]
	v_mfma_f32_16x16x32_bf16 v[100:103], v[162:165], v[202:205], v[100:103]
	v_mfma_f32_16x16x32_bf16 v[96:99], v[186:189], v[202:205], v[96:99]
	v_mfma_f32_16x16x32_bf16 v[84:87], v[162:165], v[210:213], v[84:87]
	v_mfma_f32_16x16x32_bf16 v[80:83], v[186:189], v[210:213], v[80:83]
	v_mfma_f32_16x16x32_bf16 v[68:71], v[162:165], v[218:221], v[68:71]
	v_mfma_f32_16x16x32_bf16 v[64:67], v[186:189], v[218:221], v[64:67]
	v_mfma_f32_16x16x32_bf16 v[116:119], v[182:185], v[198:201], v[116:119]
	v_mfma_f32_16x16x32_bf16 v[112:115], v[190:193], v[198:201], v[112:115]
	v_mfma_f32_16x16x32_bf16 v[100:103], v[182:185], v[206:209], v[100:103]
	v_mfma_f32_16x16x32_bf16 v[96:99], v[190:193], v[206:209], v[96:99]
	v_mfma_f32_16x16x32_bf16 v[84:87], v[182:185], v[214:217], v[84:87]
	v_mfma_f32_16x16x32_bf16 v[80:83], v[190:193], v[214:217], v[80:83]
	v_mfma_f32_16x16x32_bf16 v[68:71], v[182:185], v[222:225], v[68:71]
	v_mfma_f32_16x16x32_bf16 v[64:67], v[190:193], v[222:225], v[64:67]
	s_barrier
	s_add_i32 s56, s46, s33
	v_lshl_add_u64 v[172:173], s[26:27], 0, v[148:149]
	s_mov_b32 m0, s56
	ds_read_b128 v[194:197], v179 offset:16384
	ds_read_b128 v[198:201], v246 offset:16384
	ds_read_b128 v[202:205], v179 offset:18432
	ds_read_b128 v[206:209], v246 offset:18432
	ds_read_b128 v[210:213], v179 offset:20480
	ds_read_b128 v[214:217], v246 offset:20480
	ds_read_b128 v[218:221], v179 offset:22528
	ds_read_b128 v[222:225], v246 offset:22528
	global_load_lds_dwordx4 v[172:173], off
	s_add_i32 m0, s56, 0x2000
	s_add_u32 s56, s26, 0x40000
	v_lshl_add_u64 v[176:177], s[26:27], 0, v[144:145]
	s_addc_u32 s57, s27, 0
	s_add_i32 s58, s47, s33
	global_load_lds_dwordx4 v[176:177], off
	v_lshl_add_u64 v[226:227], s[56:57], 0, v[148:149]
	s_mov_b32 m0, s58
	v_lshl_add_u64 v[228:229], s[28:29], 0, v[146:147]
	global_load_lds_dwordx4 v[226:227], off
	v_lshl_add_u64 v[226:227], s[56:57], 0, v[144:145]
	s_add_i32 m0, s58, 0x2000
	s_nop 0
	global_load_lds_dwordx4 v[226:227], off
	v_lshl_add_u64 v[226:227], s[28:29], 0, v[150:151]
	s_mov_b32 m0, s23
	s_nop 0
	global_load_lds_dwordx4 v[226:227], off
	s_mov_b32 m0, s36
	s_nop 0
	global_load_lds_dwordx4 v[228:229], off
	s_waitcnt vmcnt(8)
	s_waitcnt lgkmcnt(0)
	s_barrier
	s_waitcnt lgkmcnt(0)
	v_mfma_f32_16x16x32_bf16 v[60:63], v[124:127], v[194:197], v[60:63]
	v_mfma_f32_16x16x32_bf16 v[56:59], v[136:139], v[194:197], v[56:59]
	v_mfma_f32_16x16x32_bf16 v[44:47], v[124:127], v[202:205], v[44:47]
	v_mfma_f32_16x16x32_bf16 v[40:43], v[136:139], v[202:205], v[40:43]
	v_mfma_f32_16x16x32_bf16 v[28:31], v[124:127], v[210:213], v[28:31]
	v_mfma_f32_16x16x32_bf16 v[24:27], v[136:139], v[210:213], v[24:27]
	v_mfma_f32_16x16x32_bf16 v[12:15], v[124:127], v[218:221], v[12:15]
	v_mfma_f32_16x16x32_bf16 v[8:11], v[136:139], v[218:221], v[8:11]
	v_mfma_f32_16x16x32_bf16 v[60:63], v[132:135], v[198:201], v[60:63]
	v_mfma_f32_16x16x32_bf16 v[56:59], v[140:143], v[198:201], v[56:59]
	v_mfma_f32_16x16x32_bf16 v[44:47], v[132:135], v[206:209], v[44:47]
	v_mfma_f32_16x16x32_bf16 v[40:43], v[140:143], v[206:209], v[40:43]
	v_mfma_f32_16x16x32_bf16 v[28:31], v[132:135], v[214:217], v[28:31]
	v_mfma_f32_16x16x32_bf16 v[24:27], v[140:143], v[214:217], v[24:27]
	v_mfma_f32_16x16x32_bf16 v[12:15], v[132:135], v[222:225], v[12:15]
	v_mfma_f32_16x16x32_bf16 v[8:11], v[140:143], v[222:225], v[8:11]
	v_mfma_f32_16x16x32_bf16 v[52:55], v[162:165], v[194:197], v[52:55]
	v_mfma_f32_16x16x32_bf16 v[48:51], v[186:189], v[194:197], v[48:51]
	v_mfma_f32_16x16x32_bf16 v[36:39], v[162:165], v[202:205], v[36:39]
	v_mfma_f32_16x16x32_bf16 v[32:35], v[186:189], v[202:205], v[32:35]
	v_mfma_f32_16x16x32_bf16 v[20:23], v[162:165], v[210:213], v[20:23]
	v_mfma_f32_16x16x32_bf16 v[16:19], v[186:189], v[210:213], v[16:19]
	v_mfma_f32_16x16x32_bf16 v[4:7], v[162:165], v[218:221], v[4:7]
	v_mfma_f32_16x16x32_bf16 v[0:3], v[186:189], v[218:221], v[0:3]
	v_mfma_f32_16x16x32_bf16 v[52:55], v[182:185], v[198:201], v[52:55]
	v_mfma_f32_16x16x32_bf16 v[48:51], v[190:193], v[198:201], v[48:51]
	v_mfma_f32_16x16x32_bf16 v[36:39], v[182:185], v[206:209], v[36:39]
	v_mfma_f32_16x16x32_bf16 v[32:35], v[190:193], v[206:209], v[32:35]
	v_mfma_f32_16x16x32_bf16 v[20:23], v[182:185], v[214:217], v[20:23]
	v_mfma_f32_16x16x32_bf16 v[16:19], v[190:193], v[214:217], v[16:19]
	v_mfma_f32_16x16x32_bf16 v[4:7], v[182:185], v[222:225], v[4:7]
	v_mfma_f32_16x16x32_bf16 v[0:3], v[190:193], v[222:225], v[0:3]
	s_barrier
	s_add_i32 s56, 0, 0x18000
	s_add_i32 s57, 0, 0x1c000
	v_add_u32_e32 v140, s56, v167
	v_add_u32_e32 v250, s56, v247
	v_add_u32_e32 v160, s57, v167
	v_add_u32_e32 v251, s57, v247
	ds_read_b128 v[124:127], v140
	ds_read_b128 v[132:135], v250
	ds_read_b128 v[136:139], v140 offset:2048
	ds_read_b128 v[140:143], v250 offset:2048
	ds_read_b128 v[162:165], v160
	ds_read_b128 v[182:185], v251
	ds_read_b128 v[186:189], v160 offset:2048
	ds_read_b128 v[190:193], v251 offset:2048
	s_add_u32 s28, s28, 0x40000
	s_addc_u32 s29, s29, 0
	s_mov_b32 m0, s37
	v_lshl_add_u64 v[230:231], s[28:29], 0, v[150:151]
	ds_read_b128 v[194:197], v179 offset:32768
	ds_read_b128 v[198:201], v246 offset:32768
	ds_read_b128 v[202:205], v179 offset:34816
	ds_read_b128 v[206:209], v246 offset:34816
	ds_read_b128 v[210:213], v179 offset:36864
	ds_read_b128 v[214:217], v246 offset:36864
	ds_read_b128 v[218:221], v179 offset:38912
	ds_read_b128 v[222:225], v246 offset:38912
	global_load_lds_dwordx4 v[230:231], off
	v_lshl_add_u64 v[230:231], s[28:29], 0, v[146:147]
	s_mov_b32 m0, s38
	s_nop 0
	global_load_lds_dwordx4 v[230:231], off
	s_waitcnt vmcnt(8)
	s_waitcnt lgkmcnt(0)
	s_barrier
	s_waitcnt lgkmcnt(0)
	v_mfma_f32_16x16x32_bf16 v[128:131], v[124:127], v[194:197], v[128:131]
	v_mfma_f32_16x16x32_bf16 v[120:123], v[136:139], v[194:197], v[120:123]
	v_mfma_f32_16x16x32_bf16 v[108:111], v[124:127], v[202:205], v[108:111]
	v_mfma_f32_16x16x32_bf16 v[104:107], v[136:139], v[202:205], v[104:107]
	v_mfma_f32_16x16x32_bf16 v[92:95], v[124:127], v[210:213], v[92:95]
	v_mfma_f32_16x16x32_bf16 v[88:91], v[136:139], v[210:213], v[88:91]
	v_mfma_f32_16x16x32_bf16 v[76:79], v[124:127], v[218:221], v[76:79]
	v_mfma_f32_16x16x32_bf16 v[72:75], v[136:139], v[218:221], v[72:75]
	v_mfma_f32_16x16x32_bf16 v[128:131], v[132:135], v[198:201], v[128:131]
	v_mfma_f32_16x16x32_bf16 v[120:123], v[140:143], v[198:201], v[120:123]
	v_mfma_f32_16x16x32_bf16 v[108:111], v[132:135], v[206:209], v[108:111]
	v_mfma_f32_16x16x32_bf16 v[104:107], v[140:143], v[206:209], v[104:107]
	v_mfma_f32_16x16x32_bf16 v[92:95], v[132:135], v[214:217], v[92:95]
	v_mfma_f32_16x16x32_bf16 v[88:91], v[140:143], v[214:217], v[88:91]
	v_mfma_f32_16x16x32_bf16 v[76:79], v[132:135], v[222:225], v[76:79]
	v_mfma_f32_16x16x32_bf16 v[72:75], v[140:143], v[222:225], v[72:75]
	v_mfma_f32_16x16x32_bf16 v[116:119], v[162:165], v[194:197], v[116:119]
	v_mfma_f32_16x16x32_bf16 v[112:115], v[186:189], v[194:197], v[112:115]
	v_mfma_f32_16x16x32_bf16 v[100:103], v[162:165], v[202:205], v[100:103]
	v_mfma_f32_16x16x32_bf16 v[96:99], v[186:189], v[202:205], v[96:99]
	v_mfma_f32_16x16x32_bf16 v[84:87], v[162:165], v[210:213], v[84:87]
	v_mfma_f32_16x16x32_bf16 v[80:83], v[186:189], v[210:213], v[80:83]
	v_mfma_f32_16x16x32_bf16 v[68:71], v[162:165], v[218:221], v[68:71]
	v_mfma_f32_16x16x32_bf16 v[64:67], v[186:189], v[218:221], v[64:67]
	v_mfma_f32_16x16x32_bf16 v[116:119], v[182:185], v[198:201], v[116:119]
	v_mfma_f32_16x16x32_bf16 v[112:115], v[190:193], v[198:201], v[112:115]
	v_mfma_f32_16x16x32_bf16 v[100:103], v[182:185], v[206:209], v[100:103]
	v_mfma_f32_16x16x32_bf16 v[96:99], v[190:193], v[206:209], v[96:99]
	v_mfma_f32_16x16x32_bf16 v[84:87], v[182:185], v[214:217], v[84:87]
	v_mfma_f32_16x16x32_bf16 v[80:83], v[190:193], v[214:217], v[80:83]
	v_mfma_f32_16x16x32_bf16 v[68:71], v[182:185], v[222:225], v[68:71]
	v_mfma_f32_16x16x32_bf16 v[64:67], v[190:193], v[222:225], v[64:67]
	s_barrier
	s_add_i32 s28, s56, s33
	v_lshl_add_u64 v[172:173], v[172:173], 0, s[10:11]
	s_mov_b32 m0, s28
	ds_read_b128 v[194:197], v179 offset:49152
	ds_read_b128 v[198:201], v246 offset:49152
	ds_read_b128 v[202:205], v179 offset:51200
	ds_read_b128 v[206:209], v246 offset:51200
	ds_read_b128 v[210:213], v179 offset:53248
	ds_read_b128 v[214:217], v246 offset:53248
	ds_read_b128 v[218:221], v179 offset:55296
	ds_read_b128 v[222:225], v246 offset:55296
	global_load_lds_dwordx4 v[172:173], off
	s_add_i32 m0, s28, 0x2000
	s_add_u32 s26, s26, 0x40080
	v_lshl_add_u64 v[172:173], v[176:177], 0, s[10:11]
	s_addc_u32 s27, s27, 0
	s_add_i32 s28, s57, s33
	global_load_lds_dwordx4 v[172:173], off
	v_lshl_add_u64 v[172:173], s[26:27], 0, v[148:149]
	s_mov_b32 m0, s28
	s_nop 0
	global_load_lds_dwordx4 v[172:173], off
	v_lshl_add_u64 v[172:173], s[26:27], 0, v[144:145]
	s_add_i32 m0, s28, 0x2000
	s_nop 0
	global_load_lds_dwordx4 v[172:173], off
	v_lshl_add_u64 v[172:173], v[226:227], 0, s[10:11]
	s_mov_b32 m0, s43
	s_nop 0
	global_load_lds_dwordx4 v[172:173], off
	v_lshl_add_u64 v[172:173], v[228:229], 0, s[10:11]
	s_mov_b32 m0, s44
	s_nop 0
	global_load_lds_dwordx4 v[172:173], off
	s_waitcnt vmcnt(8)
	s_waitcnt lgkmcnt(0)
	s_barrier
	s_waitcnt lgkmcnt(0)
	v_mfma_f32_16x16x32_bf16 v[60:63], v[124:127], v[194:197], v[60:63]
	v_mfma_f32_16x16x32_bf16 v[56:59], v[136:139], v[194:197], v[56:59]
	v_mfma_f32_16x16x32_bf16 v[44:47], v[124:127], v[202:205], v[44:47]
	v_mfma_f32_16x16x32_bf16 v[40:43], v[136:139], v[202:205], v[40:43]
	v_mfma_f32_16x16x32_bf16 v[28:31], v[124:127], v[210:213], v[28:31]
	v_mfma_f32_16x16x32_bf16 v[24:27], v[136:139], v[210:213], v[24:27]
	v_mfma_f32_16x16x32_bf16 v[12:15], v[124:127], v[218:221], v[12:15]
	v_mfma_f32_16x16x32_bf16 v[8:11], v[136:139], v[218:221], v[8:11]
	v_mfma_f32_16x16x32_bf16 v[60:63], v[132:135], v[198:201], v[60:63]
	v_mfma_f32_16x16x32_bf16 v[56:59], v[140:143], v[198:201], v[56:59]
	v_mfma_f32_16x16x32_bf16 v[44:47], v[132:135], v[206:209], v[44:47]
	v_mfma_f32_16x16x32_bf16 v[40:43], v[140:143], v[206:209], v[40:43]
	v_mfma_f32_16x16x32_bf16 v[28:31], v[132:135], v[214:217], v[28:31]
	v_mfma_f32_16x16x32_bf16 v[24:27], v[140:143], v[214:217], v[24:27]
	v_mfma_f32_16x16x32_bf16 v[12:15], v[132:135], v[222:225], v[12:15]
	v_mfma_f32_16x16x32_bf16 v[8:11], v[140:143], v[222:225], v[8:11]
	v_mfma_f32_16x16x32_bf16 v[52:55], v[162:165], v[194:197], v[52:55]
	v_mfma_f32_16x16x32_bf16 v[48:51], v[186:189], v[194:197], v[48:51]
	v_mfma_f32_16x16x32_bf16 v[36:39], v[162:165], v[202:205], v[36:39]
	v_mfma_f32_16x16x32_bf16 v[32:35], v[186:189], v[202:205], v[32:35]
	v_mfma_f32_16x16x32_bf16 v[20:23], v[162:165], v[210:213], v[20:23]
	v_mfma_f32_16x16x32_bf16 v[16:19], v[186:189], v[210:213], v[16:19]
	v_mfma_f32_16x16x32_bf16 v[4:7], v[162:165], v[218:221], v[4:7]
	v_mfma_f32_16x16x32_bf16 v[0:3], v[186:189], v[218:221], v[0:3]
	v_mfma_f32_16x16x32_bf16 v[52:55], v[182:185], v[198:201], v[52:55]
	v_mfma_f32_16x16x32_bf16 v[48:51], v[190:193], v[198:201], v[48:51]
	v_mfma_f32_16x16x32_bf16 v[36:39], v[182:185], v[206:209], v[36:39]
	v_mfma_f32_16x16x32_bf16 v[32:35], v[190:193], v[206:209], v[32:35]
	v_mfma_f32_16x16x32_bf16 v[20:23], v[182:185], v[214:217], v[20:23]
	v_mfma_f32_16x16x32_bf16 v[16:19], v[190:193], v[214:217], v[16:19]
	v_mfma_f32_16x16x32_bf16 v[4:7], v[182:185], v[222:225], v[4:7]
	v_mfma_f32_16x16x32_bf16 v[0:3], v[190:193], v[222:225], v[0:3]
	s_barrier
	s_add_i32 s55, s55, 2
	s_add_u32 s24, s24, 0x100
	s_addc_u32 s25, s25, 0
	s_add_u32 s53, s53, 0x100
	s_addc_u32 s54, s54, 0
	s_cmp_gt_u32 s55, 13
	s_cbranch_scc0 .LBB0_1113
	s_and_b64 vcc, exec, s[12:13]
	s_cbranch_vccz .LBB0_1116
	s_barrier

.LBB0_1195:
	s_add_u32 s41, s16, 0x100
	s_addc_u32 s42, s17, 0
	s_mov_b32 s43, -2
	s_waitcnt vmcnt(0)
	v_xor_b32_e32 v246, 64, v173
	v_xor_b32_e32 v247, 64, v169
	v_add_u32_e32 v248, s35, v247
	v_add_u32_e32 v249, s36, v247
	ds_read_b128 v[144:147], v171
	ds_read_b128 v[148:151], v248
	ds_read_b128 v[152:155], v171 offset:2048
	ds_read_b128 v[156:159], v248 offset:2048
	ds_read_b128 v[160:163], v172
	ds_read_b128 v[164:167], v249
	ds_read_b128 v[174:177], v172 offset:2048
	ds_read_b128 v[178:181], v249 offset:2048
	s_add_u32 s16, s14, 0x100
	s_addc_u32 s17, s15, 0
	s_cmp_eq_u32 s43, 40
	s_cselect_b32 s21, s5, s17
	s_cselect_b32 s20, s4, s16
	s_cselect_b32 s19, s13, s42
	s_cselect_b32 s18, s12, s41
	v_lshl_add_u64 v[214:215], s[14:15], 0, v[136:137]
	s_add_i32 m0, s24, 0xc000
	ds_read_b128 v[182:185], v173
	ds_read_b128 v[186:189], v246
	ds_read_b128 v[190:193], v173 offset:2048
	ds_read_b128 v[194:197], v246 offset:2048
	ds_read_b128 v[198:201], v173 offset:4096
	ds_read_b128 v[202:205], v246 offset:4096
	ds_read_b128 v[206:209], v173 offset:6144
	ds_read_b128 v[210:213], v246 offset:6144
	global_load_lds_dwordx4 v[214:215], off
	v_lshl_add_u64 v[214:215], s[14:15], 0, v[138:139]
	s_add_i32 m0, s24, 0xe000
	s_nop 0
	global_load_lds_dwordx4 v[214:215], off
	s_waitcnt vmcnt(8)
	s_waitcnt lgkmcnt(0)
	s_barrier
	s_waitcnt lgkmcnt(0)
	v_mfma_f32_16x16x32_bf16 v[124:127], v[144:147], v[182:185], 0
	v_mfma_f32_16x16x32_bf16 v[120:123], v[152:155], v[182:185], 0
	v_mfma_f32_16x16x32_bf16 v[112:115], v[144:147], v[190:193], 0
	v_mfma_f32_16x16x32_bf16 v[104:107], v[152:155], v[190:193], 0
	v_mfma_f32_16x16x32_bf16 v[96:99], v[144:147], v[198:201], 0
	v_mfma_f32_16x16x32_bf16 v[88:91], v[152:155], v[198:201], 0
	v_mfma_f32_16x16x32_bf16 v[80:83], v[144:147], v[206:209], 0
	v_mfma_f32_16x16x32_bf16 v[72:75], v[152:155], v[206:209], 0
	v_mfma_f32_16x16x32_bf16 v[124:127], v[148:151], v[186:189], v[124:127]
	v_mfma_f32_16x16x32_bf16 v[120:123], v[156:159], v[186:189], v[120:123]
	v_mfma_f32_16x16x32_bf16 v[112:115], v[148:151], v[194:197], v[112:115]
	v_mfma_f32_16x16x32_bf16 v[104:107], v[156:159], v[194:197], v[104:107]
	v_mfma_f32_16x16x32_bf16 v[96:99], v[148:151], v[202:205], v[96:99]
	v_mfma_f32_16x16x32_bf16 v[88:91], v[156:159], v[202:205], v[88:91]
	v_mfma_f32_16x16x32_bf16 v[80:83], v[148:151], v[210:213], v[80:83]
	v_mfma_f32_16x16x32_bf16 v[72:75], v[156:159], v[210:213], v[72:75]
	v_mfma_f32_16x16x32_bf16 v[116:119], v[160:163], v[182:185], 0
	v_mfma_f32_16x16x32_bf16 v[108:111], v[174:177], v[182:185], 0
	v_mfma_f32_16x16x32_bf16 v[100:103], v[160:163], v[190:193], 0
	v_mfma_f32_16x16x32_bf16 v[92:95], v[174:177], v[190:193], 0
	v_mfma_f32_16x16x32_bf16 v[84:87], v[160:163], v[198:201], 0
	v_mfma_f32_16x16x32_bf16 v[76:79], v[174:177], v[198:201], 0
	v_mfma_f32_16x16x32_bf16 v[68:71], v[160:163], v[206:209], 0
	v_mfma_f32_16x16x32_bf16 v[64:67], v[174:177], v[206:209], 0
	v_mfma_f32_16x16x32_bf16 v[116:119], v[164:167], v[186:189], v[116:119]
	v_mfma_f32_16x16x32_bf16 v[108:111], v[178:181], v[186:189], v[108:111]
	v_mfma_f32_16x16x32_bf16 v[100:103], v[164:167], v[194:197], v[100:103]
	v_mfma_f32_16x16x32_bf16 v[92:95], v[178:181], v[194:197], v[92:95]
	v_mfma_f32_16x16x32_bf16 v[84:87], v[164:167], v[202:205], v[84:87]
	v_mfma_f32_16x16x32_bf16 v[76:79], v[178:181], v[202:205], v[76:79]
	v_mfma_f32_16x16x32_bf16 v[68:71], v[164:167], v[210:213], v[68:71]
	v_mfma_f32_16x16x32_bf16 v[64:67], v[178:181], v[210:213], v[64:67]
	s_barrier
	s_add_i32 s14, s35, s23
	v_lshl_add_u64 v[214:215], s[18:19], 0, v[130:131]
	s_mov_b32 m0, s14
	ds_read_b128 v[182:185], v173 offset:16384
	ds_read_b128 v[186:189], v246 offset:16384
	ds_read_b128 v[190:193], v173 offset:18432
	ds_read_b128 v[194:197], v246 offset:18432
	ds_read_b128 v[198:201], v173 offset:20480
	ds_read_b128 v[202:205], v246 offset:20480
	ds_read_b128 v[206:209], v173 offset:22528
	ds_read_b128 v[210:213], v246 offset:22528
	global_load_lds_dwordx4 v[214:215], off
	s_add_i32 m0, s14, 0x2000
	s_add_u32 s14, s18, 0xb0000
	v_lshl_add_u64 v[216:217], s[18:19], 0, v[134:135]
	s_addc_u32 s15, s19, 0
	s_add_i32 s44, s36, s23
	global_load_lds_dwordx4 v[216:217], off
	v_lshl_add_u64 v[218:219], s[14:15], 0, v[130:131]
	s_mov_b32 m0, s44
	v_lshl_add_u64 v[220:221], s[20:21], 0, v[132:133]
	global_load_lds_dwordx4 v[218:219], off
	v_lshl_add_u64 v[218:219], s[14:15], 0, v[134:135]
	s_add_i32 m0, s44, 0x2000
	s_nop 0
	global_load_lds_dwordx4 v[218:219], off
	v_lshl_add_u64 v[218:219], s[20:21], 0, v[128:129]
	s_mov_b32 m0, s24
	s_nop 0
	global_load_lds_dwordx4 v[218:219], off
	s_mov_b32 m0, s25
	s_nop 0
	global_load_lds_dwordx4 v[220:221], off
	s_waitcnt vmcnt(8)
	s_waitcnt lgkmcnt(0)
	s_barrier
	s_waitcnt lgkmcnt(0)
	v_mfma_f32_16x16x32_bf16 v[60:63], v[144:147], v[182:185], 0
	v_mfma_f32_16x16x32_bf16 v[56:59], v[152:155], v[182:185], 0
	v_mfma_f32_16x16x32_bf16 v[48:51], v[144:147], v[190:193], 0
	v_mfma_f32_16x16x32_bf16 v[40:43], v[152:155], v[190:193], 0
	v_mfma_f32_16x16x32_bf16 v[32:35], v[144:147], v[198:201], 0
	v_mfma_f32_16x16x32_bf16 v[24:27], v[152:155], v[198:201], 0
	v_mfma_f32_16x16x32_bf16 v[16:19], v[144:147], v[206:209], 0
	v_mfma_f32_16x16x32_bf16 v[8:11], v[152:155], v[206:209], 0
	v_mfma_f32_16x16x32_bf16 v[60:63], v[148:151], v[186:189], v[60:63]
	v_mfma_f32_16x16x32_bf16 v[56:59], v[156:159], v[186:189], v[56:59]
	v_mfma_f32_16x16x32_bf16 v[48:51], v[148:151], v[194:197], v[48:51]
	v_mfma_f32_16x16x32_bf16 v[40:43], v[156:159], v[194:197], v[40:43]
	v_mfma_f32_16x16x32_bf16 v[32:35], v[148:151], v[202:205], v[32:35]
	v_mfma_f32_16x16x32_bf16 v[24:27], v[156:159], v[202:205], v[24:27]
	v_mfma_f32_16x16x32_bf16 v[16:19], v[148:151], v[210:213], v[16:19]
	v_mfma_f32_16x16x32_bf16 v[8:11], v[156:159], v[210:213], v[8:11]
	v_mfma_f32_16x16x32_bf16 v[52:55], v[160:163], v[182:185], 0
	v_mfma_f32_16x16x32_bf16 v[44:47], v[174:177], v[182:185], 0
	v_mfma_f32_16x16x32_bf16 v[36:39], v[160:163], v[190:193], 0
	v_mfma_f32_16x16x32_bf16 v[28:31], v[174:177], v[190:193], 0
	v_mfma_f32_16x16x32_bf16 v[20:23], v[160:163], v[198:201], 0
	v_mfma_f32_16x16x32_bf16 v[12:15], v[174:177], v[198:201], 0
	v_mfma_f32_16x16x32_bf16 v[4:7], v[160:163], v[206:209], 0
	v_mfma_f32_16x16x32_bf16 v[0:3], v[174:177], v[206:209], 0
	v_mfma_f32_16x16x32_bf16 v[52:55], v[164:167], v[186:189], v[52:55]
	v_mfma_f32_16x16x32_bf16 v[44:47], v[178:181], v[186:189], v[44:47]
	v_mfma_f32_16x16x32_bf16 v[36:39], v[164:167], v[194:197], v[36:39]
	v_mfma_f32_16x16x32_bf16 v[28:31], v[178:181], v[194:197], v[28:31]
	v_mfma_f32_16x16x32_bf16 v[20:23], v[164:167], v[202:205], v[20:23]
	v_mfma_f32_16x16x32_bf16 v[12:15], v[178:181], v[202:205], v[12:15]
	v_mfma_f32_16x16x32_bf16 v[4:7], v[164:167], v[210:213], v[4:7]
	v_mfma_f32_16x16x32_bf16 v[0:3], v[178:181], v[210:213], v[0:3]
	s_barrier
	s_add_i32 s44, 0, 0x18000
	s_add_i32 s45, 0, 0x1c000
	v_add_u32_e32 v156, s44, v169
	v_add_u32_e32 v250, s44, v247
	v_add_u32_e32 v178, s45, v169
	v_add_u32_e32 v251, s45, v247
	ds_read_b128 v[144:147], v156
	ds_read_b128 v[148:151], v250
	ds_read_b128 v[152:155], v156 offset:2048
	ds_read_b128 v[156:159], v250 offset:2048
	ds_read_b128 v[160:163], v178
	ds_read_b128 v[164:167], v251
	ds_read_b128 v[174:177], v178 offset:2048
	ds_read_b128 v[178:181], v251 offset:2048
	s_add_u32 s14, s20, 0xb0000
	s_addc_u32 s15, s21, 0
	s_mov_b32 m0, s26
	v_lshl_add_u64 v[222:223], s[14:15], 0, v[128:129]
	ds_read_b128 v[182:185], v173 offset:32768
	ds_read_b128 v[186:189], v246 offset:32768
	ds_read_b128 v[190:193], v173 offset:34816
	ds_read_b128 v[194:197], v246 offset:34816
	ds_read_b128 v[198:201], v173 offset:36864
	ds_read_b128 v[202:205], v246 offset:36864
	ds_read_b128 v[206:209], v173 offset:38912
	ds_read_b128 v[210:213], v246 offset:38912
	global_load_lds_dwordx4 v[222:223], off
	v_lshl_add_u64 v[222:223], s[14:15], 0, v[132:133]
	s_mov_b32 m0, s27
	s_nop 0
	global_load_lds_dwordx4 v[222:223], off
	s_waitcnt vmcnt(8)
	s_waitcnt lgkmcnt(0)
	s_barrier
	s_waitcnt lgkmcnt(0)
	v_mfma_f32_16x16x32_bf16 v[124:127], v[144:147], v[182:185], v[124:127]
	v_mfma_f32_16x16x32_bf16 v[120:123], v[152:155], v[182:185], v[120:123]
	v_mfma_f32_16x16x32_bf16 v[112:115], v[144:147], v[190:193], v[112:115]
	v_mfma_f32_16x16x32_bf16 v[104:107], v[152:155], v[190:193], v[104:107]
	v_mfma_f32_16x16x32_bf16 v[96:99], v[144:147], v[198:201], v[96:99]
	v_mfma_f32_16x16x32_bf16 v[88:91], v[152:155], v[198:201], v[88:91]
	v_mfma_f32_16x16x32_bf16 v[80:83], v[144:147], v[206:209], v[80:83]
	v_mfma_f32_16x16x32_bf16 v[72:75], v[152:155], v[206:209], v[72:75]
	v_mfma_f32_16x16x32_bf16 v[124:127], v[148:151], v[186:189], v[124:127]
	v_mfma_f32_16x16x32_bf16 v[120:123], v[156:159], v[186:189], v[120:123]
	v_mfma_f32_16x16x32_bf16 v[112:115], v[148:151], v[194:197], v[112:115]
	v_mfma_f32_16x16x32_bf16 v[104:107], v[156:159], v[194:197], v[104:107]
	v_mfma_f32_16x16x32_bf16 v[96:99], v[148:151], v[202:205], v[96:99]
	v_mfma_f32_16x16x32_bf16 v[88:91], v[156:159], v[202:205], v[88:91]
	v_mfma_f32_16x16x32_bf16 v[80:83], v[148:151], v[210:213], v[80:83]
	v_mfma_f32_16x16x32_bf16 v[72:75], v[156:159], v[210:213], v[72:75]
	v_mfma_f32_16x16x32_bf16 v[116:119], v[160:163], v[182:185], v[116:119]
	v_mfma_f32_16x16x32_bf16 v[108:111], v[174:177], v[182:185], v[108:111]
	v_mfma_f32_16x16x32_bf16 v[100:103], v[160:163], v[190:193], v[100:103]
	v_mfma_f32_16x16x32_bf16 v[92:95], v[174:177], v[190:193], v[92:95]
	v_mfma_f32_16x16x32_bf16 v[84:87], v[160:163], v[198:201], v[84:87]
	v_mfma_f32_16x16x32_bf16 v[76:79], v[174:177], v[198:201], v[76:79]
	v_mfma_f32_16x16x32_bf16 v[68:71], v[160:163], v[206:209], v[68:71]
	v_mfma_f32_16x16x32_bf16 v[64:67], v[174:177], v[206:209], v[64:67]
	v_mfma_f32_16x16x32_bf16 v[116:119], v[164:167], v[186:189], v[116:119]
	v_mfma_f32_16x16x32_bf16 v[108:111], v[178:181], v[186:189], v[108:111]
	v_mfma_f32_16x16x32_bf16 v[100:103], v[164:167], v[194:197], v[100:103]
	v_mfma_f32_16x16x32_bf16 v[92:95], v[178:181], v[194:197], v[92:95]
	v_mfma_f32_16x16x32_bf16 v[84:87], v[164:167], v[202:205], v[84:87]
	v_mfma_f32_16x16x32_bf16 v[76:79], v[178:181], v[202:205], v[76:79]
	v_mfma_f32_16x16x32_bf16 v[68:71], v[164:167], v[210:213], v[68:71]
	v_mfma_f32_16x16x32_bf16 v[64:67], v[178:181], v[210:213], v[64:67]
	s_barrier
	s_add_i32 s14, s44, s23
	v_lshl_add_u64 v[214:215], v[214:215], 0, s[8:9]
	s_mov_b32 m0, s14
	ds_read_b128 v[182:185], v173 offset:49152
	ds_read_b128 v[186:189], v246 offset:49152
	ds_read_b128 v[190:193], v173 offset:51200
	ds_read_b128 v[194:197], v246 offset:51200
	ds_read_b128 v[198:201], v173 offset:53248
	ds_read_b128 v[202:205], v246 offset:53248
	ds_read_b128 v[206:209], v173 offset:55296
	ds_read_b128 v[210:213], v246 offset:55296
	global_load_lds_dwordx4 v[214:215], off
	s_add_i32 m0, s14, 0x2000
	s_add_u32 s14, s18, 0xb0080
	v_lshl_add_u64 v[214:215], v[216:217], 0, s[8:9]
	s_addc_u32 s15, s19, 0
	s_add_i32 s18, s45, s23
	global_load_lds_dwordx4 v[214:215], off
	v_lshl_add_u64 v[214:215], s[14:15], 0, v[130:131]
	s_mov_b32 m0, s18
	s_nop 0
	global_load_lds_dwordx4 v[214:215], off
	v_lshl_add_u64 v[214:215], s[14:15], 0, v[134:135]
	s_add_i32 m0, s18, 0x2000
	s_nop 0
	global_load_lds_dwordx4 v[214:215], off
	v_lshl_add_u64 v[214:215], v[218:219], 0, s[8:9]
	s_mov_b32 m0, s31
	s_nop 0
	global_load_lds_dwordx4 v[214:215], off
	v_lshl_add_u64 v[214:215], v[220:221], 0, s[8:9]
	s_mov_b32 m0, s33
	s_nop 0
	global_load_lds_dwordx4 v[214:215], off
	s_waitcnt vmcnt(8)
	s_waitcnt lgkmcnt(0)
	s_barrier
	s_waitcnt lgkmcnt(0)
	v_mfma_f32_16x16x32_bf16 v[60:63], v[144:147], v[182:185], v[60:63]
	v_mfma_f32_16x16x32_bf16 v[56:59], v[152:155], v[182:185], v[56:59]
	v_mfma_f32_16x16x32_bf16 v[48:51], v[144:147], v[190:193], v[48:51]
	v_mfma_f32_16x16x32_bf16 v[40:43], v[152:155], v[190:193], v[40:43]
	v_mfma_f32_16x16x32_bf16 v[32:35], v[144:147], v[198:201], v[32:35]
	v_mfma_f32_16x16x32_bf16 v[24:27], v[152:155], v[198:201], v[24:27]
	v_mfma_f32_16x16x32_bf16 v[16:19], v[144:147], v[206:209], v[16:19]
	v_mfma_f32_16x16x32_bf16 v[8:11], v[152:155], v[206:209], v[8:11]
	v_mfma_f32_16x16x32_bf16 v[60:63], v[148:151], v[186:189], v[60:63]
	v_mfma_f32_16x16x32_bf16 v[56:59], v[156:159], v[186:189], v[56:59]
	v_mfma_f32_16x16x32_bf16 v[48:51], v[148:151], v[194:197], v[48:51]
	v_mfma_f32_16x16x32_bf16 v[40:43], v[156:159], v[194:197], v[40:43]
	v_mfma_f32_16x16x32_bf16 v[32:35], v[148:151], v[202:205], v[32:35]
	v_mfma_f32_16x16x32_bf16 v[24:27], v[156:159], v[202:205], v[24:27]
	v_mfma_f32_16x16x32_bf16 v[16:19], v[148:151], v[210:213], v[16:19]
	v_mfma_f32_16x16x32_bf16 v[8:11], v[156:159], v[210:213], v[8:11]
	v_mfma_f32_16x16x32_bf16 v[52:55], v[160:163], v[182:185], v[52:55]
	v_mfma_f32_16x16x32_bf16 v[44:47], v[174:177], v[182:185], v[44:47]
	v_mfma_f32_16x16x32_bf16 v[36:39], v[160:163], v[190:193], v[36:39]
	v_mfma_f32_16x16x32_bf16 v[28:31], v[174:177], v[190:193], v[28:31]
	v_mfma_f32_16x16x32_bf16 v[20:23], v[160:163], v[198:201], v[20:23]
	v_mfma_f32_16x16x32_bf16 v[12:15], v[174:177], v[198:201], v[12:15]
	v_mfma_f32_16x16x32_bf16 v[4:7], v[160:163], v[206:209], v[4:7]
	v_mfma_f32_16x16x32_bf16 v[0:3], v[174:177], v[206:209], v[0:3]
	v_mfma_f32_16x16x32_bf16 v[52:55], v[164:167], v[186:189], v[52:55]
	v_mfma_f32_16x16x32_bf16 v[44:47], v[178:181], v[186:189], v[44:47]
	v_mfma_f32_16x16x32_bf16 v[36:39], v[164:167], v[194:197], v[36:39]
	v_mfma_f32_16x16x32_bf16 v[28:31], v[178:181], v[194:197], v[28:31]
	v_mfma_f32_16x16x32_bf16 v[20:23], v[164:167], v[202:205], v[20:23]
	v_mfma_f32_16x16x32_bf16 v[12:15], v[178:181], v[202:205], v[12:15]
	v_mfma_f32_16x16x32_bf16 v[4:7], v[164:167], v[210:213], v[4:7]
	v_mfma_f32_16x16x32_bf16 v[0:3], v[178:181], v[210:213], v[0:3]
	s_barrier
	s_add_i32 s43, s43, 2
	s_add_u32 s41, s41, 0x100
	s_addc_u32 s42, s42, 0
	s_cmp_gt_u32 s43, 41
	s_mov_b64 s[14:15], s[16:17]
.LBB0_1196:
	ds_read_b128 v[144:147], v171
	ds_read_b128 v[148:151], v248
	ds_read_b128 v[152:155], v171 offset:2048
	ds_read_b128 v[156:159], v248 offset:2048
	ds_read_b128 v[160:163], v172
	ds_read_b128 v[164:167], v249
	ds_read_b128 v[174:177], v172 offset:2048
	ds_read_b128 v[178:181], v249 offset:2048
	s_add_u32 s16, s14, 0x100
	s_addc_u32 s17, s15, 0
	s_cmp_eq_u32 s43, 40
	s_cselect_b32 s21, s5, s17
	s_cselect_b32 s20, s4, s16
	s_cselect_b32 s19, s13, s42
	s_cselect_b32 s18, s12, s41
	v_lshl_add_u64 v[214:215], s[14:15], 0, v[136:137]
	s_add_i32 m0, s24, 0xc000
	ds_read_b128 v[182:185], v173
	ds_read_b128 v[186:189], v246
	ds_read_b128 v[190:193], v173 offset:2048
	ds_read_b128 v[194:197], v246 offset:2048
	ds_read_b128 v[198:201], v173 offset:4096
	ds_read_b128 v[202:205], v246 offset:4096
	ds_read_b128 v[206:209], v173 offset:6144
	ds_read_b128 v[210:213], v246 offset:6144
	global_load_lds_dwordx4 v[214:215], off
	v_lshl_add_u64 v[214:215], s[14:15], 0, v[138:139]
	s_add_i32 m0, s24, 0xe000
	s_nop 0
	global_load_lds_dwordx4 v[214:215], off
	s_waitcnt vmcnt(8)
	s_waitcnt lgkmcnt(0)
	s_barrier
	s_waitcnt lgkmcnt(0)
	v_mfma_f32_16x16x32_bf16 v[124:127], v[144:147], v[182:185], v[124:127]
	v_mfma_f32_16x16x32_bf16 v[120:123], v[152:155], v[182:185], v[120:123]
	v_mfma_f32_16x16x32_bf16 v[112:115], v[144:147], v[190:193], v[112:115]
	v_mfma_f32_16x16x32_bf16 v[104:107], v[152:155], v[190:193], v[104:107]
	v_mfma_f32_16x16x32_bf16 v[96:99], v[144:147], v[198:201], v[96:99]
	v_mfma_f32_16x16x32_bf16 v[88:91], v[152:155], v[198:201], v[88:91]
	v_mfma_f32_16x16x32_bf16 v[80:83], v[144:147], v[206:209], v[80:83]
	v_mfma_f32_16x16x32_bf16 v[72:75], v[152:155], v[206:209], v[72:75]
	v_mfma_f32_16x16x32_bf16 v[124:127], v[148:151], v[186:189], v[124:127]
	v_mfma_f32_16x16x32_bf16 v[120:123], v[156:159], v[186:189], v[120:123]
	v_mfma_f32_16x16x32_bf16 v[112:115], v[148:151], v[194:197], v[112:115]
	v_mfma_f32_16x16x32_bf16 v[104:107], v[156:159], v[194:197], v[104:107]
	v_mfma_f32_16x16x32_bf16 v[96:99], v[148:151], v[202:205], v[96:99]
	v_mfma_f32_16x16x32_bf16 v[88:91], v[156:159], v[202:205], v[88:91]
	v_mfma_f32_16x16x32_bf16 v[80:83], v[148:151], v[210:213], v[80:83]
	v_mfma_f32_16x16x32_bf16 v[72:75], v[156:159], v[210:213], v[72:75]
	v_mfma_f32_16x16x32_bf16 v[116:119], v[160:163], v[182:185], v[116:119]
	v_mfma_f32_16x16x32_bf16 v[108:111], v[174:177], v[182:185], v[108:111]
	v_mfma_f32_16x16x32_bf16 v[100:103], v[160:163], v[190:193], v[100:103]
	v_mfma_f32_16x16x32_bf16 v[92:95], v[174:177], v[190:193], v[92:95]
	v_mfma_f32_16x16x32_bf16 v[84:87], v[160:163], v[198:201], v[84:87]
	v_mfma_f32_16x16x32_bf16 v[76:79], v[174:177], v[198:201], v[76:79]
	v_mfma_f32_16x16x32_bf16 v[68:71], v[160:163], v[206:209], v[68:71]
	v_mfma_f32_16x16x32_bf16 v[64:67], v[174:177], v[206:209], v[64:67]
	v_mfma_f32_16x16x32_bf16 v[116:119], v[164:167], v[186:189], v[116:119]
	v_mfma_f32_16x16x32_bf16 v[108:111], v[178:181], v[186:189], v[108:111]
	v_mfma_f32_16x16x32_bf16 v[100:103], v[164:167], v[194:197], v[100:103]
	v_mfma_f32_16x16x32_bf16 v[92:95], v[178:181], v[194:197], v[92:95]
	v_mfma_f32_16x16x32_bf16 v[84:87], v[164:167], v[202:205], v[84:87]
	v_mfma_f32_16x16x32_bf16 v[76:79], v[178:181], v[202:205], v[76:79]
	v_mfma_f32_16x16x32_bf16 v[68:71], v[164:167], v[210:213], v[68:71]
	v_mfma_f32_16x16x32_bf16 v[64:67], v[178:181], v[210:213], v[64:67]
	s_barrier
	s_add_i32 s14, s35, s23
	v_lshl_add_u64 v[214:215], s[18:19], 0, v[130:131]
	s_mov_b32 m0, s14
	ds_read_b128 v[182:185], v173 offset:16384
	ds_read_b128 v[186:189], v246 offset:16384
	ds_read_b128 v[190:193], v173 offset:18432
	ds_read_b128 v[194:197], v246 offset:18432
	ds_read_b128 v[198:201], v173 offset:20480
	ds_read_b128 v[202:205], v246 offset:20480
	ds_read_b128 v[206:209], v173 offset:22528
	ds_read_b128 v[210:213], v246 offset:22528
	global_load_lds_dwordx4 v[214:215], off
	s_add_i32 m0, s14, 0x2000
	s_add_u32 s14, s18, 0xb0000
	v_lshl_add_u64 v[216:217], s[18:19], 0, v[134:135]
	s_addc_u32 s15, s19, 0
	s_add_i32 s44, s36, s23
	global_load_lds_dwordx4 v[216:217], off
	v_lshl_add_u64 v[218:219], s[14:15], 0, v[130:131]
	s_mov_b32 m0, s44
	v_lshl_add_u64 v[220:221], s[20:21], 0, v[132:133]
	global_load_lds_dwordx4 v[218:219], off
	v_lshl_add_u64 v[218:219], s[14:15], 0, v[134:135]
	s_add_i32 m0, s44, 0x2000
	s_nop 0
	global_load_lds_dwordx4 v[218:219], off
	v_lshl_add_u64 v[218:219], s[20:21], 0, v[128:129]
	s_mov_b32 m0, s24
	s_nop 0
	global_load_lds_dwordx4 v[218:219], off
	s_mov_b32 m0, s25
	s_nop 0
	global_load_lds_dwordx4 v[220:221], off
	s_waitcnt vmcnt(8)
	s_waitcnt lgkmcnt(0)
	s_barrier
	s_waitcnt lgkmcnt(0)
	v_mfma_f32_16x16x32_bf16 v[60:63], v[144:147], v[182:185], v[60:63]
	v_mfma_f32_16x16x32_bf16 v[56:59], v[152:155], v[182:185], v[56:59]
	v_mfma_f32_16x16x32_bf16 v[48:51], v[144:147], v[190:193], v[48:51]
	v_mfma_f32_16x16x32_bf16 v[40:43], v[152:155], v[190:193], v[40:43]
	v_mfma_f32_16x16x32_bf16 v[32:35], v[144:147], v[198:201], v[32:35]
	v_mfma_f32_16x16x32_bf16 v[24:27], v[152:155], v[198:201], v[24:27]
	v_mfma_f32_16x16x32_bf16 v[16:19], v[144:147], v[206:209], v[16:19]
	v_mfma_f32_16x16x32_bf16 v[8:11], v[152:155], v[206:209], v[8:11]
	v_mfma_f32_16x16x32_bf16 v[60:63], v[148:151], v[186:189], v[60:63]
	v_mfma_f32_16x16x32_bf16 v[56:59], v[156:159], v[186:189], v[56:59]
	v_mfma_f32_16x16x32_bf16 v[48:51], v[148:151], v[194:197], v[48:51]
	v_mfma_f32_16x16x32_bf16 v[40:43], v[156:159], v[194:197], v[40:43]
	v_mfma_f32_16x16x32_bf16 v[32:35], v[148:151], v[202:205], v[32:35]
	v_mfma_f32_16x16x32_bf16 v[24:27], v[156:159], v[202:205], v[24:27]
	v_mfma_f32_16x16x32_bf16 v[16:19], v[148:151], v[210:213], v[16:19]
	v_mfma_f32_16x16x32_bf16 v[8:11], v[156:159], v[210:213], v[8:11]
	v_mfma_f32_16x16x32_bf16 v[52:55], v[160:163], v[182:185], v[52:55]
	v_mfma_f32_16x16x32_bf16 v[44:47], v[174:177], v[182:185], v[44:47]
	v_mfma_f32_16x16x32_bf16 v[36:39], v[160:163], v[190:193], v[36:39]
	v_mfma_f32_16x16x32_bf16 v[28:31], v[174:177], v[190:193], v[28:31]
	v_mfma_f32_16x16x32_bf16 v[20:23], v[160:163], v[198:201], v[20:23]
	v_mfma_f32_16x16x32_bf16 v[12:15], v[174:177], v[198:201], v[12:15]
	v_mfma_f32_16x16x32_bf16 v[4:7], v[160:163], v[206:209], v[4:7]
	v_mfma_f32_16x16x32_bf16 v[0:3], v[174:177], v[206:209], v[0:3]
	v_mfma_f32_16x16x32_bf16 v[52:55], v[164:167], v[186:189], v[52:55]
	v_mfma_f32_16x16x32_bf16 v[44:47], v[178:181], v[186:189], v[44:47]
	v_mfma_f32_16x16x32_bf16 v[36:39], v[164:167], v[194:197], v[36:39]
	v_mfma_f32_16x16x32_bf16 v[28:31], v[178:181], v[194:197], v[28:31]
	v_mfma_f32_16x16x32_bf16 v[20:23], v[164:167], v[202:205], v[20:23]
	v_mfma_f32_16x16x32_bf16 v[12:15], v[178:181], v[202:205], v[12:15]
	v_mfma_f32_16x16x32_bf16 v[4:7], v[164:167], v[210:213], v[4:7]
	v_mfma_f32_16x16x32_bf16 v[0:3], v[178:181], v[210:213], v[0:3]
	s_barrier
	s_add_i32 s44, 0, 0x18000
	s_add_i32 s45, 0, 0x1c000
	v_add_u32_e32 v156, s44, v169
	v_add_u32_e32 v250, s44, v247
	v_add_u32_e32 v178, s45, v169
	v_add_u32_e32 v251, s45, v247
	ds_read_b128 v[144:147], v156
	ds_read_b128 v[148:151], v250
	ds_read_b128 v[152:155], v156 offset:2048
	ds_read_b128 v[156:159], v250 offset:2048
	ds_read_b128 v[160:163], v178
	ds_read_b128 v[164:167], v251
	ds_read_b128 v[174:177], v178 offset:2048
	ds_read_b128 v[178:181], v251 offset:2048
	s_add_u32 s14, s20, 0xb0000
	s_addc_u32 s15, s21, 0
	s_mov_b32 m0, s26
	v_lshl_add_u64 v[222:223], s[14:15], 0, v[128:129]
	ds_read_b128 v[182:185], v173 offset:32768
	ds_read_b128 v[186:189], v246 offset:32768
	ds_read_b128 v[190:193], v173 offset:34816
	ds_read_b128 v[194:197], v246 offset:34816
	ds_read_b128 v[198:201], v173 offset:36864
	ds_read_b128 v[202:205], v246 offset:36864
	ds_read_b128 v[206:209], v173 offset:38912
	ds_read_b128 v[210:213], v246 offset:38912
	global_load_lds_dwordx4 v[222:223], off
	v_lshl_add_u64 v[222:223], s[14:15], 0, v[132:133]
	s_mov_b32 m0, s27
	s_nop 0
	global_load_lds_dwordx4 v[222:223], off
	s_waitcnt vmcnt(8)
	s_waitcnt lgkmcnt(0)
	s_barrier
	s_waitcnt lgkmcnt(0)
	v_mfma_f32_16x16x32_bf16 v[124:127], v[144:147], v[182:185], v[124:127]
	v_mfma_f32_16x16x32_bf16 v[120:123], v[152:155], v[182:185], v[120:123]
	v_mfma_f32_16x16x32_bf16 v[112:115], v[144:147], v[190:193], v[112:115]
	v_mfma_f32_16x16x32_bf16 v[104:107], v[152:155], v[190:193], v[104:107]
	v_mfma_f32_16x16x32_bf16 v[96:99], v[144:147], v[198:201], v[96:99]
	v_mfma_f32_16x16x32_bf16 v[88:91], v[152:155], v[198:201], v[88:91]
	v_mfma_f32_16x16x32_bf16 v[80:83], v[144:147], v[206:209], v[80:83]
	v_mfma_f32_16x16x32_bf16 v[72:75], v[152:155], v[206:209], v[72:75]
	v_mfma_f32_16x16x32_bf16 v[124:127], v[148:151], v[186:189], v[124:127]
	v_mfma_f32_16x16x32_bf16 v[120:123], v[156:159], v[186:189], v[120:123]
	v_mfma_f32_16x16x32_bf16 v[112:115], v[148:151], v[194:197], v[112:115]
	v_mfma_f32_16x16x32_bf16 v[104:107], v[156:159], v[194:197], v[104:107]
	v_mfma_f32_16x16x32_bf16 v[96:99], v[148:151], v[202:205], v[96:99]
	v_mfma_f32_16x16x32_bf16 v[88:91], v[156:159], v[202:205], v[88:91]
	v_mfma_f32_16x16x32_bf16 v[80:83], v[148:151], v[210:213], v[80:83]
	v_mfma_f32_16x16x32_bf16 v[72:75], v[156:159], v[210:213], v[72:75]
	v_mfma_f32_16x16x32_bf16 v[116:119], v[160:163], v[182:185], v[116:119]
	v_mfma_f32_16x16x32_bf16 v[108:111], v[174:177], v[182:185], v[108:111]
	v_mfma_f32_16x16x32_bf16 v[100:103], v[160:163], v[190:193], v[100:103]
	v_mfma_f32_16x16x32_bf16 v[92:95], v[174:177], v[190:193], v[92:95]
	v_mfma_f32_16x16x32_bf16 v[84:87], v[160:163], v[198:201], v[84:87]
	v_mfma_f32_16x16x32_bf16 v[76:79], v[174:177], v[198:201], v[76:79]
	v_mfma_f32_16x16x32_bf16 v[68:71], v[160:163], v[206:209], v[68:71]
	v_mfma_f32_16x16x32_bf16 v[64:67], v[174:177], v[206:209], v[64:67]
	v_mfma_f32_16x16x32_bf16 v[116:119], v[164:167], v[186:189], v[116:119]
	v_mfma_f32_16x16x32_bf16 v[108:111], v[178:181], v[186:189], v[108:111]
	v_mfma_f32_16x16x32_bf16 v[100:103], v[164:167], v[194:197], v[100:103]
	v_mfma_f32_16x16x32_bf16 v[92:95], v[178:181], v[194:197], v[92:95]
	v_mfma_f32_16x16x32_bf16 v[84:87], v[164:167], v[202:205], v[84:87]
	v_mfma_f32_16x16x32_bf16 v[76:79], v[178:181], v[202:205], v[76:79]
	v_mfma_f32_16x16x32_bf16 v[68:71], v[164:167], v[210:213], v[68:71]
	v_mfma_f32_16x16x32_bf16 v[64:67], v[178:181], v[210:213], v[64:67]
	s_barrier
	s_add_i32 s14, s44, s23
	v_lshl_add_u64 v[214:215], v[214:215], 0, s[8:9]
	s_mov_b32 m0, s14
	ds_read_b128 v[182:185], v173 offset:49152
	ds_read_b128 v[186:189], v246 offset:49152
	ds_read_b128 v[190:193], v173 offset:51200
	ds_read_b128 v[194:197], v246 offset:51200
	ds_read_b128 v[198:201], v173 offset:53248
	ds_read_b128 v[202:205], v246 offset:53248
	ds_read_b128 v[206:209], v173 offset:55296
	ds_read_b128 v[210:213], v246 offset:55296
	global_load_lds_dwordx4 v[214:215], off
	s_add_i32 m0, s14, 0x2000
	s_add_u32 s14, s18, 0xb0080
	v_lshl_add_u64 v[214:215], v[216:217], 0, s[8:9]
	s_addc_u32 s15, s19, 0
	s_add_i32 s18, s45, s23
	global_load_lds_dwordx4 v[214:215], off
	v_lshl_add_u64 v[214:215], s[14:15], 0, v[130:131]
	s_mov_b32 m0, s18
	s_nop 0
	global_load_lds_dwordx4 v[214:215], off
	v_lshl_add_u64 v[214:215], s[14:15], 0, v[134:135]
	s_add_i32 m0, s18, 0x2000
	s_nop 0
	global_load_lds_dwordx4 v[214:215], off
	v_lshl_add_u64 v[214:215], v[218:219], 0, s[8:9]
	s_mov_b32 m0, s31
	s_nop 0
	global_load_lds_dwordx4 v[214:215], off
	v_lshl_add_u64 v[214:215], v[220:221], 0, s[8:9]
	s_mov_b32 m0, s33
	s_nop 0
	global_load_lds_dwordx4 v[214:215], off
	s_waitcnt vmcnt(8)
	s_waitcnt lgkmcnt(0)
	s_barrier
	s_waitcnt lgkmcnt(0)
	v_mfma_f32_16x16x32_bf16 v[60:63], v[144:147], v[182:185], v[60:63]
	v_mfma_f32_16x16x32_bf16 v[56:59], v[152:155], v[182:185], v[56:59]
	v_mfma_f32_16x16x32_bf16 v[48:51], v[144:147], v[190:193], v[48:51]
	v_mfma_f32_16x16x32_bf16 v[40:43], v[152:155], v[190:193], v[40:43]
	v_mfma_f32_16x16x32_bf16 v[32:35], v[144:147], v[198:201], v[32:35]
	v_mfma_f32_16x16x32_bf16 v[24:27], v[152:155], v[198:201], v[24:27]
	v_mfma_f32_16x16x32_bf16 v[16:19], v[144:147], v[206:209], v[16:19]
	v_mfma_f32_16x16x32_bf16 v[8:11], v[152:155], v[206:209], v[8:11]
	v_mfma_f32_16x16x32_bf16 v[60:63], v[148:151], v[186:189], v[60:63]
	v_mfma_f32_16x16x32_bf16 v[56:59], v[156:159], v[186:189], v[56:59]
	v_mfma_f32_16x16x32_bf16 v[48:51], v[148:151], v[194:197], v[48:51]
	v_mfma_f32_16x16x32_bf16 v[40:43], v[156:159], v[194:197], v[40:43]
	v_mfma_f32_16x16x32_bf16 v[32:35], v[148:151], v[202:205], v[32:35]
	v_mfma_f32_16x16x32_bf16 v[24:27], v[156:159], v[202:205], v[24:27]
	v_mfma_f32_16x16x32_bf16 v[16:19], v[148:151], v[210:213], v[16:19]
	v_mfma_f32_16x16x32_bf16 v[8:11], v[156:159], v[210:213], v[8:11]
	v_mfma_f32_16x16x32_bf16 v[52:55], v[160:163], v[182:185], v[52:55]
	v_mfma_f32_16x16x32_bf16 v[44:47], v[174:177], v[182:185], v[44:47]
	v_mfma_f32_16x16x32_bf16 v[36:39], v[160:163], v[190:193], v[36:39]
	v_mfma_f32_16x16x32_bf16 v[28:31], v[174:177], v[190:193], v[28:31]
	v_mfma_f32_16x16x32_bf16 v[20:23], v[160:163], v[198:201], v[20:23]
	v_mfma_f32_16x16x32_bf16 v[12:15], v[174:177], v[198:201], v[12:15]
	v_mfma_f32_16x16x32_bf16 v[4:7], v[160:163], v[206:209], v[4:7]
	v_mfma_f32_16x16x32_bf16 v[0:3], v[174:177], v[206:209], v[0:3]
	v_mfma_f32_16x16x32_bf16 v[52:55], v[164:167], v[186:189], v[52:55]
	v_mfma_f32_16x16x32_bf16 v[44:47], v[178:181], v[186:189], v[44:47]
	v_mfma_f32_16x16x32_bf16 v[36:39], v[164:167], v[194:197], v[36:39]
	v_mfma_f32_16x16x32_bf16 v[28:31], v[178:181], v[194:197], v[28:31]
	v_mfma_f32_16x16x32_bf16 v[20:23], v[164:167], v[202:205], v[20:23]
	v_mfma_f32_16x16x32_bf16 v[12:15], v[178:181], v[202:205], v[12:15]
	v_mfma_f32_16x16x32_bf16 v[4:7], v[164:167], v[210:213], v[4:7]
	v_mfma_f32_16x16x32_bf16 v[0:3], v[178:181], v[210:213], v[0:3]
	s_barrier
	s_add_i32 s43, s43, 2
	s_add_u32 s41, s41, 0x100
	s_addc_u32 s42, s42, 0
	s_cmp_gt_u32 s43, 41
	s_mov_b64 s[14:15], s[16:17]
	s_cbranch_scc0 .LBB0_1196
	s_and_b64 vcc, exec, s[10:11]
	s_cbranch_vccz .LBB0_1199
	s_barrier
